# P1: adaLN shift/scale staged once in LDS (ds_read instead of 32 global reloads + vmcnt(0) drains per 4 rows), gate bias hoisted; P7: k and q fragment loads batched; P5: epilogue loads hoisted
# speedup vs baseline: 1.0225x; 1.0214x over previous
; DI void phase1(const Params& p, unsigned char* smem) {
;     ...
;     const float* mod = (const float*)(ws + OFF_MOD);
;     bf16_t* h1 = (bf16_t*)(ws + 1 * U_);
;     float4 gw0[16], gw1[16];
; #pragma unroll
;     for (int i = 0; i < 4; ++i)
; #pragma unroll
;         for (int e = 0; e < 4; ++e) {
;             const float* wp = p.in[4] + (size_t)(i * 256 + lane * 4 + e) * 4616 + 2048;
;             gw0[i * 4 + e] = *(const float4*)wp; gw1[i * 4 + e] = *(const float4*)(wp + 4);
;         }
;     float* ig = (float*)(ws + OFF_IG);
;     float* lf = (float*)(ws + OFF_LOGF);
;     for (int row0 = (blockIdx.x * 8 + wid) * 4; row0 < T_; row0 += gridDim.x * 32) {
.LBB0_184:
	s_or_b64 exec, exec, s[0:1]
	s_add_u32 s62, s70, 0x2000000
	s_addc_u32 s63, s71, 0
	s_add_u32 s94, s70, 0x4000000
	s_addc_u32 s95, s71, 0
	s_add_u32 s88, s70, 0x325c000
	v_mov_b32_e32 v0, v250
	s_addc_u32 s89, s71, 0
	s_waitcnt lgkmcnt(0)
	s_barrier
	v_lshlrev_b32_e32 v150, 4, v250
	v_add_u32_e32 v151, 0x6000, v150
	v_add_u32_e32 v152, 0xc000, v150
	v_add_u32_e32 v153, 0x12000, v150
	global_load_dwordx4 v[156:159], v150, s[62:63]
	global_load_dwordx4 v[160:163], v151, s[62:63]
	global_load_dwordx4 v[164:167], v152, s[62:63]
	global_load_dwordx4 v[168:171], v153, s[62:63]
	s_waitcnt vmcnt(3)
	ds_write_b128 v150, v[156:159] offset:1024
	s_waitcnt vmcnt(2)
	ds_write_b128 v150, v[160:163] offset:9216
	s_waitcnt vmcnt(1)
	ds_write_b128 v150, v[164:167] offset:17408
	s_waitcnt vmcnt(0)
	ds_write_b128 v150, v[168:171] offset:25600
	s_waitcnt lgkmcnt(0)
	s_barrier
	s_add_u32 s20, s70, 0x32dc000
	v_ashrrev_i32_e32 v1, 4, v0
	s_addc_u32 s21, s71, 0
	s_lshl_b32 s0, s2, 5
	v_and_b32_e32 v1, -4, v1
	v_writelane_b32 v254, s0, 52
	v_add_u32_e32 v176, s0, v1
	s_mov_b32 s0, 0x8000
	v_cmp_gt_i32_e32 vcc, s0, v176
	s_and_saveexec_b64 s[22:23], vcc
	s_cbranch_execz .LBB0_219
; DI void phase1(const Params& p, unsigned char* smem) {
;     ...
;     float4 gw0[16], gw1[16];
; #pragma unroll
;     for (int i = 0; i < 4; ++i)
; #pragma unroll
;         for (int e = 0; e < 4; ++e) {
;             const float* wp = p.in[4] + (size_t)(i * 256 + lane * 4 + e) * 4616 + 2048;
;             gw0[i * 4 + e] = *(const float4*)wp; gw1[i * 4 + e] = *(const float4*)(wp + 4);
;         }
;     float* ig = (float*)(ws + OFF_IG);
;     float* lf = (float*)(ws + OFF_LOGF);
;     for (int row0 = (blockIdx.x * 8 + wid) * 4; row0 < T_; row0 += gridDim.x * 32) {
;     ...
;                 val += p.in[5][2048 + lane];
	v_and_b32_e32 v230, 63, v0
	v_mul_u32_u24_e32 v0, 0x4820, v230
	v_readlane_b32 s36, v254, 4
	v_lshlrev_b32_e32 v178, 2, v0
	v_mov_b32_e32 v179, 0
	v_readlane_b32 s44, v254, 12
	v_readlane_b32 s45, v254, 13
	v_lshlrev_b32_e32 v128, 2, v230
	v_or_b32_e32 v130, 0x100, v128
	v_lshl_add_u64 v[16:17], s[44:45], 0, v[178:179]
	v_add_co_u32_e32 v0, vcc, 0x2000, v16
	s_mov_b64 s[0:1], 0x6820
	s_nop 0
	v_addc_co_u32_e32 v1, vcc, 0, v17, vcc
	v_add_co_u32_e32 v8, vcc, 0x6000, v16
	v_mul_u32_u24_e32 v22, 0x1208, v130
	s_nop 0
	v_addc_co_u32_e32 v9, vcc, 0, v17, vcc
	v_add_co_u32_e32 v18, vcc, 0xb000, v16
	v_lshl_add_u64 v[12:13], v[16:17], 0, s[0:1]
	s_nop 0
	v_addc_co_u32_e32 v19, vcc, 0, v17, vcc
	s_mov_b64 s[0:1], 0xb040
	v_add_co_u32_e32 v24, vcc, 0xf000, v16
	v_lshlrev_b32_e32 v178, 2, v22
	s_movk_i32 s3, 0x2000
	v_lshl_add_u64 v[20:21], v[16:17], 0, s[0:1]
	s_mov_b64 s[0:1], 0xf860
	v_addc_co_u32_e32 v25, vcc, 0, v17, vcc
	v_lshl_add_u64 v[22:23], s[44:45], 0, v[178:179]
	v_lshl_add_u64 v[28:29], v[16:17], 0, s[0:1]
	v_add_co_u32_e32 v32, vcc, s3, v22
	s_mov_b64 s[0:1], 0x488820
	s_nop 0
	v_addc_co_u32_e32 v33, vcc, 0, v23, vcc
	v_lshl_add_u64 v[44:45], v[16:17], 0, s[0:1]
	s_mov_b32 s0, 0x488000
	v_add_co_u32_e32 v40, vcc, s0, v16
	s_mov_b64 s[0:1], 0x48d040
	s_nop 0
	v_addc_co_u32_e32 v41, vcc, 0, v17, vcc
	v_lshl_add_u64 v[52:53], v[16:17], 0, s[0:1]
	s_mov_b32 s0, 0x48d000
	v_add_co_u32_e32 v48, vcc, s0, v16
	s_mov_b64 s[0:1], 0x491860
	s_nop 0
	v_addc_co_u32_e32 v49, vcc, 0, v17, vcc
	v_lshl_add_u64 v[60:61], v[16:17], 0, s[0:1]
	s_mov_b32 s0, 0x491000
	v_add_co_u32_e32 v56, vcc, s0, v16
	s_mov_b64 s[0:1], 0x484000
	s_nop 0
	v_addc_co_u32_e32 v57, vcc, 0, v17, vcc
	v_lshl_add_u64 v[68:69], v[22:23], 0, s[0:1]
	s_mov_b32 s0, 0x484000
	v_add_co_u32_e32 v64, vcc, s0, v22
	s_mov_b64 s[0:1], 0x90a820
	s_nop 0
	v_addc_co_u32_e32 v65, vcc, 0, v23, vcc
	v_lshl_add_u64 v[76:77], v[16:17], 0, s[0:1]
	s_mov_b32 s0, 0x90a000
	v_add_co_u32_e32 v72, vcc, s0, v16
	s_mov_b64 s[0:1], 0x90f040
	s_nop 0
	v_addc_co_u32_e32 v73, vcc, 0, v17, vcc
	v_lshl_add_u64 v[84:85], v[16:17], 0, s[0:1]
	s_mov_b32 s0, 0x90f000
	v_add_co_u32_e32 v80, vcc, s0, v16
	s_mov_b64 s[0:1], 0x913860
	s_nop 0
	v_addc_co_u32_e32 v81, vcc, 0, v17, vcc
	v_lshl_add_u64 v[92:93], v[16:17], 0, s[0:1]
	s_mov_b32 s0, 0x913000
	v_add_co_u32_e32 v88, vcc, s0, v16
	s_mov_b64 s[0:1], 0x906000
	s_nop 0
	v_addc_co_u32_e32 v89, vcc, 0, v17, vcc
	v_lshl_add_u64 v[100:101], v[22:23], 0, s[0:1]
	s_mov_b32 s0, 0x906000
	v_add_co_u32_e32 v96, vcc, s0, v22
	s_mov_b64 s[0:1], 0xd8c820
	s_nop 0
	v_addc_co_u32_e32 v97, vcc, 0, v23, vcc
	v_lshl_add_u64 v[108:109], v[16:17], 0, s[0:1]
	s_mov_b32 s0, 0xd8c000
	v_add_co_u32_e32 v104, vcc, s0, v16
	s_mov_b64 s[0:1], 0xd91040
	s_nop 0
	v_addc_co_u32_e32 v105, vcc, 0, v17, vcc
	v_lshl_add_u64 v[116:117], v[16:17], 0, s[0:1]
	s_mov_b32 s0, 0xd91000
	v_add_co_u32_e32 v112, vcc, s0, v16
	s_mov_b64 s[0:1], 0xd95860
	s_nop 0
	v_addc_co_u32_e32 v113, vcc, 0, v17, vcc
	v_lshl_add_u64 v[124:125], v[16:17], 0, s[0:1]
	s_mov_b32 s0, 0xd95000
	s_mov_b64 s[16:17], 0x2000
	v_add_co_u32_e32 v120, vcc, s0, v16
	v_lshl_add_u64 v[4:5], v[16:17], 0, s[16:17]
	v_lshl_add_u64 v[36:37], v[22:23], 0, s[16:17]
	v_addc_co_u32_e32 v121, vcc, 0, v17, vcc
	global_load_dwordx4 v[0:3], v[0:1], off
	s_nop 0
	global_load_dwordx4 v[4:7], v[4:5], off offset:16
	s_nop 0
	global_load_dwordx4 v[8:11], v[8:9], off offset:2080
	s_nop 0
	global_load_dwordx4 v[12:15], v[12:13], off offset:16
	s_nop 0
	global_load_dwordx4 v[16:19], v[18:19], off offset:64
	s_nop 0
	global_load_dwordx4 v[20:23], v[20:21], off offset:16
	s_nop 0
	global_load_dwordx4 v[24:27], v[24:25], off offset:2144
	s_nop 0
	global_load_dwordx4 v[28:31], v[28:29], off offset:16
	s_nop 0
	global_load_dwordx4 v[32:35], v[32:33], off
	s_nop 0
	global_load_dwordx4 v[36:39], v[36:37], off offset:16
	s_nop 0
	global_load_dwordx4 v[40:43], v[40:41], off offset:2080
	s_nop 0
	global_load_dwordx4 v[44:47], v[44:45], off offset:16
	s_nop 0
	global_load_dwordx4 v[48:51], v[48:49], off offset:64
	s_nop 0
	global_load_dwordx4 v[52:55], v[52:53], off offset:16
	s_nop 0
	global_load_dwordx4 v[56:59], v[56:57], off offset:2144
	s_nop 0
	global_load_dwordx4 v[60:63], v[60:61], off offset:16
	s_nop 0
	global_load_dwordx4 v[64:67], v[64:65], off
	s_nop 0
	global_load_dwordx4 v[68:71], v[68:69], off offset:16
	s_nop 0
	global_load_dwordx4 v[72:75], v[72:73], off offset:2080
	s_nop 0
	global_load_dwordx4 v[76:79], v[76:77], off offset:16
	s_nop 0
	global_load_dwordx4 v[80:83], v[80:81], off offset:64
	s_nop 0
	global_load_dwordx4 v[84:87], v[84:85], off offset:16
	s_nop 0
	global_load_dwordx4 v[88:91], v[88:89], off offset:2144
	s_nop 0
	global_load_dwordx4 v[92:95], v[92:93], off offset:16
	s_nop 0
	global_load_dwordx4 v[96:99], v[96:97], off
	s_nop 0
	global_load_dwordx4 v[100:103], v[100:101], off offset:16
	s_nop 0
	global_load_dwordx4 v[104:107], v[104:105], off offset:2080
	s_nop 0
	global_load_dwordx4 v[108:111], v[108:109], off offset:16
	s_nop 0
	global_load_dwordx4 v[112:115], v[112:113], off offset:64
	s_nop 0
	global_load_dwordx4 v[116:119], v[116:117], off offset:16
	s_nop 0
	global_load_dwordx4 v[120:123], v[120:121], off offset:2144
	s_nop 0
	global_load_dwordx4 v[124:127], v[124:125], off offset:16
	v_readlane_b32 s37, v254, 5
	v_readlane_b32 s46, v254, 14
	v_readlane_b32 s47, v254, 15
	v_mov_b32_e32 v129, v179
	v_lshlrev_b32_e32 v178, 4, v230
	v_readlane_b32 s38, v254, 6
	v_readlane_b32 s39, v254, 7
	v_readlane_b32 s40, v254, 8
	v_or_b32_e32 v132, 0x200, v128
	v_or_b32_e32 v134, 0x300, v128
	v_subrev_co_u32_e64 v231, s[0:1], 4, v230
	v_lshl_add_u64 v[180:181], s[36:37], 0, v[178:179]
	v_lshl_add_u64 v[136:137], s[46:47], 0, v[128:129]
	v_lshlrev_b32_e32 v178, 3, v230
	v_cmp_gt_u32_e32 vcc, 8, v230
	s_xor_b64 s[24:25], s[0:1], -1
	s_lshl_b32 s3, s33, 5
	v_cmp_eq_u32_e64 s[0:1], 1, v230
	v_cmp_eq_u32_e64 s[14:15], 2, v230
	v_cmp_eq_u32_e64 s[4:5], 3, v230
	v_cmp_eq_u32_e64 s[6:7], 4, v230
	v_cmp_eq_u32_e64 s[8:9], 5, v230
	v_cmp_eq_u32_e64 s[10:11], 6, v230
	v_cmp_eq_u32_e64 s[12:13], 7, v230
	v_lshl_add_u64 v[182:183], v[136:137], 0, s[16:17]
	v_lshl_add_u64 v[184:185], s[94:95], 0, v[178:179]
	s_mov_b64 s[26:27], 0
	v_lshlrev_b32_e32 v178, 2, v128
	v_lshlrev_b32_e32 v186, 2, v130
	v_lshlrev_b32_e32 v188, 2, v132
	v_lshlrev_b32_e32 v190, 2, v134
	v_mov_b32_e32 v232, 0x3727c5ac
	s_mov_b32 s36, 0x800000
	s_mov_b32 s37, 0x3f2aaaab
	v_mov_b32_e32 v233, 0x3ecc95a3
	s_mov_b32 s38, 0x3f317218
	s_mov_b32 s39, 0x7f800000
	s_mov_b32 s40, 0x33800000
	v_mov_b32_e32 v234, 0x7f800000
	v_mov_b32_e32 v235, 0x7fc00000
	v_mov_b32_e32 v236, 0xff800000
	v_mov_b32_e32 v192, 0x3f317218
	v_readlane_b32 s41, v254, 9
	v_readlane_b32 s42, v254, 10
	v_readlane_b32 s43, v254, 11
	v_readlane_b32 s48, v254, 16
	v_readlane_b32 s49, v254, 17
	v_readlane_b32 s50, v254, 18
	v_readlane_b32 s51, v254, 19
	global_load_dword v251, v[182:183], off
	s_branch .LBB0_189

; DI void row_stats(const float (&v)[16], float& mean, float& rstd) {
;     float s = 0.f;
; #pragma unroll
;     for (int i = 0; i < 16; ++i) s += v[i];
;     mean = wsum(s) * (1.f / 1024.f);
;     float q = 0.f;
; #pragma unroll
;     for (int i = 0; i < 16; ++i) { float d = v[i] - mean; q += d * d; }
;     rstd = rsqrtf(wsum(q) * (1.f / 1024.f) + 1e-5f);
; DI void phase1(const Params& p, unsigned char* smem) {
;     ...
;             for (int i = 0; i < 4; ++i) { float4 t = *(const float4*)(p.in[0] + (size_t)(row0 + rr) * 1024 + i * 256 + lane * 4); vv[rr][4 * i] = t.x; vv[rr][4 * i + 1] = t.y; vv[rr][4 * i + 2] = t.z; vv[rr][4 * i + 3] = t.w; }
; #pragma unroll
;         for (int rr = 0; rr < 4; ++rr) {
;             const int row = row0 + rr;
;             float mean, rstd; row_stats(vv[rr], mean, rstd);
;             const float* mb = mod + (row >> 13) * 6144;
;             float ga[8];
; #pragma unroll
;             for (int j = 0; j < 8; ++j) ga[j] = 0.f;
; #pragma unroll
;             for (int i = 0; i < 4; ++i) {
;                 int c = i * 256 + lane * 4;
;                 float4 sh = *(const float4*)(mb + c), sc = *(const float4*)(mb + 1024 + c);
;                 f32x4 o;
;                 o[0] = (vv[rr][4 * i] - mean) * rstd * (1.f + sc.x) + sh.x;
;                 o[1] = (vv[rr][4 * i + 1] - mean) * rstd * (1.f + sc.y) + sh.y;
;                 o[2] = (vv[rr][4 * i + 2] - mean) * rstd * (1.f + sc.z) + sh.z;
;                 o[3] = (vv[rr][4 * i + 3] - mean) * rstd * (1.f + sc.w) + sh.w;
.LBB0_189:
	v_ashrrev_i32_e32 v177, 31, v176
	v_lshlrev_b64 v[128:129], 12, v[176:177]
	v_lshl_add_u64 v[140:141], v[180:181], 0, v[128:129]
	global_load_dwordx4 v[128:131], v[140:141], off
	global_load_dwordx4 v[132:135], v[140:141], off offset:1024
	global_load_dwordx4 v[136:139], v[140:141], off offset:2048
	s_nop 0
	global_load_dwordx4 v[140:143], v[140:141], off offset:3072
	v_ashrrev_i32_e32 v193, 13, v176
	v_lshl_add_u32 v237, v193, 13, v178
	v_add_u32_e32 v212, 1, v176
	v_add_u32_e32 v202, 2, v176
	v_add_u32_e32 v194, 3, v176
	v_ashrrev_i32_e32 v213, 31, v212
	v_ashrrev_i32_e32 v203, 31, v202
	v_ashrrev_i32_e32 v195, 31, v194
	v_mov_b32_e32 v187, v179
	v_mov_b32_e32 v189, v179
	v_mov_b32_e32 v191, v179
	s_waitcnt vmcnt(3)
	v_add_f32_e32 v144, 0, v128
	v_add_f32_e32 v144, v144, v129
	v_add_f32_e32 v144, v144, v130
	v_add_f32_e32 v144, v144, v131
	s_waitcnt vmcnt(2)
	v_add_f32_e32 v144, v144, v132
	v_add_f32_e32 v144, v144, v133
	v_add_f32_e32 v144, v144, v134
	v_add_f32_e32 v144, v144, v135
	s_waitcnt vmcnt(1)
	v_add_f32_e32 v144, v144, v136
	v_add_f32_e32 v144, v144, v137
	v_add_f32_e32 v144, v144, v138
	v_add_f32_e32 v144, v144, v139
	s_waitcnt vmcnt(0)
	v_add_f32_e32 v144, v144, v140
	v_add_f32_e32 v144, v144, v141
	v_add_f32_e32 v144, v144, v142
	v_add_f32_e32 v144, v144, v143
	s_nop 1
	v_add_f32_dpp v144, v144, v144 quad_perm:[1,0,3,2] row_mask:0xf bank_mask:0xf bound_ctrl:1
	s_nop 1
	v_add_f32_dpp v144, v144, v144 quad_perm:[2,3,0,1] row_mask:0xf bank_mask:0xf bound_ctrl:1
	s_nop 1
	v_add_f32_dpp v144, v144, v144 row_half_mirror row_mask:0xf bank_mask:0xf bound_ctrl:1
	s_nop 1
	v_add_f32_dpp v144, v144, v144 row_mirror row_mask:0xf bank_mask:0xf bound_ctrl:1
	s_nop 0
	v_readlane_b32 s17, v144, 16
	v_readlane_b32 s16, v144, 0
	v_readlane_b32 s18, v144, 32
	v_readlane_b32 s19, v144, 48
	v_mov_b32_e32 v144, s17
	v_add_f32_e32 v144, s16, v144
	v_add_f32_e32 v144, s18, v144
	v_add_f32_e32 v144, s19, v144
	v_mul_f32_e32 v144, 0x3a800000, v144
	v_pk_add_f32 v[146:147], v[128:129], v[144:145] op_sel_hi:[1,0] neg_lo:[0,1] neg_hi:[0,1]
	v_mul_i32_i24_e32 v128, 0x1800, v193
	v_ashrrev_i32_e32 v129, 31, v128
	v_pk_add_f32 v[222:223], v[132:133], v[144:145] op_sel_hi:[1,0] neg_lo:[0,1] neg_hi:[0,1]
	v_lshl_add_u64 v[132:133], v[128:129], 2, s[62:63]
	s_mov_b64 s[16:17], 0x1000
	v_lshl_add_u64 v[216:217], v[132:133], 0, s[16:17]
	v_lshl_add_u64 v[198:199], v[216:217], 0, v[178:179]
	v_pk_add_f32 v[148:149], v[130:131], v[144:145] op_sel_hi:[1,0] neg_lo:[0,1] neg_hi:[0,1]
	ds_read_b128 v[128:131], v237 offset:5120
	v_pk_add_f32 v[206:207], v[134:135], v[144:145] op_sel_hi:[1,0] neg_lo:[0,1] neg_hi:[0,1]
	v_pk_add_f32 v[214:215], v[136:137], v[144:145] op_sel_hi:[1,0] neg_lo:[0,1] neg_hi:[0,1]
	v_pk_add_f32 v[210:211], v[138:139], v[144:145] op_sel_hi:[1,0] neg_lo:[0,1] neg_hi:[0,1]
	v_pk_add_f32 v[200:201], v[140:141], v[144:145] op_sel_hi:[1,0] neg_lo:[0,1] neg_hi:[0,1]
	v_pk_add_f32 v[208:209], v[142:143], v[144:145] op_sel_hi:[1,0] neg_lo:[0,1] neg_hi:[0,1]
	v_lshl_add_u64 v[196:197], v[132:133], 0, v[178:179]
	s_waitcnt lgkmcnt(0)
	v_pk_add_f32 v[134:135], v[128:129], 1.0 op_sel_hi:[1,0]
	v_pk_mul_f32 v[128:129], v[146:147], v[146:147]
	v_pk_add_f32 v[136:137], v[130:131], 1.0 op_sel_hi:[1,0]
	v_add_f32_e32 v130, v128, v129
	v_pk_mul_f32 v[128:129], v[148:149], v[148:149]
	s_nop 0
	v_add_f32_e32 v128, v128, v130
	v_add_f32_e32 v130, v129, v128
	v_pk_mul_f32 v[128:129], v[222:223], v[222:223]
	s_nop 0
	v_add_f32_e32 v128, v128, v130
	v_add_f32_e32 v130, v129, v128
	v_pk_mul_f32 v[128:129], v[206:207], v[206:207]
	s_nop 0
	v_add_f32_e32 v128, v128, v130
	v_add_f32_e32 v130, v129, v128
	v_pk_mul_f32 v[128:129], v[214:215], v[214:215]
	s_nop 0
	v_add_f32_e32 v128, v128, v130
	v_add_f32_e32 v130, v129, v128
	v_pk_mul_f32 v[128:129], v[210:211], v[210:211]
	s_nop 0
	v_add_f32_e32 v128, v128, v130
	v_add_f32_e32 v130, v129, v128
	v_pk_mul_f32 v[128:129], v[200:201], v[200:201]
	s_nop 0
	v_add_f32_e32 v128, v128, v130
	v_add_f32_e32 v130, v129, v128
	v_pk_mul_f32 v[128:129], v[208:209], v[208:209]
	s_nop 0
	v_add_f32_e32 v128, v128, v130
	v_add_f32_e32 v128, v129, v128
	s_nop 1
	v_add_f32_dpp v128, v128, v128 quad_perm:[1,0,3,2] row_mask:0xf bank_mask:0xf bound_ctrl:1
	s_nop 1
	v_add_f32_dpp v128, v128, v128 quad_perm:[2,3,0,1] row_mask:0xf bank_mask:0xf bound_ctrl:1
	s_nop 1
	v_add_f32_dpp v128, v128, v128 row_half_mirror row_mask:0xf bank_mask:0xf bound_ctrl:1
	s_nop 1
	v_add_f32_dpp v128, v128, v128 row_mirror row_mask:0xf bank_mask:0xf bound_ctrl:1
	s_nop 0
	v_readlane_b32 s17, v128, 16
	v_readlane_b32 s16, v128, 0
	v_readlane_b32 s18, v128, 32
	v_readlane_b32 s19, v128, 48
	v_mov_b32_e32 v128, s17
	v_add_f32_e32 v128, s16, v128
	v_add_f32_e32 v128, s18, v128
	v_add_f32_e32 v128, s19, v128
	v_fmamk_f32 v128, v128, 0x3a800000, v232
	v_mul_f32_e32 v129, 0x4b800000, v128
	v_cmp_gt_f32_e64 s[16:17], s36, v128
	s_nop 1
	v_cndmask_b32_e64 v128, v128, v129, s[16:17]
	v_rsq_f32_e32 v128, v128
	s_nop 0
	v_mul_f32_e32 v129, 0x45800000, v128
	v_cndmask_b32_e64 v224, v128, v129, s[16:17]
	ds_read_b128 v[128:131], v237 offset:1024
	v_pk_mul_f32 v[132:133], v[146:147], v[224:225] op_sel_hi:[1,0]
	v_pk_mul_f32 v[222:223], v[222:223], v[224:225] op_sel_hi:[1,0]
	v_pk_mul_f32 v[206:207], v[206:207], v[224:225] op_sel_hi:[1,0]
	v_pk_mul_f32 v[214:215], v[214:215], v[224:225] op_sel_hi:[1,0]
	v_pk_mul_f32 v[210:211], v[210:211], v[224:225] op_sel_hi:[1,0]
	v_pk_mul_f32 v[200:201], v[200:201], v[224:225] op_sel_hi:[1,0]
	s_waitcnt lgkmcnt(0)
; DI uint2 pk4(f32x4 v) { return make_uint2(pk2(v[0], v[1]), pk2(v[2], v[3])); }
; DI void phase1(const Params& p, unsigned char* smem) {
;     ...
;             for (int i = 0; i < 4; ++i) { float4 t = *(const float4*)(p.in[0] + (size_t)(row0 + rr) * 1024 + i * 256 + lane * 4); vv[rr][4 * i] = t.x; vv[rr][4 * i + 1] = t.y; vv[rr][4 * i + 2] = t.z; vv[rr][4 * i + 3] = t.w; }
; #pragma unroll
;         for (int rr = 0; rr < 4; ++rr) {
;             const int row = row0 + rr;
;             float mean, rstd; row_stats(vv[rr], mean, rstd);
;             const float* mb = mod + (row >> 13) * 6144;
;             float ga[8];
; #pragma unroll
;             for (int j = 0; j < 8; ++j) ga[j] = 0.f;
; #pragma unroll
;             for (int i = 0; i < 4; ++i) {
;                 int c = i * 256 + lane * 4;
;                 float4 sh = *(const float4*)(mb + c), sc = *(const float4*)(mb + 1024 + c);
;                 f32x4 o;
;                 o[0] = (vv[rr][4 * i] - mean) * rstd * (1.f + sc.x) + sh.x;
;                 o[1] = (vv[rr][4 * i + 1] - mean) * rstd * (1.f + sc.y) + sh.y;
;                 o[2] = (vv[rr][4 * i + 2] - mean) * rstd * (1.f + sc.z) + sh.z;
;                 o[3] = (vv[rr][4 * i + 3] - mean) * rstd * (1.f + sc.w) + sh.w;
;                 *(uint2*)(h1 + (size_t)row * 1024 + c) = pk4(o);
; #pragma unroll
;                 for (int e = 0; e < 4; ++e) {
;                     const float4 w0 = gw0[i * 4 + e], w1 = gw1[i * 4 + e];
;                     ga[0] += o[e] * w0.x; ga[1] += o[e] * w0.y; ga[2] += o[e] * w0.z; ga[3] += o[e] * w0.w;
;                     ga[4] += o[e] * w1.x; ga[5] += o[e] * w1.y; ga[6] += o[e] * w1.z; ga[7] += o[e] * w1.w;
;                 }
	v_pk_fma_f32 v[220:221], v[134:135], v[132:133], v[128:129]
	v_pk_mul_f32 v[128:129], v[148:149], v[224:225] op_sel_hi:[1,0]
	v_lshlrev_b64 v[132:133], 12, v[194:195]
	v_pk_fma_f32 v[218:219], v[136:137], v[128:129], v[130:131]
	v_lshlrev_b64 v[128:129], 11, v[176:177]
	v_lshl_add_u64 v[226:227], v[184:185], 0, v[128:129]
	v_lshlrev_b64 v[128:129], 12, v[212:213]
	v_lshlrev_b64 v[130:131], 12, v[202:203]
	v_lshl_add_u64 v[128:129], v[180:181], 0, v[128:129]
	v_lshl_add_u64 v[130:131], v[180:181], 0, v[130:131]
	v_lshl_add_u64 v[204:205], v[180:181], 0, v[132:133]
	v_cvt_pk_bf16_f32 v228, v220, v221
	v_cvt_pk_bf16_f32 v229, v218, v219
	global_load_dwordx4 v[172:175], v[128:129], off
	global_load_dwordx4 v[168:171], v[128:129], off offset:1024
	global_load_dwordx4 v[164:167], v[128:129], off offset:2048
	global_load_dwordx4 v[160:163], v[128:129], off offset:3072
	global_load_dwordx4 v[156:159], v[130:131], off
	global_load_dwordx4 v[152:155], v[130:131], off offset:1024
	global_load_dwordx4 v[148:151], v[130:131], off offset:2048
	global_load_dwordx4 v[144:147], v[130:131], off offset:3072
	global_load_dwordx4 v[140:143], v[204:205], off
	global_load_dwordx4 v[136:139], v[204:205], off offset:1024
	global_load_dwordx4 v[132:135], v[204:205], off offset:2048
	s_nop 0
	global_load_dwordx4 v[128:131], v[204:205], off offset:3072
	v_lshl_add_u64 v[204:205], v[216:217], 0, v[186:187]
	global_store_dwordx2 v[226:227], v[228:229], off
	ds_read_b128 v[238:241], v237 offset:6144
	v_fma_f32 v177, v0, v220, 0
	v_fmac_f32_e32 v177, v8, v221
	v_fmac_f32_e32 v177, v16, v218
	v_fmac_f32_e32 v177, v24, v219
	v_fma_f32 v187, v1, v220, 0
	v_fmac_f32_e32 v187, v9, v221
	v_fmac_f32_e32 v187, v17, v218
	v_fmac_f32_e32 v187, v25, v219
	s_waitcnt lgkmcnt(0)
	v_pk_add_f32 v[228:229], v[238:239], 1.0 op_sel_hi:[1,0]
	v_pk_add_f32 v[242:243], v[240:241], 1.0 op_sel_hi:[1,0]
	ds_read_b128 v[238:241], v237 offset:2048
	s_waitcnt lgkmcnt(0)
	v_pk_fma_f32 v[228:229], v[222:223], v[228:229], v[238:239]
	v_pk_fma_f32 v[222:223], v[206:207], v[242:243], v[240:241]
	v_cvt_pk_bf16_f32 v206, v228, v229
	v_cvt_pk_bf16_f32 v207, v222, v223
	global_store_dwordx2 v[226:227], v[206:207], off offset:512
	v_lshl_add_u64 v[206:207], v[216:217], 0, v[188:189]
	ds_read_b128 v[238:241], v237 offset:7168
	v_fmac_f32_e32 v177, v32, v228
	v_fmac_f32_e32 v177, v40, v229
	v_fmac_f32_e32 v177, v48, v222
	v_fmac_f32_e32 v177, v56, v223
	v_fma_f32 v189, v2, v220, 0
	v_fmac_f32_e32 v187, v33, v228
	v_fmac_f32_e32 v189, v10, v221
	v_fmac_f32_e32 v187, v41, v229
	v_fmac_f32_e32 v189, v18, v218
	v_fmac_f32_e32 v187, v49, v222
	v_fmac_f32_e32 v189, v26, v219
	v_fmac_f32_e32 v187, v57, v223
	v_fmac_f32_e32 v189, v34, v228
	v_fmac_f32_e32 v189, v42, v229
	v_fmac_f32_e32 v189, v50, v222
	v_fmac_f32_e32 v189, v58, v223
	s_waitcnt lgkmcnt(0)
	v_pk_add_f32 v[242:243], v[238:239], 1.0 op_sel_hi:[1,0]
	v_pk_add_f32 v[244:245], v[240:241], 1.0 op_sel_hi:[1,0]
	ds_read_b128 v[238:241], v237 offset:3072
	s_waitcnt lgkmcnt(0)
	v_pk_fma_f32 v[238:239], v[214:215], v[242:243], v[238:239]
	v_pk_fma_f32 v[210:211], v[210:211], v[244:245], v[240:241]
	v_pk_mul_f32 v[240:241], v[208:209], v[224:225] op_sel_hi:[1,0]
	v_cvt_pk_bf16_f32 v208, v238, v239
	v_cvt_pk_bf16_f32 v209, v210, v211
	global_store_dwordx2 v[226:227], v[208:209], off offset:1024
	v_lshl_add_u64 v[208:209], v[216:217], 0, v[190:191]
	ds_read_b128 v[214:217], v237 offset:8192
	v_fmac_f32_e32 v177, v64, v238
	v_fmac_f32_e32 v177, v72, v239
	v_fmac_f32_e32 v177, v80, v210
	v_fmac_f32_e32 v177, v88, v211
	v_fma_f32 v191, v3, v220, 0
	v_fmac_f32_e32 v187, v65, v238
	v_fmac_f32_e32 v191, v11, v221
	v_fmac_f32_e32 v187, v73, v239
	v_fmac_f32_e32 v191, v19, v218
	v_fmac_f32_e32 v187, v81, v210
	v_fmac_f32_e32 v191, v27, v219
	v_fmac_f32_e32 v187, v89, v211
	v_fmac_f32_e32 v191, v35, v228
	v_fmac_f32_e32 v189, v66, v238
	v_fmac_f32_e32 v191, v43, v229
	v_fmac_f32_e32 v189, v74, v239
	v_fmac_f32_e32 v191, v51, v222
	v_fmac_f32_e32 v189, v82, v210
	v_fmac_f32_e32 v191, v59, v223
	v_fmac_f32_e32 v189, v90, v211
	v_fmac_f32_e32 v191, v67, v238
	v_fmac_f32_e32 v191, v75, v239
	v_fmac_f32_e32 v191, v83, v210
	v_fmac_f32_e32 v191, v91, v211
	v_fma_f32 v224, v6, v220, 0
	v_fmac_f32_e32 v224, v14, v221
	v_fmac_f32_e32 v224, v22, v218
	v_fmac_f32_e32 v224, v30, v219
	v_fmac_f32_e32 v224, v38, v228
	v_fmac_f32_e32 v224, v46, v229
	v_fmac_f32_e32 v224, v54, v222
	v_fmac_f32_e32 v224, v62, v223
	v_fmac_f32_e32 v224, v70, v238
	v_fmac_f32_e32 v224, v78, v239
	v_fmac_f32_e32 v224, v86, v210
	v_fmac_f32_e32 v224, v94, v211
	s_waitcnt lgkmcnt(0)
	v_pk_add_f32 v[242:243], v[214:215], 1.0 op_sel_hi:[1,0]
	v_pk_add_f32 v[244:245], v[216:217], 1.0 op_sel_hi:[1,0]
	ds_read_b128 v[214:217], v237 offset:4096
	s_waitcnt vmcnt(3) lgkmcnt(0)
; DI float wsum(float v) {
;     v += dpp_f(v, 0); v += dpp_f(v, 1); v += dpp_f(v, 2); v += dpp_f(v, 3);
;     const int x = __builtin_bit_cast(int, v);
;     return __builtin_bit_cast(float, __builtin_amdgcn_readlane(x, 0)) + __builtin_bit_cast(float, __builtin_amdgcn_readlane(x, 16))
;          + __builtin_bit_cast(float, __builtin_amdgcn_readlane(x, 32)) + __builtin_bit_cast(float, __builtin_amdgcn_readlane(x, 48));
; DI void phase1(const Params& p, unsigned char* smem) {
;     ...
;                 for (int e = 0; e < 4; ++e) {
;                     const float4 w0 = gw0[i * 4 + e], w1 = gw1[i * 4 + e];
;                     ga[0] += o[e] * w0.x; ga[1] += o[e] * w0.y; ga[2] += o[e] * w0.z; ga[3] += o[e] * w0.w;
;                     ga[4] += o[e] * w1.x; ga[5] += o[e] * w1.y; ga[6] += o[e] * w1.z; ga[7] += o[e] * w1.w;
;                 }
;             }
; #pragma unroll
;             for (int j = 0; j < 8; ++j) ga[j] = wsum(ga[j]);
;             if (lane < 8) {
;                 float val = ga[0];
; #pragma unroll
;                 for (int j = 1; j < 8; ++j) val = (lane == j) ? ga[j] : val;
;                 val += p.in[5][2048 + lane];
;                 const int b = row >> 13, sidx = row & 8191;
;                 if (lane < 4) ig[(size_t)(b * 4 + lane) * 8192 + sidx] = val;
	v_pk_fma_f32 v[200:201], v[200:201], v[242:243], v[214:215]
	s_nop 0
	v_fmac_f32_e32 v177, v96, v200
	v_pk_fma_f32 v[214:215], v[240:241], v[244:245], v[216:217]
	v_fmac_f32_e32 v177, v104, v201
	v_fmac_f32_e32 v177, v112, v214
	v_cvt_pk_bf16_f32 v216, v200, v201
	v_cvt_pk_bf16_f32 v217, v214, v215
	v_fmac_f32_e32 v177, v120, v215
	global_store_dwordx2 v[226:227], v[216:217], off offset:1536
	v_fma_f32 v216, v4, v220, 0
	v_fmac_f32_e32 v187, v97, v200
	v_add_f32_dpp v177, v177, v177 quad_perm:[1,0,3,2] row_mask:0xf bank_mask:0xf bound_ctrl:1
	v_fmac_f32_e32 v216, v12, v221
	v_fmac_f32_e32 v187, v105, v201
	v_add_f32_dpp v177, v177, v177 quad_perm:[2,3,0,1] row_mask:0xf bank_mask:0xf bound_ctrl:1
	v_fmac_f32_e32 v216, v20, v218
	v_fmac_f32_e32 v187, v113, v214
	v_add_f32_dpp v177, v177, v177 row_half_mirror row_mask:0xf bank_mask:0xf bound_ctrl:1
	v_fmac_f32_e32 v216, v28, v219
	v_fmac_f32_e32 v187, v121, v215
	v_add_f32_dpp v177, v177, v177 row_mirror row_mask:0xf bank_mask:0xf bound_ctrl:1
	v_fma_f32 v217, v5, v220, 0
	v_fmac_f32_e32 v216, v36, v228
	v_fmac_f32_e32 v189, v98, v200
	v_readlane_b32 s16, v177, 0
	v_readlane_b32 s31, v177, 16
	v_readlane_b32 s17, v177, 32
	v_readlane_b32 s30, v177, 48
	v_add_f32_dpp v177, v187, v187 quad_perm:[1,0,3,2] row_mask:0xf bank_mask:0xf bound_ctrl:1
	v_fmac_f32_e32 v217, v13, v221
	v_fmac_f32_e32 v216, v44, v229
	v_fmac_f32_e32 v189, v106, v201
	v_add_f32_dpp v177, v177, v177 quad_perm:[2,3,0,1] row_mask:0xf bank_mask:0xf bound_ctrl:1
	v_fmac_f32_e32 v217, v21, v218
	v_fmac_f32_e32 v216, v52, v222
	v_fmac_f32_e32 v189, v114, v214
	v_add_f32_dpp v177, v177, v177 row_half_mirror row_mask:0xf bank_mask:0xf bound_ctrl:1
	v_fmac_f32_e32 v217, v29, v219
	v_fmac_f32_e32 v216, v60, v223
	v_fmac_f32_e32 v189, v122, v215
	v_add_f32_dpp v177, v177, v177 row_mirror row_mask:0xf bank_mask:0xf bound_ctrl:1
	v_fmac_f32_e32 v217, v37, v228
	v_fmac_f32_e32 v216, v68, v238
	v_fmac_f32_e32 v191, v99, v200
	v_readlane_b32 s34, v177, 0
	v_readlane_b32 s42, v177, 16
	v_readlane_b32 s35, v177, 32
	v_readlane_b32 s41, v177, 48
	v_add_f32_dpp v177, v189, v189 quad_perm:[1,0,3,2] row_mask:0xf bank_mask:0xf bound_ctrl:1
	v_fmac_f32_e32 v217, v45, v229
	v_fmac_f32_e32 v216, v76, v239
	v_fmac_f32_e32 v191, v107, v201
	v_add_f32_dpp v177, v177, v177 quad_perm:[2,3,0,1] row_mask:0xf bank_mask:0xf bound_ctrl:1
	v_fmac_f32_e32 v217, v53, v222
	v_fmac_f32_e32 v216, v84, v210
	v_fmac_f32_e32 v191, v115, v214
	v_add_f32_dpp v177, v177, v177 row_half_mirror row_mask:0xf bank_mask:0xf bound_ctrl:1
	v_fmac_f32_e32 v217, v61, v223
	v_fmac_f32_e32 v216, v92, v211
	v_fmac_f32_e32 v191, v123, v215
	v_add_f32_dpp v177, v177, v177 row_mirror row_mask:0xf bank_mask:0xf bound_ctrl:1
	v_fma_f32 v220, v7, v220, 0
	v_fmac_f32_e32 v217, v69, v238
	v_fmac_f32_e32 v216, v100, v200
	v_readlane_b32 s43, v177, 0
	v_readlane_b32 s46, v177, 16
	v_readlane_b32 s44, v177, 32
	v_readlane_b32 s45, v177, 48
	v_add_f32_dpp v177, v191, v191 quad_perm:[1,0,3,2] row_mask:0xf bank_mask:0xf bound_ctrl:1
	v_fmac_f32_e32 v220, v15, v221
	v_fmac_f32_e32 v217, v77, v239
	v_fmac_f32_e32 v216, v108, v201
	v_add_f32_dpp v177, v177, v177 quad_perm:[2,3,0,1] row_mask:0xf bank_mask:0xf bound_ctrl:1
	v_fmac_f32_e32 v220, v23, v218
	v_fmac_f32_e32 v217, v85, v210
	v_fmac_f32_e32 v216, v116, v214
	v_add_f32_dpp v177, v177, v177 row_half_mirror row_mask:0xf bank_mask:0xf bound_ctrl:1
	v_fmac_f32_e32 v220, v31, v219
	v_fmac_f32_e32 v217, v93, v211
	v_fmac_f32_e32 v216, v124, v215
	v_add_f32_dpp v177, v177, v177 row_mirror row_mask:0xf bank_mask:0xf bound_ctrl:1
	v_fmac_f32_e32 v220, v39, v228
	v_fmac_f32_e32 v217, v101, v200
	v_readlane_b32 s47, v177, 0
	v_readlane_b32 s50, v177, 16
	v_readlane_b32 s48, v177, 32
	v_readlane_b32 s49, v177, 48
	v_add_f32_dpp v177, v216, v216 quad_perm:[1,0,3,2] row_mask:0xf bank_mask:0xf bound_ctrl:1
	v_fmac_f32_e32 v220, v47, v229
	v_fmac_f32_e32 v217, v109, v201
	v_add_f32_dpp v177, v177, v177 quad_perm:[2,3,0,1] row_mask:0xf bank_mask:0xf bound_ctrl:1
	v_fmac_f32_e32 v220, v55, v222
	v_fmac_f32_e32 v217, v117, v214
	v_add_f32_dpp v177, v177, v177 row_half_mirror row_mask:0xf bank_mask:0xf bound_ctrl:1
	v_fmac_f32_e32 v220, v63, v223
	v_fmac_f32_e32 v217, v125, v215
	v_add_f32_dpp v177, v177, v177 row_mirror row_mask:0xf bank_mask:0xf bound_ctrl:1
	v_fmac_f32_e32 v220, v71, v238
	v_fmac_f32_e32 v224, v102, v200
	v_readlane_b32 s51, v177, 0
	v_readlane_b32 s55, v177, 16
	v_readlane_b32 s52, v177, 32
	v_readlane_b32 s53, v177, 48
	v_add_f32_dpp v177, v217, v217 quad_perm:[1,0,3,2] row_mask:0xf bank_mask:0xf bound_ctrl:1
	v_fmac_f32_e32 v220, v79, v239
	v_fmac_f32_e32 v224, v110, v201
	v_add_f32_dpp v177, v177, v177 quad_perm:[2,3,0,1] row_mask:0xf bank_mask:0xf bound_ctrl:1
	v_fmac_f32_e32 v220, v87, v210
	v_fmac_f32_e32 v224, v118, v214
	v_add_f32_dpp v177, v177, v177 row_half_mirror row_mask:0xf bank_mask:0xf bound_ctrl:1
	v_fmac_f32_e32 v220, v95, v211
	v_fmac_f32_e32 v224, v126, v215
	v_add_f32_dpp v177, v177, v177 row_mirror row_mask:0xf bank_mask:0xf bound_ctrl:1
	v_fmac_f32_e32 v220, v103, v200
	v_readlane_b32 s56, v177, 0
	v_readlane_b32 s73, v177, 16
	v_readlane_b32 s57, v177, 32
	v_readlane_b32 s72, v177, 48
	v_add_f32_dpp v177, v224, v224 quad_perm:[1,0,3,2] row_mask:0xf bank_mask:0xf bound_ctrl:1
	v_fmac_f32_e32 v220, v111, v201
	v_fmac_f32_e32 v220, v119, v214
	v_add_f32_dpp v177, v177, v177 quad_perm:[2,3,0,1] row_mask:0xf bank_mask:0xf bound_ctrl:1
	v_fmac_f32_e32 v220, v127, v215
	s_nop 0
	v_add_f32_dpp v177, v177, v177 row_half_mirror row_mask:0xf bank_mask:0xf bound_ctrl:1
	s_nop 1
	v_add_f32_dpp v177, v177, v177 row_mirror row_mask:0xf bank_mask:0xf bound_ctrl:1
	s_nop 0
	v_readlane_b32 s74, v177, 0
	v_readlane_b32 s83, v177, 16
	v_readlane_b32 s75, v177, 32
	v_readlane_b32 s82, v177, 48
	v_add_f32_dpp v177, v220, v220 quad_perm:[1,0,3,2] row_mask:0xf bank_mask:0xf bound_ctrl:1
	s_nop 1
	v_add_f32_dpp v177, v177, v177 quad_perm:[2,3,0,1] row_mask:0xf bank_mask:0xf bound_ctrl:1
	s_nop 1
	v_add_f32_dpp v177, v177, v177 row_half_mirror row_mask:0xf bank_mask:0xf bound_ctrl:1
	s_nop 1
	v_add_f32_dpp v177, v177, v177 row_mirror row_mask:0xf bank_mask:0xf bound_ctrl:1
	s_nop 0
	v_readlane_b32 s84, v177, 0
	v_readlane_b32 s87, v177, 16
	v_readlane_b32 s85, v177, 32
	v_readlane_b32 s86, v177, 48
	v_lshlrev_b32_e32 v177, 2, v193
	v_add_u32_e32 v200, v231, v177
	v_add_u32_e32 v210, v177, v230
	v_ashrrev_i32_e32 v201, 31, v200
	v_ashrrev_i32_e32 v211, 31, v210
	v_lshlrev_b64 v[200:201], 15, v[200:201]
	v_lshlrev_b64 v[210:211], 15, v[210:211]
	v_lshl_add_u64 v[200:201], s[20:21], 0, v[200:201]
	v_lshl_add_u64 v[210:211], s[88:89], 0, v[210:211]
	s_and_saveexec_b64 s[28:29], vcc
	s_cbranch_execz .LBB0_197
; DI float logsig(float x) { return (x < 0.f) ? (x - log1pf(__expf(x))) : (-log1pf(__expf(-x))); }
; DI void phase1(const Params& p, unsigned char* smem) {
;     ...
;             if (lane < 8) {
;                 float val = ga[0];
; #pragma unroll
;                 for (int j = 1; j < 8; ++j) val = (lane == j) ? ga[j] : val;
;                 val += p.in[5][2048 + lane];
;                 const int b = row >> 13, sidx = row & 8191;
;                 if (lane < 4) ig[(size_t)(b * 4 + lane) * 8192 + sidx] = val;
;                 else lf[(size_t)(b * 4 + lane - 4) * 8192 + sidx] = logsig(val);
	v_mov_b32_e32 v215, s42
	v_mov_b32_e32 v216, s31
	v_mov_b32_e32 v214, s46
	v_add_f32_e32 v215, s34, v215
	v_add_f32_e32 v216, s16, v216
	v_mov_b32_e32 v193, s50
	v_add_f32_e32 v214, s43, v214
	v_add_f32_e32 v215, s35, v215
	v_add_f32_e32 v216, s17, v216
	v_mov_b32_e32 v191, s55
	v_add_f32_e32 v193, s47, v193
	v_add_f32_e32 v214, s44, v214
	v_add_f32_e32 v215, s41, v215
	v_add_f32_e32 v216, s30, v216
	v_mov_b32_e32 v189, s73
	v_add_f32_e32 v191, s51, v191
	v_add_f32_e32 v193, s48, v193
	v_add_f32_e32 v214, s45, v214
	v_cndmask_b32_e64 v215, v216, v215, s[0:1]
	v_mov_b32_e32 v187, s83
	v_add_f32_e32 v189, s56, v189
	v_add_f32_e32 v191, s52, v191
	v_add_f32_e32 v193, s49, v193
	v_cndmask_b32_e64 v214, v215, v214, s[14:15]
	v_mov_b32_e32 v177, s87
	v_add_f32_e32 v187, s74, v187
	v_add_f32_e32 v189, s57, v189
	v_add_f32_e32 v191, s53, v191
	v_cndmask_b32_e64 v193, v214, v193, s[4:5]
	v_add_f32_e32 v177, s84, v177
	v_add_f32_e32 v187, s75, v187
	v_add_f32_e32 v189, s72, v189
	v_cndmask_b32_e64 v191, v193, v191, s[6:7]
	v_add_f32_e32 v177, s85, v177
	v_add_f32_e32 v187, s82, v187
	v_cndmask_b32_e64 v189, v191, v189, s[8:9]
	v_add_f32_e32 v177, s86, v177
	v_cndmask_b32_e64 v187, v189, v187, s[10:11]
	v_cndmask_b32_e64 v177, v187, v177, s[12:13]
	v_mov_b32_e32 v187, v251
	v_mov_b64_e32 v[214:215], v[210:211]
	v_add_f32_e32 v177, v177, v187
	s_and_saveexec_b64 s[30:31], s[24:25]
	s_cbranch_execz .LBB0_196
	v_cmp_ngt_f32_e64 s[16:17], 0, v177
	s_and_saveexec_b64 s[34:35], s[16:17]
	s_xor_b64 s[34:35], exec, s[34:35]
	s_cbranch_execz .LBB0_193
	v_mul_f32_e32 v177, 0xbfb8aa3b, v177
	v_exp_f32_e32 v177, v177
	s_nop 0
	v_add_f32_e32 v187, 1.0, v177
	v_add_f32_e32 v189, -1.0, v187
	v_sub_f32_e32 v193, v189, v187
	v_frexp_mant_f32_e32 v191, v187
	v_cvt_f64_f32_e32 v[214:215], v187
	v_sub_f32_e32 v189, v177, v189
	v_add_f32_e32 v193, 1.0, v193
	v_add_f32_e32 v189, v189, v193
	v_frexp_exp_i32_f64_e32 v193, v[214:215]
	v_cmp_gt_f32_e64 s[16:17], s37, v191
	s_nop 1
	v_subbrev_co_u32_e64 v191, s[16:17], 0, v193, s[16:17]
	v_sub_u32_e32 v193, 0, v191
	v_ldexp_f32 v187, v187, v193
	v_ldexp_f32 v189, v189, v193
	v_add_f32_e32 v193, -1.0, v187
	v_add_f32_e32 v215, 1.0, v187
	v_add_f32_e32 v214, 1.0, v193
	v_add_f32_e32 v216, -1.0, v215
	v_sub_f32_e32 v214, v187, v214
	v_sub_f32_e32 v187, v187, v216
	v_add_f32_e32 v187, v189, v187
	v_add_f32_e32 v214, v189, v214
	v_add_f32_e32 v189, v215, v187
	v_rcp_f32_e32 v222, v189
	v_sub_f32_e32 v215, v189, v215
	v_sub_f32_e32 v187, v187, v215
	v_add_f32_e32 v215, v193, v214
	v_mul_f32_e32 v223, v215, v222
	v_mul_f32_e32 v216, v189, v223
	v_fma_f32 v218, v223, v189, -v216
	v_sub_f32_e32 v193, v215, v193
	v_fmac_f32_e32 v218, v223, v187
	v_sub_f32_e32 v193, v214, v193
	v_add_f32_e32 v214, v216, v218
	v_sub_f32_e32 v217, v215, v214
	v_pk_add_f32 v[220:221], v[214:215], v[216:217] neg_lo:[0,1] neg_hi:[0,1]
	v_mov_b32_e32 v219, v214
	v_pk_add_f32 v[214:215], v[220:221], v[218:219] neg_lo:[0,1] neg_hi:[0,1]
	v_cmp_neq_f32_e64 s[16:17], s39, v177
	v_add_f32_e32 v193, v193, v215
	v_add_f32_e32 v193, v214, v193
	v_add_f32_e32 v215, v217, v193
	v_mul_f32_e32 v224, v222, v215
	v_mul_f32_e32 v216, v189, v224
	v_fma_f32 v218, v224, v189, -v216
	v_fmac_f32_e32 v218, v224, v187
	v_add_f32_e32 v214, v216, v218
	v_sub_f32_e32 v187, v217, v215
	v_sub_f32_e32 v217, v215, v214
	v_pk_add_f32 v[220:221], v[214:215], v[216:217] neg_lo:[0,1] neg_hi:[0,1]
	v_mov_b32_e32 v219, v214
	v_add_f32_e32 v187, v193, v187
	v_pk_add_f32 v[214:215], v[220:221], v[218:219] neg_lo:[0,1] neg_hi:[0,1]
	v_add_f32_e32 v189, v223, v224
	v_add_f32_e32 v187, v187, v215
	v_add_f32_e32 v187, v214, v187
	v_add_f32_e32 v187, v217, v187
	v_sub_f32_e32 v193, v189, v223
	v_mul_f32_e32 v187, v222, v187
	v_sub_f32_e32 v193, v224, v193
	v_add_f32_e32 v187, v193, v187
	v_add_f32_e32 v215, v189, v187
	v_cvt_f32_i32_e32 v214, v191
	v_mul_f32_e32 v216, v215, v215
	v_fmamk_f32 v193, v216, 0x3e9b6dac, v233
	v_fmaak_f32 v193, v216, v193, 0x3f2aaada
	v_sub_f32_e32 v189, v215, v189
	v_ldexp_f32 v217, v215, 1
	v_mul_f32_e32 v215, v215, v216
	v_pk_mul_f32 v[218:219], v[214:215], v[192:193]
	v_sub_f32_e32 v187, v187, v189
	v_fma_f32 v216, v214, s38, -v218
	v_fmac_f32_e32 v216, 0xb102e308, v214
	v_pk_add_f32 v[214:215], v[218:219], v[216:217]
	v_ldexp_f32 v187, v187, 1
	v_sub_f32_e32 v189, v215, v217
	v_sub_f32_e32 v189, v219, v189
	v_add_f32_e32 v221, v187, v189
	v_mov_b32_e32 v220, v218
	v_pk_add_f32 v[218:219], v[214:215], v[218:219] neg_lo:[0,1] neg_hi:[0,1]
	v_pk_add_f32 v[222:223], v[214:215], v[220:221]
	v_mov_b32_e32 v217, v214
	v_mov_b32_e32 v219, v223
	v_pk_add_f32 v[226:227], v[216:217], v[218:219] neg_lo:[0,1] neg_hi:[0,1]
	v_pk_add_f32 v[216:217], v[216:217], v[218:219]
	v_mov_b32_e32 v220, v221
	v_pk_add_f32 v[218:219], v[216:217], v[214:215] op_sel:[1,0] op_sel_hi:[0,1] neg_lo:[0,1] neg_hi:[0,1]
	v_pk_add_f32 v[228:229], v[222:223], v[218:219] op_sel_hi:[1,0] neg_lo:[0,1] neg_hi:[0,1]
	v_mov_b32_e32 v222, v223
	v_mov_b32_e32 v223, v217
	v_pk_mov_b32 v[218:219], v[214:215], v[218:219] op_sel:[1,0]
	v_mov_b32_e32 v221, v214
	v_pk_add_f32 v[218:219], v[222:223], v[218:219] neg_lo:[0,1] neg_hi:[0,1]
	v_mov_b32_e32 v228, v226
	v_pk_add_f32 v[214:215], v[220:221], v[218:219] neg_lo:[0,1] neg_hi:[0,1]
	v_mov_b32_e32 v227, v217
	v_pk_add_f32 v[218:219], v[228:229], v[214:215]
	s_nop 0
	v_pk_add_f32 v[220:221], v[218:219], v[218:219] op_sel:[0,1] op_sel_hi:[1,0]
	s_nop 0
	v_pk_add_f32 v[216:217], v[216:217], v[220:221] op_sel:[1,0] op_sel_hi:[0,1]
	v_mov_b32_e32 v219, v216
	v_pk_add_f32 v[222:223], v[218:219], v[226:227] neg_lo:[0,1] neg_hi:[0,1]
	v_mov_b32_e32 v215, v220
	v_sub_f32_e32 v187, v218, v222
	v_pk_add_f32 v[214:215], v[214:215], v[222:223] neg_lo:[0,1] neg_hi:[0,1]
	v_sub_f32_e32 v187, v226, v187
	v_add_f32_e32 v187, v214, v187
	v_add_f32_e32 v187, v187, v215
	v_add_f32_e32 v187, v216, v187
	v_cndmask_b32_e64 v187, v234, v187, s[16:17]
	v_cmp_ngt_f32_e64 s[16:17], -1.0, v177
	s_nop 1
	v_cndmask_b32_e64 v187, v235, v187, s[16:17]
	v_cmp_neq_f32_e64 s[16:17], -1.0, v177
	s_nop 1
	v_cndmask_b32_e64 v187, v236, v187, s[16:17]
	v_cmp_lt_f32_e64 s[16:17], |v177|, s40
	s_nop 1
	v_cndmask_b32_e64 v177, v187, v177, s[16:17]
	v_xor_b32_e32 v177, 0x80000000, v177

; DI uint2 pk4(f32x4 v) { return make_uint2(pk2(v[0], v[1]), pk2(v[2], v[3])); }
; DI void row_stats(const float (&v)[16], float& mean, float& rstd) {
;     float s = 0.f;
; #pragma unroll
;     for (int i = 0; i < 16; ++i) s += v[i];
;     mean = wsum(s) * (1.f / 1024.f);
;     float q = 0.f;
; #pragma unroll
;     for (int i = 0; i < 16; ++i) { float d = v[i] - mean; q += d * d; }
;     rstd = rsqrtf(wsum(q) * (1.f / 1024.f) + 1e-5f);
; DI void phase1(const Params& p, unsigned char* smem) {
;     ...
;         for (int rr = 0; rr < 4; ++rr) {
;             const int row = row0 + rr;
;             float mean, rstd; row_stats(vv[rr], mean, rstd);
;             const float* mb = mod + (row >> 13) * 6144;
;             float ga[8];
; #pragma unroll
;             for (int j = 0; j < 8; ++j) ga[j] = 0.f;
; #pragma unroll
;             for (int i = 0; i < 4; ++i) {
;                 int c = i * 256 + lane * 4;
;                 float4 sh = *(const float4*)(mb + c), sc = *(const float4*)(mb + 1024 + c);
;                 f32x4 o;
;                 o[0] = (vv[rr][4 * i] - mean) * rstd * (1.f + sc.x) + sh.x;
;                 o[1] = (vv[rr][4 * i + 1] - mean) * rstd * (1.f + sc.y) + sh.y;
;                 o[2] = (vv[rr][4 * i + 2] - mean) * rstd * (1.f + sc.z) + sh.z;
;                 o[3] = (vv[rr][4 * i + 3] - mean) * rstd * (1.f + sc.w) + sh.w;
;                 *(uint2*)(h1 + (size_t)row * 1024 + c) = pk4(o);
.LBB0_197:
	s_or_b64 exec, exec, s[28:29]
	ds_read_b128 v[214:217], v237 offset:5120
	ds_read_b128 v[218:221], v237 offset:1024
	v_add_f32_e32 v177, 0, v172
	v_add_f32_e32 v177, v177, v173
	v_add_f32_e32 v177, v177, v174
	v_add_f32_e32 v177, v177, v175
	v_add_f32_e32 v177, v177, v168
	v_add_f32_e32 v177, v177, v169
	v_add_f32_e32 v177, v177, v170
	v_add_f32_e32 v177, v177, v171
	v_add_f32_e32 v177, v177, v164
	v_add_f32_e32 v177, v177, v165
	v_add_f32_e32 v177, v177, v166
	v_add_f32_e32 v177, v177, v167
	v_add_f32_e32 v177, v177, v160
	v_add_f32_e32 v177, v177, v161
	v_add_f32_e32 v177, v177, v162
	v_add_f32_e32 v177, v177, v163
	v_lshlrev_b64 v[222:223], 11, v[212:213]
	s_nop 0
	v_add_f32_dpp v177, v177, v177 quad_perm:[1,0,3,2] row_mask:0xf bank_mask:0xf bound_ctrl:1
	s_nop 1
	v_add_f32_dpp v177, v177, v177 quad_perm:[2,3,0,1] row_mask:0xf bank_mask:0xf bound_ctrl:1
	s_nop 1
	v_add_f32_dpp v177, v177, v177 row_half_mirror row_mask:0xf bank_mask:0xf bound_ctrl:1
	s_nop 1
	v_add_f32_dpp v177, v177, v177 row_mirror row_mask:0xf bank_mask:0xf bound_ctrl:1
	s_nop 0
	v_readlane_b32 s17, v177, 16
	v_readlane_b32 s16, v177, 0
	v_readlane_b32 s18, v177, 32
	v_readlane_b32 s19, v177, 48
	v_mov_b32_e32 v177, s17
	v_add_f32_e32 v177, s16, v177
	v_add_f32_e32 v177, s18, v177
	v_add_f32_e32 v177, s19, v177
	v_mul_f32_e32 v224, 0x3a800000, v177
	v_pk_add_f32 v[172:173], v[172:173], v[224:225] op_sel_hi:[1,0] neg_lo:[0,1] neg_hi:[0,1]
	v_pk_add_f32 v[174:175], v[174:175], v[224:225] op_sel_hi:[1,0] neg_lo:[0,1] neg_hi:[0,1]
	v_pk_add_f32 v[240:241], v[164:165], v[224:225] op_sel_hi:[1,0] neg_lo:[0,1] neg_hi:[0,1]
	v_pk_add_f32 v[164:165], v[162:163], v[224:225] op_sel_hi:[1,0] neg_lo:[0,1] neg_hi:[0,1]
	v_pk_mul_f32 v[162:163], v[172:173], v[172:173]
	v_pk_add_f32 v[238:239], v[166:167], v[224:225] op_sel_hi:[1,0] neg_lo:[0,1] neg_hi:[0,1]
	v_pk_add_f32 v[166:167], v[160:161], v[224:225] op_sel_hi:[1,0] neg_lo:[0,1] neg_hi:[0,1]
	v_pk_mul_f32 v[160:161], v[174:175], v[174:175]
	v_add_f32_e32 v162, v162, v163
	v_pk_add_f32 v[228:229], v[168:169], v[224:225] op_sel_hi:[1,0] neg_lo:[0,1] neg_hi:[0,1]
	v_add_f32_e32 v160, v160, v162
	v_pk_add_f32 v[226:227], v[170:171], v[224:225] op_sel_hi:[1,0] neg_lo:[0,1] neg_hi:[0,1]
	v_pk_mul_f32 v[170:171], v[228:229], v[228:229]
	v_add_f32_e32 v160, v161, v160
	v_add_f32_e32 v160, v170, v160
	v_pk_mul_f32 v[168:169], v[226:227], v[226:227]
	v_add_f32_e32 v160, v171, v160
	v_add_f32_e32 v160, v168, v160
	v_pk_mul_f32 v[244:245], v[240:241], v[240:241]
	v_add_f32_e32 v160, v169, v160
	v_add_f32_e32 v160, v244, v160
	v_pk_mul_f32 v[242:243], v[238:239], v[238:239]
	v_add_f32_e32 v160, v245, v160
	v_add_f32_e32 v160, v242, v160
	v_pk_mul_f32 v[248:249], v[166:167], v[166:167]
	v_add_f32_e32 v160, v243, v160
	v_add_f32_e32 v160, v248, v160
	v_pk_mul_f32 v[246:247], v[164:165], v[164:165]
	v_add_f32_e32 v160, v249, v160
	v_add_f32_e32 v160, v246, v160
	v_add_f32_e32 v160, v247, v160
	s_waitcnt lgkmcnt(1)
	v_pk_add_f32 v[162:163], v[214:215], 1.0 op_sel_hi:[1,0]
	v_add_f32_dpp v160, v160, v160 quad_perm:[1,0,3,2] row_mask:0xf bank_mask:0xf bound_ctrl:1
	v_pk_add_f32 v[170:171], v[216:217], 1.0 op_sel_hi:[1,0]
	s_nop 0
	v_add_f32_dpp v160, v160, v160 quad_perm:[2,3,0,1] row_mask:0xf bank_mask:0xf bound_ctrl:1
	s_nop 1
	v_add_f32_dpp v160, v160, v160 row_half_mirror row_mask:0xf bank_mask:0xf bound_ctrl:1
	s_nop 1
	v_add_f32_dpp v160, v160, v160 row_mirror row_mask:0xf bank_mask:0xf bound_ctrl:1
	s_nop 0
	v_readlane_b32 s17, v160, 16
	v_readlane_b32 s16, v160, 0
	v_readlane_b32 s18, v160, 32
	v_readlane_b32 s19, v160, 48
	v_mov_b32_e32 v160, s17
	v_add_f32_e32 v160, s16, v160
	v_add_f32_e32 v160, s18, v160
	v_add_f32_e32 v160, s19, v160
	v_fmamk_f32 v160, v160, 0x3a800000, v232
	v_mul_f32_e32 v161, 0x4b800000, v160
	v_cmp_gt_f32_e64 s[16:17], s36, v160
	s_nop 1
	v_cndmask_b32_e64 v160, v160, v161, s[16:17]
	v_rsq_f32_e32 v168, v160
	v_lshl_add_u64 v[160:161], v[184:185], 0, v[222:223]
	v_mul_f32_e32 v169, 0x45800000, v168
	v_cndmask_b32_e64 v222, v168, v169, s[16:17]
	v_pk_mul_f32 v[168:169], v[172:173], v[222:223] op_sel_hi:[1,0]
	s_waitcnt lgkmcnt(0)
	v_pk_fma_f32 v[168:169], v[162:163], v[168:169], v[218:219]
	v_pk_mul_f32 v[162:163], v[174:175], v[222:223] op_sel_hi:[1,0]
	v_pk_mul_f32 v[174:175], v[228:229], v[222:223] op_sel_hi:[1,0]
	v_pk_fma_f32 v[162:163], v[170:171], v[162:163], v[220:221]
	v_cvt_pk_bf16_f32 v170, v168, v169
	v_cvt_pk_bf16_f32 v171, v162, v163
	global_store_dwordx2 v[160:161], v[170:171], off
	ds_read_b128 v[170:173], v237 offset:6144
	s_nop 0
	ds_read_b128 v[214:217], v237 offset:2048
	v_pk_mul_f32 v[218:219], v[226:227], v[222:223] op_sel_hi:[1,0]
	v_pk_mul_f32 v[220:221], v[240:241], v[222:223] op_sel_hi:[1,0]
	v_pk_mul_f32 v[226:227], v[238:239], v[222:223] op_sel_hi:[1,0]
	v_pk_mul_f32 v[228:229], v[166:167], v[222:223] op_sel_hi:[1,0]
	v_pk_mul_f32 v[222:223], v[164:165], v[222:223] op_sel_hi:[1,0]
	v_fma_f32 v177, v0, v168, 0
	v_fma_f32 v187, v1, v168, 0
	v_fma_f32 v189, v2, v168, 0
	v_fma_f32 v191, v3, v168, 0
	v_fma_f32 v193, v4, v168, 0
	v_fma_f32 v213, v5, v168, 0
	v_fma_f32 v224, v6, v168, 0
	v_fma_f32 v225, v7, v168, 0
	v_fmac_f32_e32 v177, v8, v169
	v_fmac_f32_e32 v187, v9, v169
	v_fmac_f32_e32 v189, v10, v169
	v_fmac_f32_e32 v191, v11, v169
	v_fmac_f32_e32 v193, v12, v169
	v_fmac_f32_e32 v213, v13, v169
	v_fmac_f32_e32 v224, v14, v169
	v_fmac_f32_e32 v225, v15, v169
	v_fmac_f32_e32 v177, v16, v162
	v_fmac_f32_e32 v187, v17, v162
	v_fmac_f32_e32 v189, v18, v162
	v_fmac_f32_e32 v191, v19, v162
	v_fmac_f32_e32 v193, v20, v162
	v_fmac_f32_e32 v213, v21, v162
	v_fmac_f32_e32 v224, v22, v162
	v_fmac_f32_e32 v225, v23, v162
	v_fmac_f32_e32 v177, v24, v163
	v_fmac_f32_e32 v187, v25, v163
	v_fmac_f32_e32 v189, v26, v163
	v_fmac_f32_e32 v191, v27, v163
	v_fmac_f32_e32 v193, v28, v163
	v_fmac_f32_e32 v213, v29, v163
	v_fmac_f32_e32 v224, v30, v163
	v_fmac_f32_e32 v225, v31, v163
	s_waitcnt lgkmcnt(1)
; DI uint2 pk4(f32x4 v) { return make_uint2(pk2(v[0], v[1]), pk2(v[2], v[3])); }
; DI void phase1(const Params& p, unsigned char* smem) {
;     ...
;             for (int i = 0; i < 4; ++i) {
;                 int c = i * 256 + lane * 4;
;                 float4 sh = *(const float4*)(mb + c), sc = *(const float4*)(mb + 1024 + c);
;                 f32x4 o;
;                 o[0] = (vv[rr][4 * i] - mean) * rstd * (1.f + sc.x) + sh.x;
;                 o[1] = (vv[rr][4 * i + 1] - mean) * rstd * (1.f + sc.y) + sh.y;
;                 o[2] = (vv[rr][4 * i + 2] - mean) * rstd * (1.f + sc.z) + sh.z;
;                 o[3] = (vv[rr][4 * i + 3] - mean) * rstd * (1.f + sc.w) + sh.w;
;                 *(uint2*)(h1 + (size_t)row * 1024 + c) = pk4(o);
; #pragma unroll
;                 for (int e = 0; e < 4; ++e) {
;                     const float4 w0 = gw0[i * 4 + e], w1 = gw1[i * 4 + e];
;                     ga[0] += o[e] * w0.x; ga[1] += o[e] * w0.y; ga[2] += o[e] * w0.z; ga[3] += o[e] * w0.w;
;                     ga[4] += o[e] * w1.x; ga[5] += o[e] * w1.y; ga[6] += o[e] * w1.z; ga[7] += o[e] * w1.w;
;                 }
;             }
; #pragma unroll
;             for (int j = 0; j < 8; ++j) ga[j] = wsum(ga[j]);
	v_pk_add_f32 v[170:171], v[170:171], 1.0 op_sel_hi:[1,0]
	v_pk_add_f32 v[172:173], v[172:173], 1.0 op_sel_hi:[1,0]
	s_waitcnt lgkmcnt(0)
	v_pk_fma_f32 v[174:175], v[174:175], v[170:171], v[214:215]
	v_pk_fma_f32 v[218:219], v[218:219], v[172:173], v[216:217]
	v_cvt_pk_bf16_f32 v170, v174, v175
	v_cvt_pk_bf16_f32 v171, v218, v219
	global_store_dwordx2 v[160:161], v[170:171], off offset:512
	ds_read_b128 v[170:173], v237 offset:7168
	s_nop 0
	ds_read_b128 v[214:217], v237 offset:3072
	v_fmac_f32_e32 v177, v32, v174
	v_fmac_f32_e32 v187, v33, v174
	v_fmac_f32_e32 v189, v34, v174
	v_fmac_f32_e32 v191, v35, v174
	v_fmac_f32_e32 v193, v36, v174
	v_fmac_f32_e32 v213, v37, v174
	v_fmac_f32_e32 v224, v38, v174
	v_fmac_f32_e32 v225, v39, v174
	v_fmac_f32_e32 v177, v40, v175
	v_fmac_f32_e32 v187, v41, v175
	v_fmac_f32_e32 v189, v42, v175
	v_fmac_f32_e32 v191, v43, v175
	v_fmac_f32_e32 v193, v44, v175
	v_fmac_f32_e32 v213, v45, v175
	v_fmac_f32_e32 v224, v46, v175
	v_fmac_f32_e32 v225, v47, v175
	v_fmac_f32_e32 v177, v48, v218
	v_fmac_f32_e32 v187, v49, v218
	v_fmac_f32_e32 v189, v50, v218
	v_fmac_f32_e32 v191, v51, v218
	v_fmac_f32_e32 v193, v52, v218
	v_fmac_f32_e32 v213, v53, v218
	v_fmac_f32_e32 v224, v54, v218
	v_fmac_f32_e32 v225, v55, v218
	v_fmac_f32_e32 v177, v56, v219
	v_fmac_f32_e32 v187, v57, v219
	v_fmac_f32_e32 v189, v58, v219
	v_fmac_f32_e32 v191, v59, v219
	v_fmac_f32_e32 v193, v60, v219
	v_fmac_f32_e32 v213, v61, v219
	v_fmac_f32_e32 v224, v62, v219
	v_fmac_f32_e32 v225, v63, v219
	s_waitcnt lgkmcnt(1)
	v_pk_add_f32 v[164:165], v[170:171], 1.0 op_sel_hi:[1,0]
	v_pk_add_f32 v[166:167], v[172:173], 1.0 op_sel_hi:[1,0]
	s_waitcnt lgkmcnt(0)
	v_pk_fma_f32 v[172:173], v[220:221], v[164:165], v[214:215]
	v_pk_fma_f32 v[214:215], v[226:227], v[166:167], v[216:217]
	v_cvt_pk_bf16_f32 v164, v172, v173
	v_cvt_pk_bf16_f32 v165, v214, v215
	global_store_dwordx2 v[160:161], v[164:165], off offset:1024
	ds_read_b128 v[164:167], v237 offset:4096
	s_nop 0
	ds_read_b128 v[168:171], v237 offset:8192
	v_fmac_f32_e32 v177, v64, v172
	v_fmac_f32_e32 v187, v65, v172
	v_fmac_f32_e32 v189, v66, v172
	v_fmac_f32_e32 v191, v67, v172
	v_fmac_f32_e32 v193, v68, v172
	v_fmac_f32_e32 v213, v69, v172
	v_fmac_f32_e32 v224, v70, v172
	v_fmac_f32_e32 v225, v71, v172
	v_fmac_f32_e32 v177, v72, v173
	v_fmac_f32_e32 v187, v73, v173
	v_fmac_f32_e32 v189, v74, v173
	v_fmac_f32_e32 v191, v75, v173
	v_fmac_f32_e32 v193, v76, v173
	v_fmac_f32_e32 v213, v77, v173
	v_fmac_f32_e32 v224, v78, v173
	v_fmac_f32_e32 v225, v79, v173
	v_fmac_f32_e32 v177, v80, v214
	v_fmac_f32_e32 v187, v81, v214
	v_fmac_f32_e32 v189, v82, v214
	v_fmac_f32_e32 v191, v83, v214
	v_fmac_f32_e32 v193, v84, v214
	v_fmac_f32_e32 v213, v85, v214
	v_fmac_f32_e32 v224, v86, v214
	v_fmac_f32_e32 v225, v87, v214
	v_fmac_f32_e32 v177, v88, v215
	v_fmac_f32_e32 v187, v89, v215
	v_fmac_f32_e32 v189, v90, v215
	v_fmac_f32_e32 v191, v91, v215
	v_fmac_f32_e32 v193, v92, v215
	v_fmac_f32_e32 v213, v93, v215
	v_fmac_f32_e32 v224, v94, v215
	v_fmac_f32_e32 v225, v95, v215
	s_waitcnt lgkmcnt(0)
	v_pk_add_f32 v[162:163], v[168:169], 1.0 op_sel_hi:[1,0]
	s_nop 0
	v_pk_fma_f32 v[162:163], v[228:229], v[162:163], v[164:165]
	v_pk_add_f32 v[168:169], v[170:171], 1.0 op_sel_hi:[1,0]
	v_fmac_f32_e32 v177, v96, v162
	v_fmac_f32_e32 v187, v97, v162
	v_fmac_f32_e32 v189, v98, v162
	v_fmac_f32_e32 v191, v99, v162
	v_fmac_f32_e32 v193, v100, v162
	v_fmac_f32_e32 v213, v101, v162
	v_fmac_f32_e32 v224, v102, v162
	v_fmac_f32_e32 v225, v103, v162
	v_pk_fma_f32 v[164:165], v[222:223], v[168:169], v[166:167]
	v_fmac_f32_e32 v177, v104, v163
	v_fmac_f32_e32 v187, v105, v163
	v_fmac_f32_e32 v189, v106, v163
	v_fmac_f32_e32 v191, v107, v163
	v_fmac_f32_e32 v193, v108, v163
	v_fmac_f32_e32 v213, v109, v163
	v_fmac_f32_e32 v224, v110, v163
	v_fmac_f32_e32 v225, v111, v163
	v_fmac_f32_e32 v177, v112, v164
	v_fmac_f32_e32 v187, v113, v164
	v_fmac_f32_e32 v189, v114, v164
	v_fmac_f32_e32 v191, v115, v164
	v_fmac_f32_e32 v193, v116, v164
	v_fmac_f32_e32 v213, v117, v164
	v_fmac_f32_e32 v224, v118, v164
	v_fmac_f32_e32 v225, v119, v164
	v_cvt_pk_bf16_f32 v166, v162, v163
	v_cvt_pk_bf16_f32 v167, v164, v165
	v_fmac_f32_e32 v177, v120, v165
	v_fmac_f32_e32 v187, v121, v165
	v_fmac_f32_e32 v189, v122, v165
	v_fmac_f32_e32 v191, v123, v165
	v_fmac_f32_e32 v193, v124, v165
	v_fmac_f32_e32 v213, v125, v165
	v_fmac_f32_e32 v224, v126, v165
	v_fmac_f32_e32 v225, v127, v165
	global_store_dwordx2 v[160:161], v[166:167], off offset:1536
	v_add_f32_dpp v160, v177, v177 quad_perm:[1,0,3,2] row_mask:0xf bank_mask:0xf bound_ctrl:1
	v_add_f32_dpp v161, v187, v187 quad_perm:[1,0,3,2] row_mask:0xf bank_mask:0xf bound_ctrl:1
	v_add_f32_dpp v162, v189, v189 quad_perm:[1,0,3,2] row_mask:0xf bank_mask:0xf bound_ctrl:1
	v_add_f32_dpp v163, v191, v191 quad_perm:[1,0,3,2] row_mask:0xf bank_mask:0xf bound_ctrl:1
	v_add_f32_dpp v164, v193, v193 quad_perm:[1,0,3,2] row_mask:0xf bank_mask:0xf bound_ctrl:1
	v_add_f32_dpp v165, v213, v213 quad_perm:[1,0,3,2] row_mask:0xf bank_mask:0xf bound_ctrl:1
	v_add_f32_dpp v166, v224, v224 quad_perm:[1,0,3,2] row_mask:0xf bank_mask:0xf bound_ctrl:1
	v_add_f32_dpp v167, v225, v225 quad_perm:[1,0,3,2] row_mask:0xf bank_mask:0xf bound_ctrl:1
	v_add_f32_dpp v160, v160, v160 quad_perm:[2,3,0,1] row_mask:0xf bank_mask:0xf bound_ctrl:1
	v_add_f32_dpp v161, v161, v161 quad_perm:[2,3,0,1] row_mask:0xf bank_mask:0xf bound_ctrl:1
	v_add_f32_dpp v162, v162, v162 quad_perm:[2,3,0,1] row_mask:0xf bank_mask:0xf bound_ctrl:1
	v_add_f32_dpp v163, v163, v163 quad_perm:[2,3,0,1] row_mask:0xf bank_mask:0xf bound_ctrl:1
; DI float logsig(float x) { return (x < 0.f) ? (x - log1pf(__expf(x))) : (-log1pf(__expf(-x))); }
; DI float wsum(float v) {
;     v += dpp_f(v, 0); v += dpp_f(v, 1); v += dpp_f(v, 2); v += dpp_f(v, 3);
;     const int x = __builtin_bit_cast(int, v);
;     return __builtin_bit_cast(float, __builtin_amdgcn_readlane(x, 0)) + __builtin_bit_cast(float, __builtin_amdgcn_readlane(x, 16))
;          + __builtin_bit_cast(float, __builtin_amdgcn_readlane(x, 32)) + __builtin_bit_cast(float, __builtin_amdgcn_readlane(x, 48));
; DI void phase1(const Params& p, unsigned char* smem) {
;     ...
;             for (int j = 0; j < 8; ++j) ga[j] = wsum(ga[j]);
;             if (lane < 8) {
;                 float val = ga[0];
; #pragma unroll
;                 for (int j = 1; j < 8; ++j) val = (lane == j) ? ga[j] : val;
;                 val += p.in[5][2048 + lane];
;                 const int b = row >> 13, sidx = row & 8191;
;                 if (lane < 4) ig[(size_t)(b * 4 + lane) * 8192 + sidx] = val;
;                 else lf[(size_t)(b * 4 + lane - 4) * 8192 + sidx] = logsig(val);
	v_add_f32_dpp v164, v164, v164 quad_perm:[2,3,0,1] row_mask:0xf bank_mask:0xf bound_ctrl:1
	v_add_f32_dpp v165, v165, v165 quad_perm:[2,3,0,1] row_mask:0xf bank_mask:0xf bound_ctrl:1
	v_add_f32_dpp v166, v166, v166 quad_perm:[2,3,0,1] row_mask:0xf bank_mask:0xf bound_ctrl:1
	v_add_f32_dpp v167, v167, v167 quad_perm:[2,3,0,1] row_mask:0xf bank_mask:0xf bound_ctrl:1
	v_add_f32_dpp v160, v160, v160 row_half_mirror row_mask:0xf bank_mask:0xf bound_ctrl:1
	v_add_f32_dpp v161, v161, v161 row_half_mirror row_mask:0xf bank_mask:0xf bound_ctrl:1
	v_add_f32_dpp v162, v162, v162 row_half_mirror row_mask:0xf bank_mask:0xf bound_ctrl:1
	v_add_f32_dpp v163, v163, v163 row_half_mirror row_mask:0xf bank_mask:0xf bound_ctrl:1
	v_add_f32_dpp v164, v164, v164 row_half_mirror row_mask:0xf bank_mask:0xf bound_ctrl:1
	v_add_f32_dpp v165, v165, v165 row_half_mirror row_mask:0xf bank_mask:0xf bound_ctrl:1
	v_add_f32_dpp v166, v166, v166 row_half_mirror row_mask:0xf bank_mask:0xf bound_ctrl:1
	v_add_f32_dpp v167, v167, v167 row_half_mirror row_mask:0xf bank_mask:0xf bound_ctrl:1
	v_add_f32_dpp v160, v160, v160 row_mirror row_mask:0xf bank_mask:0xf bound_ctrl:1
	v_add_f32_dpp v161, v161, v161 row_mirror row_mask:0xf bank_mask:0xf bound_ctrl:1
	v_add_f32_dpp v162, v162, v162 row_mirror row_mask:0xf bank_mask:0xf bound_ctrl:1
	v_add_f32_dpp v163, v163, v163 row_mirror row_mask:0xf bank_mask:0xf bound_ctrl:1
	v_add_f32_dpp v164, v164, v164 row_mirror row_mask:0xf bank_mask:0xf bound_ctrl:1
	v_add_f32_dpp v165, v165, v165 row_mirror row_mask:0xf bank_mask:0xf bound_ctrl:1
	v_add_f32_dpp v166, v166, v166 row_mirror row_mask:0xf bank_mask:0xf bound_ctrl:1
	v_add_f32_dpp v167, v167, v167 row_mirror row_mask:0xf bank_mask:0xf bound_ctrl:1
	v_readlane_b32 s16, v160, 0
	v_readlane_b32 s31, v160, 16
	v_readlane_b32 s17, v160, 32
	v_readlane_b32 s30, v160, 48
	v_readlane_b32 s34, v161, 0
	v_readlane_b32 s42, v161, 16
	v_readlane_b32 s35, v161, 32
	v_readlane_b32 s41, v161, 48
	v_readlane_b32 s43, v162, 0
	v_readlane_b32 s46, v162, 16
	v_readlane_b32 s44, v162, 32
	v_readlane_b32 s45, v162, 48
	v_readlane_b32 s47, v163, 0
	v_readlane_b32 s50, v163, 16
	v_readlane_b32 s48, v163, 32
	v_readlane_b32 s49, v163, 48
	v_readlane_b32 s51, v164, 0
	v_readlane_b32 s55, v164, 16
	v_readlane_b32 s52, v164, 32
	v_readlane_b32 s53, v164, 48
	v_readlane_b32 s56, v165, 0
	v_readlane_b32 s73, v165, 16
	v_readlane_b32 s57, v165, 32
	v_readlane_b32 s72, v165, 48
	v_readlane_b32 s74, v166, 0
	v_readlane_b32 s83, v166, 16
	v_readlane_b32 s75, v166, 32
	v_readlane_b32 s82, v166, 48
	v_readlane_b32 s84, v167, 0
	v_readlane_b32 s87, v167, 16
	v_readlane_b32 s85, v167, 32
	v_readlane_b32 s86, v167, 48
	s_and_saveexec_b64 s[28:29], vcc
	s_cbranch_execz .LBB0_205
	v_mov_b32_e32 v166, s42
	v_mov_b32_e32 v167, s31
	v_mov_b32_e32 v165, s46
	v_add_f32_e32 v166, s34, v166
	v_add_f32_e32 v167, s16, v167
	v_mov_b32_e32 v164, s50
	v_add_f32_e32 v165, s43, v165
	v_add_f32_e32 v166, s35, v166
	v_add_f32_e32 v167, s17, v167
	v_mov_b32_e32 v163, s55
	v_add_f32_e32 v164, s47, v164
	v_add_f32_e32 v165, s44, v165
	v_add_f32_e32 v166, s41, v166
	v_add_f32_e32 v167, s30, v167
	v_mov_b32_e32 v162, s73
	v_add_f32_e32 v163, s51, v163
	v_add_f32_e32 v164, s48, v164
	v_add_f32_e32 v165, s45, v165
	v_cndmask_b32_e64 v166, v167, v166, s[0:1]
	v_mov_b32_e32 v161, s83
	v_add_f32_e32 v162, s56, v162
	v_add_f32_e32 v163, s52, v163
	v_add_f32_e32 v164, s49, v164
	v_cndmask_b32_e64 v165, v166, v165, s[14:15]
	v_mov_b32_e32 v160, s87
	v_add_f32_e32 v161, s74, v161
	v_add_f32_e32 v162, s57, v162
	v_add_f32_e32 v163, s53, v163
	v_cndmask_b32_e64 v164, v165, v164, s[4:5]
	v_add_f32_e32 v160, s84, v160
	v_add_f32_e32 v161, s75, v161
	v_add_f32_e32 v162, s72, v162
	v_cndmask_b32_e64 v163, v164, v163, s[6:7]
	v_add_f32_e32 v160, s85, v160
	v_add_f32_e32 v161, s82, v161
	v_cndmask_b32_e64 v162, v163, v162, s[8:9]
	v_add_f32_e32 v160, s86, v160
	v_cndmask_b32_e64 v161, v162, v161, s[10:11]
	v_cndmask_b32_e64 v160, v161, v160, s[12:13]
	v_mov_b32_e32 v161, v251
	v_add_f32_e32 v162, v160, v161
	v_mov_b64_e32 v[160:161], v[210:211]
	s_and_saveexec_b64 s[30:31], s[24:25]
	s_cbranch_execz .LBB0_204
	v_cmp_ngt_f32_e64 s[16:17], 0, v162
	s_and_saveexec_b64 s[34:35], s[16:17]
	s_xor_b64 s[34:35], exec, s[34:35]
	s_cbranch_execz .LBB0_201
; DI float logsig(float x) { return (x < 0.f) ? (x - log1pf(__expf(x))) : (-log1pf(__expf(-x))); }
	v_mul_f32_e32 v160, 0xbfb8aa3b, v162
	v_exp_f32_e32 v174, v160
	s_nop 0
	v_add_f32_e32 v162, 1.0, v174
	v_frexp_mant_f32_e32 v164, v162
	v_cvt_f64_f32_e32 v[160:161], v162
	v_frexp_exp_i32_f64_e32 v160, v[160:161]
	v_cmp_gt_f32_e64 s[16:17], s37, v164
	v_add_f32_e32 v163, -1.0, v162
	v_sub_f32_e32 v165, v163, v162
	v_subbrev_co_u32_e64 v168, s[16:17], 0, v160, s[16:17]
	v_sub_u32_e32 v160, 0, v168
	v_sub_f32_e32 v163, v174, v163
	v_add_f32_e32 v165, 1.0, v165
	v_ldexp_f32 v161, v162, v160
	v_add_f32_e32 v163, v163, v165
	v_add_f32_e32 v162, -1.0, v161
	v_add_f32_e32 v164, 1.0, v161
	v_ldexp_f32 v160, v163, v160
	v_add_f32_e32 v163, 1.0, v162
	v_add_f32_e32 v165, -1.0, v164
	v_sub_f32_e32 v163, v161, v163
	v_sub_f32_e32 v161, v161, v165
	v_add_f32_e32 v163, v160, v163
	v_add_f32_e32 v160, v160, v161
	v_add_f32_e32 v169, v164, v160
	v_rcp_f32_e32 v171, v169
	v_sub_f32_e32 v161, v169, v164
	v_sub_f32_e32 v170, v160, v161
	v_add_f32_e32 v161, v162, v163
	v_mul_f32_e32 v173, v161, v171
	v_sub_f32_e32 v160, v161, v162
	v_mul_f32_e32 v162, v169, v173
	v_fma_f32 v164, v173, v169, -v162
	v_fmac_f32_e32 v164, v173, v170
	v_sub_f32_e32 v172, v163, v160
	v_add_f32_e32 v160, v162, v164
	v_sub_f32_e32 v163, v161, v160
	v_pk_add_f32 v[166:167], v[160:161], v[162:163] neg_lo:[0,1] neg_hi:[0,1]
	v_mov_b32_e32 v165, v160
	v_pk_add_f32 v[160:161], v[166:167], v[164:165] neg_lo:[0,1] neg_hi:[0,1]
	v_cmp_neq_f32_e64 s[16:17], s39, v174
	v_add_f32_e32 v161, v172, v161
	v_add_f32_e32 v160, v160, v161
	v_add_f32_e32 v161, v163, v160
	v_mul_f32_e32 v172, v171, v161
	v_mul_f32_e32 v162, v169, v172
	v_fma_f32 v164, v172, v169, -v162
	v_fmac_f32_e32 v164, v172, v170
	v_sub_f32_e32 v163, v163, v161
	v_add_f32_e32 v169, v160, v163
	v_add_f32_e32 v160, v162, v164
	v_sub_f32_e32 v163, v161, v160
	v_pk_add_f32 v[166:167], v[160:161], v[162:163] neg_lo:[0,1] neg_hi:[0,1]
	v_mov_b32_e32 v165, v160
	v_pk_add_f32 v[160:161], v[166:167], v[164:165] neg_lo:[0,1] neg_hi:[0,1]
	s_nop 0
	v_add_f32_e32 v161, v169, v161
	v_add_f32_e32 v160, v160, v161
	v_add_f32_e32 v161, v173, v172
	v_add_f32_e32 v160, v163, v160
	v_sub_f32_e32 v162, v161, v173
	v_mul_f32_e32 v160, v171, v160
	v_sub_f32_e32 v162, v172, v162
	v_add_f32_e32 v162, v162, v160
	v_add_f32_e32 v164, v161, v162
	v_mul_f32_e32 v165, v164, v164
	v_fmamk_f32 v160, v165, 0x3e9b6dac, v233
	v_fmaak_f32 v193, v165, v160, 0x3f2aaada
	v_cvt_f32_i32_e32 v160, v168
	v_sub_f32_e32 v161, v164, v161
	v_sub_f32_e32 v161, v162, v161
	v_ldexp_f32 v166, v161, 1
	v_mul_f32_e32 v161, v164, v165
	v_ldexp_f32 v163, v164, 1
	v_pk_mul_f32 v[164:165], v[160:161], v[192:193]
	s_nop 0
	v_fma_f32 v162, v160, s38, -v164
	v_fmac_f32_e32 v162, 0xb102e308, v160
	v_pk_add_f32 v[160:161], v[164:165], v[162:163]
	s_nop 0
	v_sub_f32_e32 v163, v161, v163
	v_sub_f32_e32 v163, v165, v163
	v_add_f32_e32 v167, v166, v163
	v_mov_b32_e32 v166, v164
	v_pk_add_f32 v[164:165], v[160:161], v[164:165] neg_lo:[0,1] neg_hi:[0,1]
	v_pk_add_f32 v[168:169], v[160:161], v[166:167]
	v_mov_b32_e32 v163, v160
	v_mov_b32_e32 v165, v169
	v_pk_add_f32 v[170:171], v[162:163], v[164:165] neg_lo:[0,1] neg_hi:[0,1]
	v_pk_add_f32 v[162:163], v[162:163], v[164:165]
	v_mov_b32_e32 v166, v167
	v_pk_add_f32 v[164:165], v[162:163], v[160:161] op_sel:[1,0] op_sel_hi:[0,1] neg_lo:[0,1] neg_hi:[0,1]
	v_pk_add_f32 v[172:173], v[168:169], v[164:165] op_sel_hi:[1,0] neg_lo:[0,1] neg_hi:[0,1]
	v_mov_b32_e32 v168, v169
	v_mov_b32_e32 v169, v163
	v_pk_mov_b32 v[164:165], v[160:161], v[164:165] op_sel:[1,0]
	v_mov_b32_e32 v167, v160
	v_pk_add_f32 v[164:165], v[168:169], v[164:165] neg_lo:[0,1] neg_hi:[0,1]
	v_mov_b32_e32 v172, v170
	v_pk_add_f32 v[160:161], v[166:167], v[164:165] neg_lo:[0,1] neg_hi:[0,1]
	v_mov_b32_e32 v171, v163
	v_pk_add_f32 v[164:165], v[172:173], v[160:161]
	s_nop 0
	v_pk_add_f32 v[166:167], v[164:165], v[164:165] op_sel:[0,1] op_sel_hi:[1,0]
	s_nop 0
	v_pk_add_f32 v[162:163], v[162:163], v[166:167] op_sel:[1,0] op_sel_hi:[0,1]
	v_mov_b32_e32 v165, v162
	v_pk_add_f32 v[168:169], v[164:165], v[170:171] neg_lo:[0,1] neg_hi:[0,1]
	v_mov_b32_e32 v161, v166
	v_sub_f32_e32 v163, v164, v168
	v_pk_add_f32 v[160:161], v[160:161], v[168:169] neg_lo:[0,1] neg_hi:[0,1]
	v_sub_f32_e32 v163, v170, v163
	v_add_f32_e32 v160, v160, v163
	v_add_f32_e32 v160, v160, v161
	v_add_f32_e32 v160, v162, v160
	v_cndmask_b32_e64 v160, v234, v160, s[16:17]
	v_cmp_ngt_f32_e64 s[16:17], -1.0, v174
	s_nop 1
	v_cndmask_b32_e64 v160, v235, v160, s[16:17]
	v_cmp_neq_f32_e64 s[16:17], -1.0, v174
	s_nop 1
	v_cndmask_b32_e64 v160, v236, v160, s[16:17]
	v_cmp_lt_f32_e64 s[16:17], |v174|, s40
	s_nop 1
	v_cndmask_b32_e64 v160, v160, v174, s[16:17]
	v_xor_b32_e32 v162, 0x80000000, v160

; DI uint2 pk4(f32x4 v) { return make_uint2(pk2(v[0], v[1]), pk2(v[2], v[3])); }
; DI void row_stats(const float (&v)[16], float& mean, float& rstd) {
;     float s = 0.f;
; #pragma unroll
;     for (int i = 0; i < 16; ++i) s += v[i];
;     mean = wsum(s) * (1.f / 1024.f);
;     float q = 0.f;
; #pragma unroll
;     for (int i = 0; i < 16; ++i) { float d = v[i] - mean; q += d * d; }
;     rstd = rsqrtf(wsum(q) * (1.f / 1024.f) + 1e-5f);
; DI void phase1(const Params& p, unsigned char* smem) {
;     ...
;         for (int rr = 0; rr < 4; ++rr) {
;             const int row = row0 + rr;
;             float mean, rstd; row_stats(vv[rr], mean, rstd);
;             const float* mb = mod + (row >> 13) * 6144;
;             float ga[8];
; #pragma unroll
;             for (int j = 0; j < 8; ++j) ga[j] = 0.f;
; #pragma unroll
;             for (int i = 0; i < 4; ++i) {
;                 int c = i * 256 + lane * 4;
;                 float4 sh = *(const float4*)(mb + c), sc = *(const float4*)(mb + 1024 + c);
;                 f32x4 o;
;                 o[0] = (vv[rr][4 * i] - mean) * rstd * (1.f + sc.x) + sh.x;
;                 o[1] = (vv[rr][4 * i + 1] - mean) * rstd * (1.f + sc.y) + sh.y;
;                 o[2] = (vv[rr][4 * i + 2] - mean) * rstd * (1.f + sc.z) + sh.z;
;                 o[3] = (vv[rr][4 * i + 3] - mean) * rstd * (1.f + sc.w) + sh.w;
;                 *(uint2*)(h1 + (size_t)row * 1024 + c) = pk4(o);
.LBB0_205:
	s_or_b64 exec, exec, s[28:29]
	ds_read_b128 v[160:163], v237 offset:5120
	ds_read_b128 v[164:167], v237 offset:1024
	v_add_f32_e32 v170, 0, v156
	v_add_f32_e32 v170, v170, v157
	v_add_f32_e32 v170, v170, v158
	v_add_f32_e32 v170, v170, v159
	v_add_f32_e32 v170, v170, v152
	v_add_f32_e32 v170, v170, v153
	v_add_f32_e32 v170, v170, v154
	v_add_f32_e32 v170, v170, v155
	v_add_f32_e32 v170, v170, v148
	v_add_f32_e32 v170, v170, v149
	v_add_f32_e32 v170, v170, v150
	v_add_f32_e32 v170, v170, v151
	v_add_f32_e32 v170, v170, v144
	v_add_f32_e32 v170, v170, v145
	v_add_f32_e32 v170, v170, v146
	v_add_f32_e32 v170, v170, v147
	v_lshlrev_b64 v[168:169], 11, v[202:203]
	s_nop 0
	v_add_f32_dpp v170, v170, v170 quad_perm:[1,0,3,2] row_mask:0xf bank_mask:0xf bound_ctrl:1
	s_nop 1
	v_add_f32_dpp v170, v170, v170 quad_perm:[2,3,0,1] row_mask:0xf bank_mask:0xf bound_ctrl:1
	s_nop 1
	v_add_f32_dpp v170, v170, v170 row_half_mirror row_mask:0xf bank_mask:0xf bound_ctrl:1
	s_nop 1
	v_add_f32_dpp v170, v170, v170 row_mirror row_mask:0xf bank_mask:0xf bound_ctrl:1
	s_nop 0
	v_readlane_b32 s17, v170, 16
	v_readlane_b32 s16, v170, 0
	v_readlane_b32 s18, v170, 32
	v_readlane_b32 s19, v170, 48
	v_mov_b32_e32 v170, s17
	v_add_f32_e32 v170, s16, v170
	v_add_f32_e32 v170, s18, v170
	v_add_f32_e32 v170, s19, v170
	v_mul_f32_e32 v170, 0x3a800000, v170
	v_pk_add_f32 v[156:157], v[156:157], v[170:171] op_sel_hi:[1,0] neg_lo:[0,1] neg_hi:[0,1]
	v_pk_add_f32 v[158:159], v[158:159], v[170:171] op_sel_hi:[1,0] neg_lo:[0,1] neg_hi:[0,1]
	v_pk_add_f32 v[214:215], v[148:149], v[170:171] op_sel_hi:[1,0] neg_lo:[0,1] neg_hi:[0,1]
	v_pk_add_f32 v[148:149], v[146:147], v[170:171] op_sel_hi:[1,0] neg_lo:[0,1] neg_hi:[0,1]
	v_pk_mul_f32 v[146:147], v[156:157], v[156:157]
	v_pk_add_f32 v[212:213], v[150:151], v[170:171] op_sel_hi:[1,0] neg_lo:[0,1] neg_hi:[0,1]
	v_pk_add_f32 v[150:151], v[144:145], v[170:171] op_sel_hi:[1,0] neg_lo:[0,1] neg_hi:[0,1]
	v_pk_mul_f32 v[144:145], v[158:159], v[158:159]
	v_add_f32_e32 v146, v146, v147
	v_pk_add_f32 v[174:175], v[152:153], v[170:171] op_sel_hi:[1,0] neg_lo:[0,1] neg_hi:[0,1]
	v_add_f32_e32 v144, v144, v146
	v_pk_add_f32 v[172:173], v[154:155], v[170:171] op_sel_hi:[1,0] neg_lo:[0,1] neg_hi:[0,1]
	v_pk_mul_f32 v[154:155], v[174:175], v[174:175]
	v_add_f32_e32 v144, v145, v144
	v_add_f32_e32 v144, v154, v144
	v_pk_mul_f32 v[152:153], v[172:173], v[172:173]
	v_add_f32_e32 v144, v155, v144
	v_add_f32_e32 v144, v152, v144
	v_pk_mul_f32 v[216:217], v[214:215], v[214:215]
	v_add_f32_e32 v144, v153, v144
	v_add_f32_e32 v144, v216, v144
	v_pk_mul_f32 v[170:171], v[212:213], v[212:213]
	v_add_f32_e32 v144, v217, v144
	v_add_f32_e32 v144, v170, v144
	v_pk_mul_f32 v[220:221], v[150:151], v[150:151]
	v_add_f32_e32 v144, v171, v144
	v_add_f32_e32 v144, v220, v144
	v_pk_mul_f32 v[218:219], v[148:149], v[148:149]
	v_add_f32_e32 v144, v221, v144
	v_add_f32_e32 v144, v218, v144
	v_add_f32_e32 v144, v219, v144
	s_waitcnt lgkmcnt(1)
	v_pk_add_f32 v[154:155], v[162:163], 1.0 op_sel_hi:[1,0]
	v_add_f32_dpp v144, v144, v144 quad_perm:[1,0,3,2] row_mask:0xf bank_mask:0xf bound_ctrl:1
	v_pk_add_f32 v[146:147], v[160:161], 1.0 op_sel_hi:[1,0]
	s_nop 0
	v_add_f32_dpp v144, v144, v144 quad_perm:[2,3,0,1] row_mask:0xf bank_mask:0xf bound_ctrl:1
	s_nop 1
	v_add_f32_dpp v144, v144, v144 row_half_mirror row_mask:0xf bank_mask:0xf bound_ctrl:1
	s_nop 1
	v_add_f32_dpp v144, v144, v144 row_mirror row_mask:0xf bank_mask:0xf bound_ctrl:1
	s_nop 0
	v_readlane_b32 s17, v144, 16
	v_readlane_b32 s16, v144, 0
	v_readlane_b32 s18, v144, 32
	v_readlane_b32 s19, v144, 48
	v_mov_b32_e32 v144, s17
	v_add_f32_e32 v144, s16, v144
	v_add_f32_e32 v144, s18, v144
	v_add_f32_e32 v144, s19, v144
	v_fmamk_f32 v144, v144, 0x3a800000, v232
	v_mul_f32_e32 v145, 0x4b800000, v144
	v_cmp_gt_f32_e64 s[16:17], s36, v144
	s_nop 1
	v_cndmask_b32_e64 v144, v144, v145, s[16:17]
	v_rsq_f32_e32 v152, v144
	v_lshl_add_u64 v[144:145], v[184:185], 0, v[168:169]
	v_mul_f32_e32 v153, 0x45800000, v152
	v_cndmask_b32_e64 v162, v152, v153, s[16:17]
	v_pk_mul_f32 v[152:153], v[156:157], v[162:163] op_sel_hi:[1,0]
	v_pk_mul_f32 v[168:169], v[214:215], v[162:163] op_sel_hi:[1,0]
	s_waitcnt lgkmcnt(0)
	v_pk_fma_f32 v[152:153], v[146:147], v[152:153], v[164:165]
	v_pk_mul_f32 v[146:147], v[158:159], v[162:163] op_sel_hi:[1,0]
	v_pk_mul_f32 v[164:165], v[174:175], v[162:163] op_sel_hi:[1,0]
	v_pk_fma_f32 v[146:147], v[154:155], v[146:147], v[166:167]
	v_cvt_pk_bf16_f32 v154, v152, v153
	v_cvt_pk_bf16_f32 v155, v146, v147
	global_store_dwordx2 v[144:145], v[154:155], off
	ds_read_b128 v[154:157], v237 offset:6144
	s_nop 0
	ds_read_b128 v[158:161], v237 offset:2048
	v_pk_mul_f32 v[166:167], v[172:173], v[162:163] op_sel_hi:[1,0]
	v_pk_mul_f32 v[170:171], v[212:213], v[162:163] op_sel_hi:[1,0]
	v_pk_mul_f32 v[172:173], v[150:151], v[162:163] op_sel_hi:[1,0]
	v_pk_mul_f32 v[162:163], v[148:149], v[162:163] op_sel_hi:[1,0]
	v_fma_f32 v174, v0, v152, 0
	v_fma_f32 v175, v1, v152, 0
	v_fma_f32 v177, v2, v152, 0
	v_fma_f32 v187, v3, v152, 0
	v_fma_f32 v189, v4, v152, 0
	v_fma_f32 v191, v5, v152, 0
	v_fma_f32 v193, v6, v152, 0
	v_fma_f32 v203, v7, v152, 0
	v_fmac_f32_e32 v174, v8, v153
	v_fmac_f32_e32 v175, v9, v153
	v_fmac_f32_e32 v177, v10, v153
	v_fmac_f32_e32 v187, v11, v153
	v_fmac_f32_e32 v189, v12, v153
	v_fmac_f32_e32 v191, v13, v153
	v_fmac_f32_e32 v193, v14, v153
	v_fmac_f32_e32 v203, v15, v153
	v_fmac_f32_e32 v174, v16, v146
	v_fmac_f32_e32 v175, v17, v146
	v_fmac_f32_e32 v177, v18, v146
	v_fmac_f32_e32 v187, v19, v146
	v_fmac_f32_e32 v189, v20, v146
	v_fmac_f32_e32 v191, v21, v146
	v_fmac_f32_e32 v193, v22, v146
	v_fmac_f32_e32 v203, v23, v146
	v_fmac_f32_e32 v174, v24, v147
	v_fmac_f32_e32 v175, v25, v147
	v_fmac_f32_e32 v177, v26, v147
	v_fmac_f32_e32 v187, v27, v147
	v_fmac_f32_e32 v189, v28, v147
	v_fmac_f32_e32 v191, v29, v147
	v_fmac_f32_e32 v193, v30, v147
	v_fmac_f32_e32 v203, v31, v147
	s_waitcnt lgkmcnt(1)
; DI uint2 pk4(f32x4 v) { return make_uint2(pk2(v[0], v[1]), pk2(v[2], v[3])); }
; DI void phase1(const Params& p, unsigned char* smem) {
;     ...
;             for (int i = 0; i < 4; ++i) {
;                 int c = i * 256 + lane * 4;
;                 float4 sh = *(const float4*)(mb + c), sc = *(const float4*)(mb + 1024 + c);
;                 f32x4 o;
;                 o[0] = (vv[rr][4 * i] - mean) * rstd * (1.f + sc.x) + sh.x;
;                 o[1] = (vv[rr][4 * i + 1] - mean) * rstd * (1.f + sc.y) + sh.y;
;                 o[2] = (vv[rr][4 * i + 2] - mean) * rstd * (1.f + sc.z) + sh.z;
;                 o[3] = (vv[rr][4 * i + 3] - mean) * rstd * (1.f + sc.w) + sh.w;
;                 *(uint2*)(h1 + (size_t)row * 1024 + c) = pk4(o);
; #pragma unroll
;                 for (int e = 0; e < 4; ++e) {
;                     const float4 w0 = gw0[i * 4 + e], w1 = gw1[i * 4 + e];
;                     ga[0] += o[e] * w0.x; ga[1] += o[e] * w0.y; ga[2] += o[e] * w0.z; ga[3] += o[e] * w0.w;
;                     ga[4] += o[e] * w1.x; ga[5] += o[e] * w1.y; ga[6] += o[e] * w1.z; ga[7] += o[e] * w1.w;
;                 }
;             }
; #pragma unroll
;             for (int j = 0; j < 8; ++j) ga[j] = wsum(ga[j]);
	v_pk_add_f32 v[154:155], v[154:155], 1.0 op_sel_hi:[1,0]
	v_pk_add_f32 v[156:157], v[156:157], 1.0 op_sel_hi:[1,0]
	s_waitcnt lgkmcnt(0)
	v_pk_fma_f32 v[164:165], v[164:165], v[154:155], v[158:159]
	v_pk_fma_f32 v[166:167], v[166:167], v[156:157], v[160:161]
	v_cvt_pk_bf16_f32 v154, v164, v165
	v_cvt_pk_bf16_f32 v155, v166, v167
	global_store_dwordx2 v[144:145], v[154:155], off offset:512
	ds_read_b128 v[154:157], v237 offset:7168
	s_nop 0
	ds_read_b128 v[158:161], v237 offset:3072
	v_fmac_f32_e32 v174, v32, v164
	v_fmac_f32_e32 v175, v33, v164
	v_fmac_f32_e32 v177, v34, v164
	v_fmac_f32_e32 v187, v35, v164
	v_fmac_f32_e32 v189, v36, v164
	v_fmac_f32_e32 v191, v37, v164
	v_fmac_f32_e32 v193, v38, v164
	v_fmac_f32_e32 v203, v39, v164
	v_fmac_f32_e32 v174, v40, v165
	v_fmac_f32_e32 v175, v41, v165
	v_fmac_f32_e32 v177, v42, v165
	v_fmac_f32_e32 v187, v43, v165
	v_fmac_f32_e32 v189, v44, v165
	v_fmac_f32_e32 v191, v45, v165
	v_fmac_f32_e32 v193, v46, v165
	v_fmac_f32_e32 v203, v47, v165
	v_fmac_f32_e32 v174, v48, v166
	v_fmac_f32_e32 v175, v49, v166
	v_fmac_f32_e32 v177, v50, v166
	v_fmac_f32_e32 v187, v51, v166
	v_fmac_f32_e32 v189, v52, v166
	v_fmac_f32_e32 v191, v53, v166
	v_fmac_f32_e32 v193, v54, v166
	v_fmac_f32_e32 v203, v55, v166
	v_fmac_f32_e32 v174, v56, v167
	v_fmac_f32_e32 v175, v57, v167
	v_fmac_f32_e32 v177, v58, v167
	v_fmac_f32_e32 v187, v59, v167
	v_fmac_f32_e32 v189, v60, v167
	v_fmac_f32_e32 v191, v61, v167
	v_fmac_f32_e32 v193, v62, v167
	v_fmac_f32_e32 v203, v63, v167
	s_waitcnt lgkmcnt(1)
	v_pk_add_f32 v[148:149], v[154:155], 1.0 op_sel_hi:[1,0]
	v_pk_add_f32 v[150:151], v[156:157], 1.0 op_sel_hi:[1,0]
	s_waitcnt lgkmcnt(0)
	v_pk_fma_f32 v[156:157], v[168:169], v[148:149], v[158:159]
	v_pk_fma_f32 v[158:159], v[170:171], v[150:151], v[160:161]
	v_cvt_pk_bf16_f32 v148, v156, v157
	v_cvt_pk_bf16_f32 v149, v158, v159
	global_store_dwordx2 v[144:145], v[148:149], off offset:1024
	ds_read_b128 v[148:151], v237 offset:4096
	s_nop 0
	ds_read_b128 v[152:155], v237 offset:8192
	v_fmac_f32_e32 v174, v64, v156
	v_fmac_f32_e32 v175, v65, v156
	v_fmac_f32_e32 v177, v66, v156
	v_fmac_f32_e32 v187, v67, v156
	v_fmac_f32_e32 v189, v68, v156
	v_fmac_f32_e32 v191, v69, v156
	v_fmac_f32_e32 v193, v70, v156
	v_fmac_f32_e32 v203, v71, v156
	v_fmac_f32_e32 v174, v72, v157
	v_fmac_f32_e32 v175, v73, v157
	v_fmac_f32_e32 v177, v74, v157
	v_fmac_f32_e32 v187, v75, v157
	v_fmac_f32_e32 v189, v76, v157
	v_fmac_f32_e32 v191, v77, v157
	v_fmac_f32_e32 v193, v78, v157
	v_fmac_f32_e32 v203, v79, v157
	v_fmac_f32_e32 v174, v80, v158
	v_fmac_f32_e32 v175, v81, v158
	v_fmac_f32_e32 v177, v82, v158
	v_fmac_f32_e32 v187, v83, v158
	v_fmac_f32_e32 v189, v84, v158
	v_fmac_f32_e32 v191, v85, v158
	v_fmac_f32_e32 v193, v86, v158
	v_fmac_f32_e32 v203, v87, v158
	v_fmac_f32_e32 v174, v88, v159
	v_fmac_f32_e32 v175, v89, v159
	v_fmac_f32_e32 v177, v90, v159
	v_fmac_f32_e32 v187, v91, v159
	v_fmac_f32_e32 v189, v92, v159
	v_fmac_f32_e32 v191, v93, v159
	v_fmac_f32_e32 v193, v94, v159
	v_fmac_f32_e32 v203, v95, v159
	s_waitcnt lgkmcnt(0)
	v_pk_add_f32 v[146:147], v[152:153], 1.0 op_sel_hi:[1,0]
	s_nop 0
	v_pk_fma_f32 v[146:147], v[172:173], v[146:147], v[148:149]
	v_pk_add_f32 v[152:153], v[154:155], 1.0 op_sel_hi:[1,0]
	v_fmac_f32_e32 v174, v96, v146
	v_fmac_f32_e32 v175, v97, v146
	v_fmac_f32_e32 v177, v98, v146
	v_fmac_f32_e32 v187, v99, v146
	v_fmac_f32_e32 v189, v100, v146
	v_fmac_f32_e32 v191, v101, v146
	v_fmac_f32_e32 v193, v102, v146
	v_fmac_f32_e32 v203, v103, v146
	v_pk_fma_f32 v[148:149], v[162:163], v[152:153], v[150:151]
	v_fmac_f32_e32 v174, v104, v147
	v_fmac_f32_e32 v175, v105, v147
	v_fmac_f32_e32 v177, v106, v147
	v_fmac_f32_e32 v187, v107, v147
	v_fmac_f32_e32 v189, v108, v147
	v_fmac_f32_e32 v191, v109, v147
	v_fmac_f32_e32 v193, v110, v147
	v_fmac_f32_e32 v203, v111, v147
	v_fmac_f32_e32 v174, v112, v148
	v_fmac_f32_e32 v175, v113, v148
	v_fmac_f32_e32 v177, v114, v148
	v_fmac_f32_e32 v187, v115, v148
	v_fmac_f32_e32 v189, v116, v148
	v_fmac_f32_e32 v191, v117, v148
	v_fmac_f32_e32 v193, v118, v148
	v_fmac_f32_e32 v203, v119, v148
	v_cvt_pk_bf16_f32 v150, v146, v147
	v_cvt_pk_bf16_f32 v151, v148, v149
	v_fmac_f32_e32 v174, v120, v149
	v_fmac_f32_e32 v175, v121, v149
	v_fmac_f32_e32 v177, v122, v149
	v_fmac_f32_e32 v187, v123, v149
	v_fmac_f32_e32 v189, v124, v149
	v_fmac_f32_e32 v191, v125, v149
	v_fmac_f32_e32 v193, v126, v149
	v_fmac_f32_e32 v203, v127, v149
	global_store_dwordx2 v[144:145], v[150:151], off offset:1536
	v_add_f32_dpp v144, v174, v174 quad_perm:[1,0,3,2] row_mask:0xf bank_mask:0xf bound_ctrl:1
	v_add_f32_dpp v145, v175, v175 quad_perm:[1,0,3,2] row_mask:0xf bank_mask:0xf bound_ctrl:1
	v_add_f32_dpp v146, v177, v177 quad_perm:[1,0,3,2] row_mask:0xf bank_mask:0xf bound_ctrl:1
	v_add_f32_dpp v147, v187, v187 quad_perm:[1,0,3,2] row_mask:0xf bank_mask:0xf bound_ctrl:1
	v_add_f32_dpp v148, v189, v189 quad_perm:[1,0,3,2] row_mask:0xf bank_mask:0xf bound_ctrl:1
	v_add_f32_dpp v149, v191, v191 quad_perm:[1,0,3,2] row_mask:0xf bank_mask:0xf bound_ctrl:1
	v_add_f32_dpp v150, v193, v193 quad_perm:[1,0,3,2] row_mask:0xf bank_mask:0xf bound_ctrl:1
	v_add_f32_dpp v151, v203, v203 quad_perm:[1,0,3,2] row_mask:0xf bank_mask:0xf bound_ctrl:1
	v_add_f32_dpp v144, v144, v144 quad_perm:[2,3,0,1] row_mask:0xf bank_mask:0xf bound_ctrl:1
	v_add_f32_dpp v145, v145, v145 quad_perm:[2,3,0,1] row_mask:0xf bank_mask:0xf bound_ctrl:1
	v_add_f32_dpp v146, v146, v146 quad_perm:[2,3,0,1] row_mask:0xf bank_mask:0xf bound_ctrl:1
	v_add_f32_dpp v147, v147, v147 quad_perm:[2,3,0,1] row_mask:0xf bank_mask:0xf bound_ctrl:1
; DI float logsig(float x) { return (x < 0.f) ? (x - log1pf(__expf(x))) : (-log1pf(__expf(-x))); }
; DI float wsum(float v) {
;     v += dpp_f(v, 0); v += dpp_f(v, 1); v += dpp_f(v, 2); v += dpp_f(v, 3);
;     const int x = __builtin_bit_cast(int, v);
;     return __builtin_bit_cast(float, __builtin_amdgcn_readlane(x, 0)) + __builtin_bit_cast(float, __builtin_amdgcn_readlane(x, 16))
;          + __builtin_bit_cast(float, __builtin_amdgcn_readlane(x, 32)) + __builtin_bit_cast(float, __builtin_amdgcn_readlane(x, 48));
; DI void phase1(const Params& p, unsigned char* smem) {
;     ...
;             for (int j = 0; j < 8; ++j) ga[j] = wsum(ga[j]);
;             if (lane < 8) {
;                 float val = ga[0];
; #pragma unroll
;                 for (int j = 1; j < 8; ++j) val = (lane == j) ? ga[j] : val;
;                 val += p.in[5][2048 + lane];
;                 const int b = row >> 13, sidx = row & 8191;
;                 if (lane < 4) ig[(size_t)(b * 4 + lane) * 8192 + sidx] = val;
;                 else lf[(size_t)(b * 4 + lane - 4) * 8192 + sidx] = logsig(val);
	v_add_f32_dpp v148, v148, v148 quad_perm:[2,3,0,1] row_mask:0xf bank_mask:0xf bound_ctrl:1
	v_add_f32_dpp v149, v149, v149 quad_perm:[2,3,0,1] row_mask:0xf bank_mask:0xf bound_ctrl:1
	v_add_f32_dpp v150, v150, v150 quad_perm:[2,3,0,1] row_mask:0xf bank_mask:0xf bound_ctrl:1
	v_add_f32_dpp v151, v151, v151 quad_perm:[2,3,0,1] row_mask:0xf bank_mask:0xf bound_ctrl:1
	v_add_f32_dpp v144, v144, v144 row_half_mirror row_mask:0xf bank_mask:0xf bound_ctrl:1
	v_add_f32_dpp v145, v145, v145 row_half_mirror row_mask:0xf bank_mask:0xf bound_ctrl:1
	v_add_f32_dpp v146, v146, v146 row_half_mirror row_mask:0xf bank_mask:0xf bound_ctrl:1
	v_add_f32_dpp v147, v147, v147 row_half_mirror row_mask:0xf bank_mask:0xf bound_ctrl:1
	v_add_f32_dpp v148, v148, v148 row_half_mirror row_mask:0xf bank_mask:0xf bound_ctrl:1
	v_add_f32_dpp v149, v149, v149 row_half_mirror row_mask:0xf bank_mask:0xf bound_ctrl:1
	v_add_f32_dpp v150, v150, v150 row_half_mirror row_mask:0xf bank_mask:0xf bound_ctrl:1
	v_add_f32_dpp v151, v151, v151 row_half_mirror row_mask:0xf bank_mask:0xf bound_ctrl:1
	v_add_f32_dpp v144, v144, v144 row_mirror row_mask:0xf bank_mask:0xf bound_ctrl:1
	v_add_f32_dpp v145, v145, v145 row_mirror row_mask:0xf bank_mask:0xf bound_ctrl:1
	v_add_f32_dpp v146, v146, v146 row_mirror row_mask:0xf bank_mask:0xf bound_ctrl:1
	v_add_f32_dpp v147, v147, v147 row_mirror row_mask:0xf bank_mask:0xf bound_ctrl:1
	v_add_f32_dpp v148, v148, v148 row_mirror row_mask:0xf bank_mask:0xf bound_ctrl:1
	v_add_f32_dpp v149, v149, v149 row_mirror row_mask:0xf bank_mask:0xf bound_ctrl:1
	v_add_f32_dpp v150, v150, v150 row_mirror row_mask:0xf bank_mask:0xf bound_ctrl:1
	v_add_f32_dpp v151, v151, v151 row_mirror row_mask:0xf bank_mask:0xf bound_ctrl:1
	v_readlane_b32 s16, v144, 0
	v_readlane_b32 s31, v144, 16
	v_readlane_b32 s17, v144, 32
	v_readlane_b32 s30, v144, 48
	v_readlane_b32 s34, v145, 0
	v_readlane_b32 s42, v145, 16
	v_readlane_b32 s35, v145, 32
	v_readlane_b32 s41, v145, 48
	v_readlane_b32 s43, v146, 0
	v_readlane_b32 s46, v146, 16
	v_readlane_b32 s44, v146, 32
	v_readlane_b32 s45, v146, 48
	v_readlane_b32 s47, v147, 0
	v_readlane_b32 s50, v147, 16
	v_readlane_b32 s48, v147, 32
	v_readlane_b32 s49, v147, 48
	v_readlane_b32 s51, v148, 0
	v_readlane_b32 s55, v148, 16
	v_readlane_b32 s52, v148, 32
	v_readlane_b32 s53, v148, 48
	v_readlane_b32 s56, v149, 0
	v_readlane_b32 s73, v149, 16
	v_readlane_b32 s57, v149, 32
	v_readlane_b32 s72, v149, 48
	v_readlane_b32 s74, v150, 0
	v_readlane_b32 s83, v150, 16
	v_readlane_b32 s75, v150, 32
	v_readlane_b32 s82, v150, 48
	v_readlane_b32 s84, v151, 0
	v_readlane_b32 s87, v151, 16
	v_readlane_b32 s85, v151, 32
	v_readlane_b32 s86, v151, 48
	s_and_saveexec_b64 s[28:29], vcc
	s_cbranch_execz .LBB0_213
	v_mov_b32_e32 v150, s42
	v_mov_b32_e32 v151, s31
	v_mov_b32_e32 v149, s46
	v_add_f32_e32 v150, s34, v150
	v_add_f32_e32 v151, s16, v151
	v_mov_b32_e32 v148, s50
	v_add_f32_e32 v149, s43, v149
	v_add_f32_e32 v150, s35, v150
	v_add_f32_e32 v151, s17, v151
	v_mov_b32_e32 v147, s55
	v_add_f32_e32 v148, s47, v148
	v_add_f32_e32 v149, s44, v149
	v_add_f32_e32 v150, s41, v150
	v_add_f32_e32 v151, s30, v151
	v_mov_b32_e32 v146, s73
	v_add_f32_e32 v147, s51, v147
	v_add_f32_e32 v148, s48, v148
	v_add_f32_e32 v149, s45, v149
	v_cndmask_b32_e64 v150, v151, v150, s[0:1]
	v_mov_b32_e32 v145, s83
	v_add_f32_e32 v146, s56, v146
	v_add_f32_e32 v147, s52, v147
	v_add_f32_e32 v148, s49, v148
	v_cndmask_b32_e64 v149, v150, v149, s[14:15]
	v_mov_b32_e32 v144, s87
	v_add_f32_e32 v145, s74, v145
	v_add_f32_e32 v146, s57, v146
	v_add_f32_e32 v147, s53, v147
	v_cndmask_b32_e64 v148, v149, v148, s[4:5]
	v_add_f32_e32 v144, s84, v144
	v_add_f32_e32 v145, s75, v145
	v_add_f32_e32 v146, s72, v146
	v_cndmask_b32_e64 v147, v148, v147, s[6:7]
	v_add_f32_e32 v144, s85, v144
	v_add_f32_e32 v145, s82, v145
	v_cndmask_b32_e64 v146, v147, v146, s[8:9]
	v_add_f32_e32 v144, s86, v144
	v_cndmask_b32_e64 v145, v146, v145, s[10:11]
	v_cndmask_b32_e64 v144, v145, v144, s[12:13]
	v_mov_b32_e32 v145, v251
	v_add_f32_e32 v146, v144, v145
	v_mov_b64_e32 v[144:145], v[210:211]
	s_and_saveexec_b64 s[30:31], s[24:25]
	s_cbranch_execz .LBB0_212
	v_cmp_ngt_f32_e64 s[16:17], 0, v146
	s_and_saveexec_b64 s[34:35], s[16:17]
	s_xor_b64 s[34:35], exec, s[34:35]
	s_cbranch_execz .LBB0_209
; DI float logsig(float x) { return (x < 0.f) ? (x - log1pf(__expf(x))) : (-log1pf(__expf(-x))); }
	v_mul_f32_e32 v144, 0xbfb8aa3b, v146
	v_exp_f32_e32 v158, v144
	s_nop 0
	v_add_f32_e32 v146, 1.0, v158
	v_frexp_mant_f32_e32 v148, v146
	v_cvt_f64_f32_e32 v[144:145], v146
	v_frexp_exp_i32_f64_e32 v144, v[144:145]
	v_cmp_gt_f32_e64 s[16:17], s37, v148
	v_add_f32_e32 v147, -1.0, v146
	v_sub_f32_e32 v149, v147, v146
	v_subbrev_co_u32_e64 v152, s[16:17], 0, v144, s[16:17]
	v_sub_u32_e32 v144, 0, v152
	v_sub_f32_e32 v147, v158, v147
	v_add_f32_e32 v149, 1.0, v149
	v_ldexp_f32 v145, v146, v144
	v_add_f32_e32 v147, v147, v149
	v_add_f32_e32 v146, -1.0, v145
	v_add_f32_e32 v148, 1.0, v145
	v_ldexp_f32 v144, v147, v144
	v_add_f32_e32 v147, 1.0, v146
	v_add_f32_e32 v149, -1.0, v148
	v_sub_f32_e32 v147, v145, v147
	v_sub_f32_e32 v145, v145, v149
	v_add_f32_e32 v147, v144, v147
	v_add_f32_e32 v144, v144, v145
	v_add_f32_e32 v153, v148, v144
	v_rcp_f32_e32 v155, v153
	v_sub_f32_e32 v145, v153, v148
	v_sub_f32_e32 v154, v144, v145
	v_add_f32_e32 v145, v146, v147
	v_mul_f32_e32 v157, v145, v155
	v_sub_f32_e32 v144, v145, v146
	v_mul_f32_e32 v146, v153, v157
	v_fma_f32 v148, v157, v153, -v146
	v_fmac_f32_e32 v148, v157, v154
	v_sub_f32_e32 v156, v147, v144
	v_add_f32_e32 v144, v146, v148
	v_sub_f32_e32 v147, v145, v144
	v_pk_add_f32 v[150:151], v[144:145], v[146:147] neg_lo:[0,1] neg_hi:[0,1]
	v_mov_b32_e32 v149, v144
	v_pk_add_f32 v[144:145], v[150:151], v[148:149] neg_lo:[0,1] neg_hi:[0,1]
	v_cmp_neq_f32_e64 s[16:17], s39, v158
	v_add_f32_e32 v145, v156, v145
	v_add_f32_e32 v144, v144, v145
	v_add_f32_e32 v145, v147, v144
	v_mul_f32_e32 v156, v155, v145
	v_mul_f32_e32 v146, v153, v156
	v_fma_f32 v148, v156, v153, -v146
	v_fmac_f32_e32 v148, v156, v154
	v_sub_f32_e32 v147, v147, v145
	v_add_f32_e32 v153, v144, v147
	v_add_f32_e32 v144, v146, v148
	v_sub_f32_e32 v147, v145, v144
	v_pk_add_f32 v[150:151], v[144:145], v[146:147] neg_lo:[0,1] neg_hi:[0,1]
	v_mov_b32_e32 v149, v144
	v_pk_add_f32 v[144:145], v[150:151], v[148:149] neg_lo:[0,1] neg_hi:[0,1]
	s_nop 0
	v_add_f32_e32 v145, v153, v145
	v_add_f32_e32 v144, v144, v145
	v_add_f32_e32 v145, v157, v156
	v_add_f32_e32 v144, v147, v144
	v_sub_f32_e32 v146, v145, v157
	v_mul_f32_e32 v144, v155, v144
	v_sub_f32_e32 v146, v156, v146
	v_add_f32_e32 v146, v146, v144
	v_add_f32_e32 v148, v145, v146
	v_mul_f32_e32 v149, v148, v148
	v_fmamk_f32 v144, v149, 0x3e9b6dac, v233
	v_fmaak_f32 v193, v149, v144, 0x3f2aaada
	v_cvt_f32_i32_e32 v144, v152
	v_sub_f32_e32 v145, v148, v145
	v_sub_f32_e32 v145, v146, v145
	v_ldexp_f32 v150, v145, 1
	v_mul_f32_e32 v145, v148, v149
	v_ldexp_f32 v147, v148, 1
	v_pk_mul_f32 v[148:149], v[144:145], v[192:193]
	s_nop 0
	v_fma_f32 v146, v144, s38, -v148
	v_fmac_f32_e32 v146, 0xb102e308, v144
	v_pk_add_f32 v[144:145], v[148:149], v[146:147]
	s_nop 0
	v_sub_f32_e32 v147, v145, v147
	v_sub_f32_e32 v147, v149, v147
	v_add_f32_e32 v151, v150, v147
	v_mov_b32_e32 v150, v148
	v_pk_add_f32 v[148:149], v[144:145], v[148:149] neg_lo:[0,1] neg_hi:[0,1]
	v_pk_add_f32 v[152:153], v[144:145], v[150:151]
	v_mov_b32_e32 v147, v144
	v_mov_b32_e32 v149, v153
	v_pk_add_f32 v[154:155], v[146:147], v[148:149] neg_lo:[0,1] neg_hi:[0,1]
	v_pk_add_f32 v[146:147], v[146:147], v[148:149]
	v_mov_b32_e32 v150, v151
	v_pk_add_f32 v[148:149], v[146:147], v[144:145] op_sel:[1,0] op_sel_hi:[0,1] neg_lo:[0,1] neg_hi:[0,1]
	v_pk_add_f32 v[156:157], v[152:153], v[148:149] op_sel_hi:[1,0] neg_lo:[0,1] neg_hi:[0,1]
	v_mov_b32_e32 v152, v153
	v_mov_b32_e32 v153, v147
	v_pk_mov_b32 v[148:149], v[144:145], v[148:149] op_sel:[1,0]
	v_mov_b32_e32 v151, v144
	v_pk_add_f32 v[148:149], v[152:153], v[148:149] neg_lo:[0,1] neg_hi:[0,1]
	v_mov_b32_e32 v156, v154
	v_pk_add_f32 v[144:145], v[150:151], v[148:149] neg_lo:[0,1] neg_hi:[0,1]
	v_mov_b32_e32 v155, v147
	v_pk_add_f32 v[148:149], v[156:157], v[144:145]
	s_nop 0
	v_pk_add_f32 v[150:151], v[148:149], v[148:149] op_sel:[0,1] op_sel_hi:[1,0]
	s_nop 0
	v_pk_add_f32 v[146:147], v[146:147], v[150:151] op_sel:[1,0] op_sel_hi:[0,1]
	v_mov_b32_e32 v149, v146
	v_pk_add_f32 v[152:153], v[148:149], v[154:155] neg_lo:[0,1] neg_hi:[0,1]
	v_mov_b32_e32 v145, v150
	v_sub_f32_e32 v147, v148, v152
	v_pk_add_f32 v[144:145], v[144:145], v[152:153] neg_lo:[0,1] neg_hi:[0,1]
	v_sub_f32_e32 v147, v154, v147
	v_add_f32_e32 v144, v144, v147
	v_add_f32_e32 v144, v144, v145
	v_add_f32_e32 v144, v146, v144
	v_cndmask_b32_e64 v144, v234, v144, s[16:17]
	v_cmp_ngt_f32_e64 s[16:17], -1.0, v158
	s_nop 1
	v_cndmask_b32_e64 v144, v235, v144, s[16:17]
	v_cmp_neq_f32_e64 s[16:17], -1.0, v158
	s_nop 1
	v_cndmask_b32_e64 v144, v236, v144, s[16:17]
	v_cmp_lt_f32_e64 s[16:17], |v158|, s40
	s_nop 1
	v_cndmask_b32_e64 v144, v144, v158, s[16:17]
	v_xor_b32_e32 v146, 0x80000000, v144

; DI uint2 pk4(f32x4 v) { return make_uint2(pk2(v[0], v[1]), pk2(v[2], v[3])); }
; DI void row_stats(const float (&v)[16], float& mean, float& rstd) {
;     float s = 0.f;
; #pragma unroll
;     for (int i = 0; i < 16; ++i) s += v[i];
;     mean = wsum(s) * (1.f / 1024.f);
;     float q = 0.f;
; #pragma unroll
;     for (int i = 0; i < 16; ++i) { float d = v[i] - mean; q += d * d; }
;     rstd = rsqrtf(wsum(q) * (1.f / 1024.f) + 1e-5f);
; DI void phase1(const Params& p, unsigned char* smem) {
;     ...
;         for (int rr = 0; rr < 4; ++rr) {
;             const int row = row0 + rr;
;             float mean, rstd; row_stats(vv[rr], mean, rstd);
;             const float* mb = mod + (row >> 13) * 6144;
;             float ga[8];
; #pragma unroll
;             for (int j = 0; j < 8; ++j) ga[j] = 0.f;
; #pragma unroll
;             for (int i = 0; i < 4; ++i) {
;                 int c = i * 256 + lane * 4;
;                 float4 sh = *(const float4*)(mb + c), sc = *(const float4*)(mb + 1024 + c);
;                 f32x4 o;
;                 o[0] = (vv[rr][4 * i] - mean) * rstd * (1.f + sc.x) + sh.x;
;                 o[1] = (vv[rr][4 * i + 1] - mean) * rstd * (1.f + sc.y) + sh.y;
;                 o[2] = (vv[rr][4 * i + 2] - mean) * rstd * (1.f + sc.z) + sh.z;
;                 o[3] = (vv[rr][4 * i + 3] - mean) * rstd * (1.f + sc.w) + sh.w;
;                 *(uint2*)(h1 + (size_t)row * 1024 + c) = pk4(o);
.LBB0_213:
	s_or_b64 exec, exec, s[28:29]
	ds_read_b128 v[144:147], v237 offset:5120
	ds_read_b128 v[148:151], v237 offset:1024
	v_add_f32_e32 v154, 0, v140
	v_add_f32_e32 v154, v154, v141
	v_add_f32_e32 v154, v154, v142
	v_add_f32_e32 v154, v154, v143
	v_add_f32_e32 v154, v154, v136
	v_add_f32_e32 v154, v154, v137
	v_add_f32_e32 v154, v154, v138
	v_add_f32_e32 v154, v154, v139
	v_add_f32_e32 v154, v154, v132
	v_add_f32_e32 v154, v154, v133
	v_add_f32_e32 v154, v154, v134
	v_add_f32_e32 v154, v154, v135
	v_add_f32_e32 v154, v154, v128
	v_add_f32_e32 v154, v154, v129
	v_add_f32_e32 v154, v154, v130
	v_add_f32_e32 v154, v154, v131
	v_lshlrev_b64 v[152:153], 11, v[194:195]
	s_nop 0
	v_add_f32_dpp v154, v154, v154 quad_perm:[1,0,3,2] row_mask:0xf bank_mask:0xf bound_ctrl:1
	s_nop 1
	v_add_f32_dpp v154, v154, v154 quad_perm:[2,3,0,1] row_mask:0xf bank_mask:0xf bound_ctrl:1
	s_nop 1
	v_add_f32_dpp v154, v154, v154 row_half_mirror row_mask:0xf bank_mask:0xf bound_ctrl:1
	s_nop 1
	v_add_f32_dpp v154, v154, v154 row_mirror row_mask:0xf bank_mask:0xf bound_ctrl:1
	s_nop 0
	v_readlane_b32 s17, v154, 16
	v_readlane_b32 s16, v154, 0
	v_readlane_b32 s18, v154, 32
	v_readlane_b32 s19, v154, 48
	v_mov_b32_e32 v154, s17
	v_add_f32_e32 v154, s16, v154
	v_add_f32_e32 v154, s18, v154
	v_add_f32_e32 v154, s19, v154
	v_mul_f32_e32 v154, 0x3a800000, v154
	v_pk_add_f32 v[140:141], v[140:141], v[154:155] op_sel_hi:[1,0] neg_lo:[0,1] neg_hi:[0,1]
	v_pk_add_f32 v[142:143], v[142:143], v[154:155] op_sel_hi:[1,0] neg_lo:[0,1] neg_hi:[0,1]
	v_pk_add_f32 v[162:163], v[132:133], v[154:155] op_sel_hi:[1,0] neg_lo:[0,1] neg_hi:[0,1]
	v_pk_add_f32 v[132:133], v[130:131], v[154:155] op_sel_hi:[1,0] neg_lo:[0,1] neg_hi:[0,1]
	v_pk_mul_f32 v[130:131], v[140:141], v[140:141]
	v_pk_add_f32 v[160:161], v[134:135], v[154:155] op_sel_hi:[1,0] neg_lo:[0,1] neg_hi:[0,1]
	v_pk_add_f32 v[134:135], v[128:129], v[154:155] op_sel_hi:[1,0] neg_lo:[0,1] neg_hi:[0,1]
	v_pk_mul_f32 v[128:129], v[142:143], v[142:143]
	v_add_f32_e32 v130, v130, v131
	v_pk_add_f32 v[158:159], v[136:137], v[154:155] op_sel_hi:[1,0] neg_lo:[0,1] neg_hi:[0,1]
	v_add_f32_e32 v128, v128, v130
	v_pk_add_f32 v[156:157], v[138:139], v[154:155] op_sel_hi:[1,0] neg_lo:[0,1] neg_hi:[0,1]
	v_pk_mul_f32 v[138:139], v[158:159], v[158:159]
	v_add_f32_e32 v128, v129, v128
	v_add_f32_e32 v128, v138, v128
	v_pk_mul_f32 v[136:137], v[156:157], v[156:157]
	v_add_f32_e32 v128, v139, v128
	v_add_f32_e32 v128, v136, v128
	v_pk_mul_f32 v[164:165], v[162:163], v[162:163]
	v_add_f32_e32 v128, v137, v128
	v_add_f32_e32 v128, v164, v128
	v_pk_mul_f32 v[154:155], v[160:161], v[160:161]
	v_add_f32_e32 v128, v165, v128
	v_add_f32_e32 v128, v154, v128
	v_pk_mul_f32 v[168:169], v[134:135], v[134:135]
	v_add_f32_e32 v128, v155, v128
	v_add_f32_e32 v128, v168, v128
	v_pk_mul_f32 v[166:167], v[132:133], v[132:133]
	v_add_f32_e32 v128, v169, v128
	v_add_f32_e32 v128, v166, v128
	v_add_f32_e32 v128, v167, v128
	s_waitcnt lgkmcnt(1)
	v_pk_add_f32 v[138:139], v[146:147], 1.0 op_sel_hi:[1,0]
	v_add_f32_dpp v128, v128, v128 quad_perm:[1,0,3,2] row_mask:0xf bank_mask:0xf bound_ctrl:1
	v_pk_add_f32 v[130:131], v[144:145], 1.0 op_sel_hi:[1,0]
	s_nop 0
	v_add_f32_dpp v128, v128, v128 quad_perm:[2,3,0,1] row_mask:0xf bank_mask:0xf bound_ctrl:1
	s_nop 1
	v_add_f32_dpp v128, v128, v128 row_half_mirror row_mask:0xf bank_mask:0xf bound_ctrl:1
	s_nop 1
	v_add_f32_dpp v128, v128, v128 row_mirror row_mask:0xf bank_mask:0xf bound_ctrl:1
	s_nop 0
	v_readlane_b32 s17, v128, 16
	v_readlane_b32 s16, v128, 0
	v_readlane_b32 s18, v128, 32
	v_readlane_b32 s19, v128, 48
	v_mov_b32_e32 v128, s17
	v_add_f32_e32 v128, s16, v128
	v_add_f32_e32 v128, s18, v128
	v_add_f32_e32 v128, s19, v128
	v_fmamk_f32 v128, v128, 0x3a800000, v232
	v_mul_f32_e32 v129, 0x4b800000, v128
	v_cmp_gt_f32_e64 s[16:17], s36, v128
	s_nop 1
	v_cndmask_b32_e64 v128, v128, v129, s[16:17]
	v_rsq_f32_e32 v136, v128
	v_lshl_add_u64 v[128:129], v[184:185], 0, v[152:153]
	v_mul_f32_e32 v137, 0x45800000, v136
	v_cndmask_b32_e64 v146, v136, v137, s[16:17]
	v_pk_mul_f32 v[136:137], v[140:141], v[146:147] op_sel_hi:[1,0]
	v_pk_mul_f32 v[152:153], v[162:163], v[146:147] op_sel_hi:[1,0]
	s_waitcnt lgkmcnt(0)
	v_pk_fma_f32 v[136:137], v[130:131], v[136:137], v[148:149]
	v_pk_mul_f32 v[130:131], v[142:143], v[146:147] op_sel_hi:[1,0]
	v_pk_mul_f32 v[148:149], v[158:159], v[146:147] op_sel_hi:[1,0]
	v_pk_fma_f32 v[130:131], v[138:139], v[130:131], v[150:151]
	v_cvt_pk_bf16_f32 v138, v136, v137
	v_cvt_pk_bf16_f32 v139, v130, v131
	global_store_dwordx2 v[128:129], v[138:139], off
	ds_read_b128 v[138:141], v237 offset:6144
	s_nop 0
	ds_read_b128 v[142:145], v237 offset:2048
	v_pk_mul_f32 v[150:151], v[156:157], v[146:147] op_sel_hi:[1,0]
	v_pk_mul_f32 v[154:155], v[160:161], v[146:147] op_sel_hi:[1,0]
	v_pk_mul_f32 v[156:157], v[134:135], v[146:147] op_sel_hi:[1,0]
	v_pk_mul_f32 v[146:147], v[132:133], v[146:147] op_sel_hi:[1,0]
	v_fma_f32 v158, v0, v136, 0
	v_fma_f32 v159, v1, v136, 0
	v_fma_f32 v160, v2, v136, 0
	v_fma_f32 v161, v3, v136, 0
	v_fma_f32 v162, v4, v136, 0
	v_fma_f32 v163, v5, v136, 0
	v_fma_f32 v164, v6, v136, 0
	v_fma_f32 v165, v7, v136, 0
	v_fmac_f32_e32 v158, v8, v137
	v_fmac_f32_e32 v159, v9, v137
	v_fmac_f32_e32 v160, v10, v137
	v_fmac_f32_e32 v161, v11, v137
	v_fmac_f32_e32 v162, v12, v137
	v_fmac_f32_e32 v163, v13, v137
	v_fmac_f32_e32 v164, v14, v137
	v_fmac_f32_e32 v165, v15, v137
	v_fmac_f32_e32 v158, v16, v130
	v_fmac_f32_e32 v159, v17, v130
	v_fmac_f32_e32 v160, v18, v130
	v_fmac_f32_e32 v161, v19, v130
	v_fmac_f32_e32 v162, v20, v130
	v_fmac_f32_e32 v163, v21, v130
	v_fmac_f32_e32 v164, v22, v130
	v_fmac_f32_e32 v165, v23, v130
	v_fmac_f32_e32 v158, v24, v131
	v_fmac_f32_e32 v159, v25, v131
	v_fmac_f32_e32 v160, v26, v131
	v_fmac_f32_e32 v161, v27, v131
	v_fmac_f32_e32 v162, v28, v131
	v_fmac_f32_e32 v163, v29, v131
	v_fmac_f32_e32 v164, v30, v131
	v_fmac_f32_e32 v165, v31, v131
	s_waitcnt lgkmcnt(1)
; DI uint2 pk4(f32x4 v) { return make_uint2(pk2(v[0], v[1]), pk2(v[2], v[3])); }
; DI void phase1(const Params& p, unsigned char* smem) {
;     ...
;             for (int i = 0; i < 4; ++i) {
;                 int c = i * 256 + lane * 4;
;                 float4 sh = *(const float4*)(mb + c), sc = *(const float4*)(mb + 1024 + c);
;                 f32x4 o;
;                 o[0] = (vv[rr][4 * i] - mean) * rstd * (1.f + sc.x) + sh.x;
;                 o[1] = (vv[rr][4 * i + 1] - mean) * rstd * (1.f + sc.y) + sh.y;
;                 o[2] = (vv[rr][4 * i + 2] - mean) * rstd * (1.f + sc.z) + sh.z;
;                 o[3] = (vv[rr][4 * i + 3] - mean) * rstd * (1.f + sc.w) + sh.w;
;                 *(uint2*)(h1 + (size_t)row * 1024 + c) = pk4(o);
; #pragma unroll
;                 for (int e = 0; e < 4; ++e) {
;                     const float4 w0 = gw0[i * 4 + e], w1 = gw1[i * 4 + e];
;                     ga[0] += o[e] * w0.x; ga[1] += o[e] * w0.y; ga[2] += o[e] * w0.z; ga[3] += o[e] * w0.w;
;                     ga[4] += o[e] * w1.x; ga[5] += o[e] * w1.y; ga[6] += o[e] * w1.z; ga[7] += o[e] * w1.w;
;                 }
;             }
; #pragma unroll
;             for (int j = 0; j < 8; ++j) ga[j] = wsum(ga[j]);
	v_pk_add_f32 v[138:139], v[138:139], 1.0 op_sel_hi:[1,0]
	v_pk_add_f32 v[140:141], v[140:141], 1.0 op_sel_hi:[1,0]
	s_waitcnt lgkmcnt(0)
	v_pk_fma_f32 v[148:149], v[148:149], v[138:139], v[142:143]
	v_pk_fma_f32 v[150:151], v[150:151], v[140:141], v[144:145]
	v_cvt_pk_bf16_f32 v138, v148, v149
	v_cvt_pk_bf16_f32 v139, v150, v151
	global_store_dwordx2 v[128:129], v[138:139], off offset:512
	ds_read_b128 v[138:141], v237 offset:7168
	s_nop 0
	ds_read_b128 v[142:145], v237 offset:3072
	v_fmac_f32_e32 v158, v32, v148
	v_fmac_f32_e32 v159, v33, v148
	v_fmac_f32_e32 v160, v34, v148
	v_fmac_f32_e32 v161, v35, v148
	v_fmac_f32_e32 v162, v36, v148
	v_fmac_f32_e32 v163, v37, v148
	v_fmac_f32_e32 v164, v38, v148
	v_fmac_f32_e32 v165, v39, v148
	v_fmac_f32_e32 v158, v40, v149
	v_fmac_f32_e32 v159, v41, v149
	v_fmac_f32_e32 v160, v42, v149
	v_fmac_f32_e32 v161, v43, v149
	v_fmac_f32_e32 v162, v44, v149
	v_fmac_f32_e32 v163, v45, v149
	v_fmac_f32_e32 v164, v46, v149
	v_fmac_f32_e32 v165, v47, v149
	v_fmac_f32_e32 v158, v48, v150
	v_fmac_f32_e32 v159, v49, v150
	v_fmac_f32_e32 v160, v50, v150
	v_fmac_f32_e32 v161, v51, v150
	v_fmac_f32_e32 v162, v52, v150
	v_fmac_f32_e32 v163, v53, v150
	v_fmac_f32_e32 v164, v54, v150
	v_fmac_f32_e32 v165, v55, v150
	v_fmac_f32_e32 v158, v56, v151
	v_fmac_f32_e32 v159, v57, v151
	v_fmac_f32_e32 v160, v58, v151
	v_fmac_f32_e32 v161, v59, v151
	v_fmac_f32_e32 v162, v60, v151
	v_fmac_f32_e32 v163, v61, v151
	v_fmac_f32_e32 v164, v62, v151
	v_fmac_f32_e32 v165, v63, v151
	s_waitcnt lgkmcnt(1)
	v_pk_add_f32 v[132:133], v[138:139], 1.0 op_sel_hi:[1,0]
	v_pk_add_f32 v[134:135], v[140:141], 1.0 op_sel_hi:[1,0]
	s_waitcnt lgkmcnt(0)
	v_pk_fma_f32 v[140:141], v[152:153], v[132:133], v[142:143]
	v_pk_fma_f32 v[142:143], v[154:155], v[134:135], v[144:145]
	v_cvt_pk_bf16_f32 v132, v140, v141
	v_cvt_pk_bf16_f32 v133, v142, v143
	global_store_dwordx2 v[128:129], v[132:133], off offset:1024
	ds_read_b128 v[132:135], v237 offset:4096
	s_nop 0
	ds_read_b128 v[136:139], v237 offset:8192
	v_fmac_f32_e32 v158, v64, v140
	v_fmac_f32_e32 v159, v65, v140
	v_fmac_f32_e32 v160, v66, v140
	v_fmac_f32_e32 v161, v67, v140
	v_fmac_f32_e32 v162, v68, v140
	v_fmac_f32_e32 v163, v69, v140
	v_fmac_f32_e32 v164, v70, v140
	v_fmac_f32_e32 v165, v71, v140
	v_fmac_f32_e32 v158, v72, v141
	v_fmac_f32_e32 v159, v73, v141
	v_fmac_f32_e32 v160, v74, v141
	v_fmac_f32_e32 v161, v75, v141
	v_fmac_f32_e32 v162, v76, v141
	v_fmac_f32_e32 v163, v77, v141
	v_fmac_f32_e32 v164, v78, v141
	v_fmac_f32_e32 v165, v79, v141
	v_fmac_f32_e32 v158, v80, v142
	v_fmac_f32_e32 v159, v81, v142
	v_fmac_f32_e32 v160, v82, v142
	v_fmac_f32_e32 v161, v83, v142
	v_fmac_f32_e32 v162, v84, v142
	v_fmac_f32_e32 v163, v85, v142
	v_fmac_f32_e32 v164, v86, v142
	v_fmac_f32_e32 v165, v87, v142
	v_fmac_f32_e32 v158, v88, v143
	v_fmac_f32_e32 v159, v89, v143
	v_fmac_f32_e32 v160, v90, v143
	v_fmac_f32_e32 v161, v91, v143
	v_fmac_f32_e32 v162, v92, v143
	v_fmac_f32_e32 v163, v93, v143
	v_fmac_f32_e32 v164, v94, v143
	v_fmac_f32_e32 v165, v95, v143
	s_waitcnt lgkmcnt(0)
	v_pk_add_f32 v[130:131], v[136:137], 1.0 op_sel_hi:[1,0]
	s_nop 0
	v_pk_fma_f32 v[130:131], v[156:157], v[130:131], v[132:133]
	v_pk_add_f32 v[136:137], v[138:139], 1.0 op_sel_hi:[1,0]
	v_fmac_f32_e32 v158, v96, v130
	v_fmac_f32_e32 v159, v97, v130
	v_fmac_f32_e32 v160, v98, v130
	v_fmac_f32_e32 v161, v99, v130
	v_fmac_f32_e32 v162, v100, v130
	v_fmac_f32_e32 v163, v101, v130
	v_fmac_f32_e32 v164, v102, v130
	v_fmac_f32_e32 v165, v103, v130
	v_pk_fma_f32 v[132:133], v[146:147], v[136:137], v[134:135]
	v_fmac_f32_e32 v158, v104, v131
	v_fmac_f32_e32 v159, v105, v131
	v_fmac_f32_e32 v160, v106, v131
	v_fmac_f32_e32 v161, v107, v131
	v_fmac_f32_e32 v162, v108, v131
	v_fmac_f32_e32 v163, v109, v131
	v_fmac_f32_e32 v164, v110, v131
	v_fmac_f32_e32 v165, v111, v131
	v_fmac_f32_e32 v158, v112, v132
	v_fmac_f32_e32 v159, v113, v132
	v_fmac_f32_e32 v160, v114, v132
	v_fmac_f32_e32 v161, v115, v132
	v_fmac_f32_e32 v162, v116, v132
	v_fmac_f32_e32 v163, v117, v132
	v_fmac_f32_e32 v164, v118, v132
	v_fmac_f32_e32 v165, v119, v132
	v_cvt_pk_bf16_f32 v134, v130, v131
	v_cvt_pk_bf16_f32 v135, v132, v133
	v_fmac_f32_e32 v158, v120, v133
	v_fmac_f32_e32 v159, v121, v133
	v_fmac_f32_e32 v160, v122, v133
	v_fmac_f32_e32 v161, v123, v133
	v_fmac_f32_e32 v162, v124, v133
	v_fmac_f32_e32 v163, v125, v133
	v_fmac_f32_e32 v164, v126, v133
	v_fmac_f32_e32 v165, v127, v133
	global_store_dwordx2 v[128:129], v[134:135], off offset:1536
	v_add_f32_dpp v128, v158, v158 quad_perm:[1,0,3,2] row_mask:0xf bank_mask:0xf bound_ctrl:1
	v_add_f32_dpp v129, v159, v159 quad_perm:[1,0,3,2] row_mask:0xf bank_mask:0xf bound_ctrl:1
	v_add_f32_dpp v130, v160, v160 quad_perm:[1,0,3,2] row_mask:0xf bank_mask:0xf bound_ctrl:1
	v_add_f32_dpp v131, v161, v161 quad_perm:[1,0,3,2] row_mask:0xf bank_mask:0xf bound_ctrl:1
	v_add_f32_dpp v132, v162, v162 quad_perm:[1,0,3,2] row_mask:0xf bank_mask:0xf bound_ctrl:1
	v_add_f32_dpp v133, v163, v163 quad_perm:[1,0,3,2] row_mask:0xf bank_mask:0xf bound_ctrl:1
	v_add_f32_dpp v134, v164, v164 quad_perm:[1,0,3,2] row_mask:0xf bank_mask:0xf bound_ctrl:1
	v_add_f32_dpp v135, v165, v165 quad_perm:[1,0,3,2] row_mask:0xf bank_mask:0xf bound_ctrl:1
	v_add_f32_dpp v128, v128, v128 quad_perm:[2,3,0,1] row_mask:0xf bank_mask:0xf bound_ctrl:1
	v_add_f32_dpp v129, v129, v129 quad_perm:[2,3,0,1] row_mask:0xf bank_mask:0xf bound_ctrl:1
	v_add_f32_dpp v130, v130, v130 quad_perm:[2,3,0,1] row_mask:0xf bank_mask:0xf bound_ctrl:1
	v_add_f32_dpp v131, v131, v131 quad_perm:[2,3,0,1] row_mask:0xf bank_mask:0xf bound_ctrl:1
; DI float wsum(float v) {
;     v += dpp_f(v, 0); v += dpp_f(v, 1); v += dpp_f(v, 2); v += dpp_f(v, 3);
;     const int x = __builtin_bit_cast(int, v);
;     return __builtin_bit_cast(float, __builtin_amdgcn_readlane(x, 0)) + __builtin_bit_cast(float, __builtin_amdgcn_readlane(x, 16))
;          + __builtin_bit_cast(float, __builtin_amdgcn_readlane(x, 32)) + __builtin_bit_cast(float, __builtin_amdgcn_readlane(x, 48));
; }
; DI void phase1(const Params& p, unsigned char* smem) {
;     ...
;             if (lane < 8) {
;                 float val = ga[0];
; #pragma unroll
;                 for (int j = 1; j < 8; ++j) val = (lane == j) ? ga[j] : val;
;                 val += p.in[5][2048 + lane];
;                 const int b = row >> 13, sidx = row & 8191;
;                 if (lane < 4) ig[(size_t)(b * 4 + lane) * 8192 + sidx] = val;
	v_add_f32_dpp v132, v132, v132 quad_perm:[2,3,0,1] row_mask:0xf bank_mask:0xf bound_ctrl:1
	v_add_f32_dpp v133, v133, v133 quad_perm:[2,3,0,1] row_mask:0xf bank_mask:0xf bound_ctrl:1
	v_add_f32_dpp v134, v134, v134 quad_perm:[2,3,0,1] row_mask:0xf bank_mask:0xf bound_ctrl:1
	v_add_f32_dpp v135, v135, v135 quad_perm:[2,3,0,1] row_mask:0xf bank_mask:0xf bound_ctrl:1
	v_add_f32_dpp v128, v128, v128 row_half_mirror row_mask:0xf bank_mask:0xf bound_ctrl:1
	v_add_f32_dpp v129, v129, v129 row_half_mirror row_mask:0xf bank_mask:0xf bound_ctrl:1
	v_add_f32_dpp v130, v130, v130 row_half_mirror row_mask:0xf bank_mask:0xf bound_ctrl:1
	v_add_f32_dpp v131, v131, v131 row_half_mirror row_mask:0xf bank_mask:0xf bound_ctrl:1
	v_add_f32_dpp v132, v132, v132 row_half_mirror row_mask:0xf bank_mask:0xf bound_ctrl:1
	v_add_f32_dpp v133, v133, v133 row_half_mirror row_mask:0xf bank_mask:0xf bound_ctrl:1
	v_add_f32_dpp v134, v134, v134 row_half_mirror row_mask:0xf bank_mask:0xf bound_ctrl:1
	v_add_f32_dpp v135, v135, v135 row_half_mirror row_mask:0xf bank_mask:0xf bound_ctrl:1
	v_add_f32_dpp v128, v128, v128 row_mirror row_mask:0xf bank_mask:0xf bound_ctrl:1
	v_add_f32_dpp v129, v129, v129 row_mirror row_mask:0xf bank_mask:0xf bound_ctrl:1
	v_add_f32_dpp v130, v130, v130 row_mirror row_mask:0xf bank_mask:0xf bound_ctrl:1
	v_add_f32_dpp v131, v131, v131 row_mirror row_mask:0xf bank_mask:0xf bound_ctrl:1
	v_add_f32_dpp v132, v132, v132 row_mirror row_mask:0xf bank_mask:0xf bound_ctrl:1
	v_add_f32_dpp v133, v133, v133 row_mirror row_mask:0xf bank_mask:0xf bound_ctrl:1
	v_add_f32_dpp v134, v134, v134 row_mirror row_mask:0xf bank_mask:0xf bound_ctrl:1
	v_add_f32_dpp v135, v135, v135 row_mirror row_mask:0xf bank_mask:0xf bound_ctrl:1
	v_readlane_b32 s16, v128, 0
	v_readlane_b32 s31, v128, 16
	v_readlane_b32 s17, v128, 32
	v_readlane_b32 s30, v128, 48
	v_readlane_b32 s34, v129, 0
	v_readlane_b32 s42, v129, 16
	v_readlane_b32 s35, v129, 32
	v_readlane_b32 s41, v129, 48
	v_readlane_b32 s43, v130, 0
	v_readlane_b32 s46, v130, 16
	v_readlane_b32 s44, v130, 32
	v_readlane_b32 s45, v130, 48
	v_readlane_b32 s47, v131, 0
	v_readlane_b32 s50, v131, 16
	v_readlane_b32 s48, v131, 32
	v_readlane_b32 s49, v131, 48
	v_readlane_b32 s51, v132, 0
	v_readlane_b32 s55, v132, 16
	v_readlane_b32 s52, v132, 32
	v_readlane_b32 s53, v132, 48
	v_readlane_b32 s56, v133, 0
	v_readlane_b32 s73, v133, 16
	v_readlane_b32 s57, v133, 32
	v_readlane_b32 s72, v133, 48
	v_readlane_b32 s74, v134, 0
	v_readlane_b32 s83, v134, 16
	v_readlane_b32 s75, v134, 32
	v_readlane_b32 s82, v134, 48
	v_readlane_b32 s84, v135, 0
	v_readlane_b32 s87, v135, 16
	v_readlane_b32 s85, v135, 32
	v_readlane_b32 s86, v135, 48
	s_and_saveexec_b64 s[28:29], vcc
	s_cbranch_execz .LBB0_188
	v_mov_b32_e32 v134, s42
	v_mov_b32_e32 v135, s31
	v_mov_b32_e32 v133, s46
	v_add_f32_e32 v134, s34, v134
	v_add_f32_e32 v135, s16, v135
	v_mov_b32_e32 v132, s50
	v_add_f32_e32 v133, s43, v133
	v_add_f32_e32 v134, s35, v134
	v_add_f32_e32 v135, s17, v135
	v_mov_b32_e32 v131, s55
	v_add_f32_e32 v132, s47, v132
	v_add_f32_e32 v133, s44, v133
	v_add_f32_e32 v134, s41, v134
	v_add_f32_e32 v135, s30, v135
	v_mov_b32_e32 v130, s73
	v_add_f32_e32 v131, s51, v131
	v_add_f32_e32 v132, s48, v132
	v_add_f32_e32 v133, s45, v133
	v_cndmask_b32_e64 v134, v135, v134, s[0:1]
	v_mov_b32_e32 v129, s83
	v_add_f32_e32 v130, s56, v130
	v_add_f32_e32 v131, s52, v131
	v_add_f32_e32 v132, s49, v132
	v_cndmask_b32_e64 v133, v134, v133, s[14:15]
	v_mov_b32_e32 v128, s87
	v_add_f32_e32 v129, s74, v129
	v_add_f32_e32 v130, s57, v130
	v_add_f32_e32 v131, s53, v131
	v_cndmask_b32_e64 v132, v133, v132, s[4:5]
	v_add_f32_e32 v128, s84, v128
	v_add_f32_e32 v129, s75, v129
	v_add_f32_e32 v130, s72, v130
	v_cndmask_b32_e64 v131, v132, v131, s[6:7]
	v_add_f32_e32 v128, s85, v128
	v_add_f32_e32 v129, s82, v129
	v_cndmask_b32_e64 v130, v131, v130, s[8:9]
	v_add_f32_e32 v128, s86, v128
	v_cndmask_b32_e64 v129, v130, v129, s[10:11]
	v_cndmask_b32_e64 v128, v129, v128, s[12:13]
	v_mov_b32_e32 v129, v251
	v_add_f32_e32 v128, v128, v129
	s_and_saveexec_b64 s[30:31], s[24:25]
	s_cbranch_execz .LBB0_187
	v_cmp_ngt_f32_e64 s[16:17], 0, v128
	s_and_saveexec_b64 s[34:35], s[16:17]
	s_xor_b64 s[34:35], exec, s[34:35]
	s_cbranch_execz .LBB0_217
; DI float logsig(float x) { return (x < 0.f) ? (x - log1pf(__expf(x))) : (-log1pf(__expf(-x))); }
	v_mul_f32_e32 v128, 0xbfb8aa3b, v128
	v_exp_f32_e32 v142, v128
	s_nop 0
	v_add_f32_e32 v130, 1.0, v142
	v_frexp_mant_f32_e32 v132, v130
	v_cvt_f64_f32_e32 v[128:129], v130
	v_frexp_exp_i32_f64_e32 v128, v[128:129]
	v_cmp_gt_f32_e64 s[16:17], s37, v132
	v_add_f32_e32 v131, -1.0, v130
	v_sub_f32_e32 v133, v131, v130
	v_subbrev_co_u32_e64 v136, s[16:17], 0, v128, s[16:17]
	v_sub_u32_e32 v128, 0, v136
	v_sub_f32_e32 v131, v142, v131
	v_add_f32_e32 v133, 1.0, v133
	v_ldexp_f32 v129, v130, v128
	v_add_f32_e32 v131, v131, v133
	v_add_f32_e32 v130, -1.0, v129
	v_add_f32_e32 v132, 1.0, v129
	v_ldexp_f32 v128, v131, v128
	v_add_f32_e32 v131, 1.0, v130
	v_add_f32_e32 v133, -1.0, v132
	v_sub_f32_e32 v131, v129, v131
	v_sub_f32_e32 v129, v129, v133
	v_add_f32_e32 v131, v128, v131
	v_add_f32_e32 v128, v128, v129
	v_add_f32_e32 v137, v132, v128
	v_rcp_f32_e32 v139, v137
	v_sub_f32_e32 v129, v137, v132
	v_sub_f32_e32 v138, v128, v129
	v_add_f32_e32 v129, v130, v131
	v_mul_f32_e32 v141, v129, v139
	v_sub_f32_e32 v128, v129, v130
	v_mul_f32_e32 v130, v137, v141
	v_fma_f32 v132, v141, v137, -v130
	v_fmac_f32_e32 v132, v141, v138
	v_sub_f32_e32 v140, v131, v128
	v_add_f32_e32 v128, v130, v132
	v_sub_f32_e32 v131, v129, v128
	v_pk_add_f32 v[134:135], v[128:129], v[130:131] neg_lo:[0,1] neg_hi:[0,1]
	v_mov_b32_e32 v133, v128
	v_pk_add_f32 v[128:129], v[134:135], v[132:133] neg_lo:[0,1] neg_hi:[0,1]
	v_cmp_neq_f32_e64 s[16:17], s39, v142
	v_add_f32_e32 v129, v140, v129
	v_add_f32_e32 v128, v128, v129
	v_add_f32_e32 v129, v131, v128
	v_mul_f32_e32 v140, v139, v129
	v_mul_f32_e32 v130, v137, v140
	v_fma_f32 v132, v140, v137, -v130
	v_fmac_f32_e32 v132, v140, v138
	v_sub_f32_e32 v131, v131, v129
	v_add_f32_e32 v137, v128, v131
	v_add_f32_e32 v128, v130, v132
	v_sub_f32_e32 v131, v129, v128
	v_pk_add_f32 v[134:135], v[128:129], v[130:131] neg_lo:[0,1] neg_hi:[0,1]
	v_mov_b32_e32 v133, v128
	v_pk_add_f32 v[128:129], v[134:135], v[132:133] neg_lo:[0,1] neg_hi:[0,1]
	s_nop 0
	v_add_f32_e32 v129, v137, v129
	v_add_f32_e32 v128, v128, v129
	v_add_f32_e32 v129, v141, v140
	v_add_f32_e32 v128, v131, v128
	v_sub_f32_e32 v130, v129, v141
	v_mul_f32_e32 v128, v139, v128
	v_sub_f32_e32 v130, v140, v130
	v_add_f32_e32 v130, v130, v128
	v_add_f32_e32 v132, v129, v130
	v_mul_f32_e32 v133, v132, v132
	v_fmamk_f32 v128, v133, 0x3e9b6dac, v233
	v_fmaak_f32 v193, v133, v128, 0x3f2aaada
	v_cvt_f32_i32_e32 v128, v136
	v_sub_f32_e32 v129, v132, v129
	v_sub_f32_e32 v129, v130, v129
	v_ldexp_f32 v134, v129, 1
	v_mul_f32_e32 v129, v132, v133
	v_ldexp_f32 v131, v132, 1
	v_pk_mul_f32 v[132:133], v[128:129], v[192:193]
	s_nop 0
	v_fma_f32 v130, v128, s38, -v132
	v_fmac_f32_e32 v130, 0xb102e308, v128
	v_pk_add_f32 v[128:129], v[132:133], v[130:131]
	s_nop 0
	v_sub_f32_e32 v131, v129, v131
	v_sub_f32_e32 v131, v133, v131
	v_add_f32_e32 v135, v134, v131
	v_mov_b32_e32 v134, v132
	v_pk_add_f32 v[132:133], v[128:129], v[132:133] neg_lo:[0,1] neg_hi:[0,1]
	v_pk_add_f32 v[136:137], v[128:129], v[134:135]
	v_mov_b32_e32 v131, v128
	v_mov_b32_e32 v133, v137
	v_pk_add_f32 v[138:139], v[130:131], v[132:133] neg_lo:[0,1] neg_hi:[0,1]
	v_pk_add_f32 v[130:131], v[130:131], v[132:133]
	v_mov_b32_e32 v134, v135
	v_pk_add_f32 v[132:133], v[130:131], v[128:129] op_sel:[1,0] op_sel_hi:[0,1] neg_lo:[0,1] neg_hi:[0,1]
	v_pk_add_f32 v[140:141], v[136:137], v[132:133] op_sel_hi:[1,0] neg_lo:[0,1] neg_hi:[0,1]
	v_mov_b32_e32 v136, v137
	v_mov_b32_e32 v137, v131
	v_pk_mov_b32 v[132:133], v[128:129], v[132:133] op_sel:[1,0]
	v_mov_b32_e32 v135, v128
	v_pk_add_f32 v[132:133], v[136:137], v[132:133] neg_lo:[0,1] neg_hi:[0,1]
	v_mov_b32_e32 v140, v138
	v_pk_add_f32 v[128:129], v[134:135], v[132:133] neg_lo:[0,1] neg_hi:[0,1]
	v_mov_b32_e32 v139, v131
	v_pk_add_f32 v[132:133], v[140:141], v[128:129]
	s_nop 0
	v_pk_add_f32 v[134:135], v[132:133], v[132:133] op_sel:[0,1] op_sel_hi:[1,0]
	s_nop 0
	v_pk_add_f32 v[130:131], v[130:131], v[134:135] op_sel:[1,0] op_sel_hi:[0,1]
	v_mov_b32_e32 v133, v130
	v_pk_add_f32 v[136:137], v[132:133], v[138:139] neg_lo:[0,1] neg_hi:[0,1]
	v_mov_b32_e32 v129, v134
	v_sub_f32_e32 v131, v132, v136
	v_pk_add_f32 v[128:129], v[128:129], v[136:137] neg_lo:[0,1] neg_hi:[0,1]
	v_sub_f32_e32 v131, v138, v131
	v_add_f32_e32 v128, v128, v131
	v_add_f32_e32 v128, v128, v129
	v_add_f32_e32 v128, v130, v128
	v_cndmask_b32_e64 v128, v234, v128, s[16:17]
	v_cmp_ngt_f32_e64 s[16:17], -1.0, v142
	s_nop 1
	v_cndmask_b32_e64 v128, v235, v128, s[16:17]
	v_cmp_neq_f32_e64 s[16:17], -1.0, v142
	s_nop 1
	v_cndmask_b32_e64 v128, v236, v128, s[16:17]
	v_cmp_lt_f32_e64 s[16:17], |v142|, s40
	s_nop 1
	v_cndmask_b32_e64 v128, v128, v142, s[16:17]
	v_xor_b32_e32 v128, 0x80000000, v128

; DI f32x4 mfma16(bf16x8 a, bf16x8 b, f32x4 c) { return __builtin_amdgcn_mfma_f32_16x16x32_bf16(a, b, c, 0, 0, 0); }
; DI void mlstm_out_unit(const Params& p, unsigned char* smem, const int tid, int u) {
;     ...
;         const bf16_t* qb = q + (tok0 + 16 * w + (lane & 15)) * 128 + (lane >> 4) * 8;
;         bf16x8 qf[4];
; #pragma unroll
;         for (int ks = 0; ks < 4; ++ks) qf[ks] = ld16(qb + ks * 32);
; #pragma unroll
;         for (int jt = 0; jt < 4; ++jt) {
;             if (jt <= w) {
;                 const bf16_t* kb = k + (tok0 + 16 * jt + (lane & 15)) * 128 + (lane >> 4) * 8;
; #pragma unroll
;                 for (int ks = 0; ks < 4; ++ks) X[jt] = mfma16(ld16(kb + ks * 32), qf[ks], X[jt]);
;             }
;         }
;     ...
;         const bf16_t* qb = q + (tok0 + (lane & 15)) * 128 + (lane >> 4) * 8;
; #pragma unroll
;         for (int ks = 0; ks < 4; ++ks) {
;             bf16x8 bfr[4];
; #pragma unroll
;             for (int i = 0; i < 4; ++i) bfr[i] = ld16(qb + (size_t)i * 16 * 128 + ks * 32);
.LBB0_723:
	s_or_b64 exec, exec, s[86:87]
	v_or_b32_e32 v72, v76, v116
	s_waitcnt lgkmcnt(0)
	v_lshlrev_b64 v[64:65], 8, v[72:73]
	v_or_b32_e32 v72, v76, v104
	v_lshlrev_b64 v[130:131], 8, v[72:73]
	v_lshl_add_u64 v[64:65], v[112:113], 0, v[64:65]
	v_lshl_add_u64 v[132:133], v[114:115], 0, v[130:131]
	global_load_dwordx4 v[92:95], v[64:65], off
	global_load_dwordx4 v[88:91], v[64:65], off offset:64
	global_load_dwordx4 v[84:87], v[64:65], off offset:128
	global_load_dwordx4 v[80:83], v[64:65], off offset:192
	s_mov_b64 s[100:101], 0x1000
	global_load_dwordx4 v[188:191], v[132:133], off
	global_load_dwordx4 v[192:195], v[132:133], off offset:64
	global_load_dwordx4 v[196:199], v[132:133], off offset:128
	global_load_dwordx4 v[200:203], v[132:133], off offset:192
	v_lshl_add_u64 v[182:183], v[132:133], 0, s[100:101]
	v_lshl_add_u64 v[248:249], v[182:183], 0, s[100:101]
	v_lshl_add_u64 v[144:145], v[248:249], 0, s[100:101]
	s_and_saveexec_b64 s[86:87], s[56:57]
	s_cbranch_execz .Lp7_kld_1
	global_load_dwordx4 v[204:207], v[182:183], off
	global_load_dwordx4 v[208:211], v[182:183], off offset:64
	global_load_dwordx4 v[212:215], v[182:183], off offset:128
	global_load_dwordx4 v[216:219], v[182:183], off offset:192
.Lp7_kld_1:
	s_or_b64 exec, exec, s[86:87]
	s_and_saveexec_b64 s[86:87], s[18:19]
	s_cbranch_execz .Lp7_kld_2
	global_load_dwordx4 v[220:223], v[248:249], off
	global_load_dwordx4 v[224:227], v[248:249], off offset:64
	global_load_dwordx4 v[228:231], v[248:249], off offset:128
	global_load_dwordx4 v[232:235], v[248:249], off offset:192
.Lp7_kld_2:
	s_or_b64 exec, exec, s[86:87]
	s_and_saveexec_b64 s[86:87], s[20:21]
	s_cbranch_execz .Lp7_kld_3
	global_load_dwordx4 v[236:239], v[144:145], off
	global_load_dwordx4 v[240:243], v[144:145], off offset:64
	global_load_dwordx4 v[244:247], v[144:145], off offset:128
	global_load_dwordx4 v[140:143], v[144:145], off offset:192
.Lp7_kld_3:
	s_or_b64 exec, exec, s[86:87]
	v_mov_b32_e32 v64, 0
	v_mov_b32_e32 v65, 0
	v_mov_b32_e32 v66, 0
	v_mov_b32_e32 v67, 0
	v_mov_b32_e32 v68, 0
	v_mov_b32_e32 v69, 0
	v_mov_b32_e32 v70, 0
	v_mov_b32_e32 v71, 0
	v_mov_b32_e32 v72, 0
	v_mov_b32_e32 v73, 0
	v_mov_b32_e32 v74, 0
	v_mov_b32_e32 v75, 0
	s_barrier
	s_waitcnt vmcnt(0)
	v_mfma_f32_16x16x32_bf16 v[76:79], v[188:191], v[92:95], 0
	v_mfma_f32_16x16x32_bf16 v[76:79], v[192:195], v[88:91], v[76:79]
	v_mfma_f32_16x16x32_bf16 v[76:79], v[196:199], v[84:87], v[76:79]
	v_mfma_f32_16x16x32_bf16 v[76:79], v[200:203], v[80:83], v[76:79]
	s_and_saveexec_b64 s[86:87], s[56:57]
	s_cbranch_execz .Lp7_kmm_1
	v_mfma_f32_16x16x32_bf16 v[72:75], v[204:207], v[92:95], 0
	v_mfma_f32_16x16x32_bf16 v[72:75], v[208:211], v[88:91], v[72:75]
	v_mfma_f32_16x16x32_bf16 v[72:75], v[212:215], v[84:87], v[72:75]
	v_mfma_f32_16x16x32_bf16 v[72:75], v[216:219], v[80:83], v[72:75]
.Lp7_kmm_1:
	s_or_b64 exec, exec, s[86:87]
	s_and_saveexec_b64 s[86:87], s[18:19]
	s_cbranch_execz .Lp7_kmm_2
	v_mfma_f32_16x16x32_bf16 v[68:71], v[220:223], v[92:95], 0
	v_mfma_f32_16x16x32_bf16 v[68:71], v[224:227], v[88:91], v[68:71]
	v_mfma_f32_16x16x32_bf16 v[68:71], v[228:231], v[84:87], v[68:71]
	v_mfma_f32_16x16x32_bf16 v[68:71], v[232:235], v[80:83], v[68:71]
.Lp7_kmm_2:
	s_or_b64 exec, exec, s[86:87]
	s_and_saveexec_b64 s[86:87], s[20:21]
	s_cbranch_execz .Lp7_kmm_3
	v_mfma_f32_16x16x32_bf16 v[64:67], v[236:239], v[92:95], 0
	v_mfma_f32_16x16x32_bf16 v[64:67], v[240:243], v[88:91], v[64:67]
	v_mfma_f32_16x16x32_bf16 v[64:67], v[244:247], v[84:87], v[64:67]
	v_mfma_f32_16x16x32_bf16 v[64:67], v[140:143], v[80:83], v[64:67]
.Lp7_kmm_3:
	s_or_b64 exec, exec, s[86:87]
	s_mov_b64 s[86:87], exec
	v_lshl_add_u64 v[182:183], v[112:113], 0, v[130:131]
	v_lshl_add_u64 v[248:249], v[182:183], 0, s[100:101]
	v_lshl_add_u64 v[144:145], v[248:249], 0, s[100:101]
	v_lshl_add_u64 v[146:147], v[144:145], 0, s[100:101]
	global_load_dwordx4 v[188:191], v[182:183], off
	global_load_dwordx4 v[192:195], v[248:249], off
	global_load_dwordx4 v[196:199], v[144:145], off
	global_load_dwordx4 v[200:203], v[146:147], off
	global_load_dwordx4 v[204:207], v[182:183], off offset:64
	global_load_dwordx4 v[208:211], v[248:249], off offset:64
	global_load_dwordx4 v[212:215], v[144:145], off offset:64
	global_load_dwordx4 v[216:219], v[146:147], off offset:64
	global_load_dwordx4 v[220:223], v[182:183], off offset:128
	global_load_dwordx4 v[224:227], v[248:249], off offset:128
	global_load_dwordx4 v[228:231], v[144:145], off offset:128
	global_load_dwordx4 v[232:235], v[146:147], off offset:128
	global_load_dwordx4 v[236:239], v[182:183], off offset:192
	global_load_dwordx4 v[240:243], v[248:249], off offset:192
	global_load_dwordx4 v[244:247], v[144:145], off offset:192
	global_load_dwordx2 v[248:249], v[146:147], off offset:192
	global_load_dwordx2 v[182:183], v[146:147], off offset:200
	s_nop 7

; DI uint2 pk4(f32x4 v) { return make_uint2(pk2(v[0], v[1]), pk2(v[2], v[3])); }
; DI f32x4 mfma16(bf16x8 a, bf16x8 b, f32x4 c) { return __builtin_amdgcn_mfma_f32_16x16x32_bf16(a, b, c, 0, 0, 0); }
; DI void mlstm_out_unit(const Params& p, unsigned char* smem, const int tid, int u) {
;     ...
;         for (int pr = 0; pr < 2; ++pr) {
;             uint2 lo = pk4(X[2 * pr]), hi = pk4(X[2 * pr + 1]);
;             xs[(w * 2 + pr) * 64 + lane] = make_uint4(lo.x, lo.y, hi.x, hi.y);
;         }
;     }
;     __syncthreads();
;     f32x4 acc[4][4];
; #pragma unroll
;     for (int i = 0; i < 4; ++i)
; #pragma unroll
;         for (int j = 0; j < 4; ++j) acc[i][j] = f32x4{0.f, 0.f, 0.f, 0.f};
;     {
;         const bf16_t* qb = q + (tok0 + (lane & 15)) * 128 + (lane >> 4) * 8;
; #pragma unroll
;         for (int ks = 0; ks < 4; ++ks) {
;             bf16x8 bfr[4];
; #pragma unroll
;             for (int i = 0; i < 4; ++i) bfr[i] = ld16(qb + (size_t)i * 16 * 128 + ks * 32);
; #pragma unroll
;             for (int i = 0; i < 4; ++i)
; #pragma unroll
;                 for (int j = 0; j < 4; ++j) acc[i][j] = mfma16(ctf[ks][i], bfr[j], acc[i][j]);
;         }
.LBB0_763:
	s_or_b64 exec, exec, s[86:87]
	v_lshl_add_u64 v[180:181], v[112:113], 0, v[130:131]
	v_add_co_u32_e32 v84, vcc, s3, v180
	s_movk_i32 s86, 0x3000
	s_nop 0
	v_addc_co_u32_e32 v85, vcc, 0, v181, vcc
	v_add_co_u32_e32 v86, vcc, s91, v180
	v_cvt_pk_bf16_f32 v80, v81, v80
	s_nop 0
	v_addc_co_u32_e32 v87, vcc, 0, v181, vcc
	v_add_co_u32_e32 v88, vcc, s86, v180
	v_cvt_pk_bf16_f32 v81, v77, v76
	v_cvt_pk_bf16_f32 v82, v79, v78
	v_cvt_pk_bf16_f32 v83, v73, v72
	v_cvt_pk_bf16_f32 v66, v75, v74
	s_waitcnt lgkmcnt(0)
	v_cvt_pk_bf16_f32 v67, v69, v68
	v_cvt_pk_bf16_f32 v68, v71, v70
	v_cvt_pk_bf16_f32 v69, v65, v64
	v_addc_co_u32_e32 v89, vcc, 0, v181, vcc
	ds_write_b128 v121, v[80:83] offset:4096
	ds_write_b128 v121, v[66:69] offset:5120
	s_waitcnt lgkmcnt(0)
	s_barrier
	s_waitcnt vmcnt(0)
	v_mov_b64_e32 v[64:65], v[188:189]
	v_mov_b64_e32 v[66:67], v[190:191]
	v_mov_b64_e32 v[68:69], v[192:193]
	v_mov_b64_e32 v[70:71], v[194:195]
	v_mov_b64_e32 v[72:73], v[196:197]
	v_mov_b64_e32 v[74:75], v[198:199]
	v_mov_b64_e32 v[76:77], v[200:201]
	v_mov_b64_e32 v[78:79], v[202:203]
	s_waitcnt vmcnt(3)
	v_mfma_f32_16x16x32_bf16 v[80:83], v[52:55], v[64:67], 0
	s_waitcnt vmcnt(2)
	v_mfma_f32_16x16x32_bf16 v[92:95], v[52:55], v[68:71], 0
	s_waitcnt vmcnt(1)
	v_mfma_f32_16x16x32_bf16 v[130:133], v[52:55], v[72:75], 0
	s_waitcnt vmcnt(0)
	v_mfma_f32_16x16x32_bf16 v[52:55], v[52:55], v[76:79], 0
	v_mfma_f32_16x16x32_bf16 v[140:143], v[60:63], v[64:67], 0
	v_mfma_f32_16x16x32_bf16 v[144:147], v[60:63], v[68:71], 0
	v_mfma_f32_16x16x32_bf16 v[148:151], v[60:63], v[72:75], 0
	v_mfma_f32_16x16x32_bf16 v[60:63], v[60:63], v[76:79], 0
	v_mfma_f32_16x16x32_bf16 v[152:155], v[56:59], v[64:67], 0
	v_mfma_f32_16x16x32_bf16 v[156:159], v[56:59], v[68:71], 0
	v_mfma_f32_16x16x32_bf16 v[160:163], v[56:59], v[72:75], 0
	v_mfma_f32_16x16x32_bf16 v[56:59], v[56:59], v[76:79], 0
	v_mfma_f32_16x16x32_bf16 v[64:67], v[48:51], v[64:67], 0
	v_mfma_f32_16x16x32_bf16 v[68:71], v[48:51], v[68:71], 0
	v_mfma_f32_16x16x32_bf16 v[72:75], v[48:51], v[72:75], 0
	v_mfma_f32_16x16x32_bf16 v[48:51], v[48:51], v[76:79], 0
	v_mov_b64_e32 v[76:77], v[204:205]
	v_mov_b64_e32 v[78:79], v[206:207]
	v_mov_b64_e32 v[164:165], v[208:209]
	v_mov_b64_e32 v[166:167], v[210:211]
	v_mov_b64_e32 v[168:169], v[212:213]
	v_mov_b64_e32 v[170:171], v[214:215]
	v_mov_b64_e32 v[172:173], v[216:217]
	v_mov_b64_e32 v[174:175], v[218:219]
	s_waitcnt vmcnt(3)
	v_mfma_f32_16x16x32_bf16 v[80:83], v[44:47], v[76:79], v[80:83]
	s_waitcnt vmcnt(2)
	v_mfma_f32_16x16x32_bf16 v[92:95], v[44:47], v[164:167], v[92:95]
	s_waitcnt vmcnt(1)
	v_mfma_f32_16x16x32_bf16 v[130:133], v[44:47], v[168:171], v[130:133]
	s_waitcnt vmcnt(0)
	v_mfma_f32_16x16x32_bf16 v[44:47], v[44:47], v[172:175], v[52:55]
	v_mfma_f32_16x16x32_bf16 v[52:55], v[40:43], v[76:79], v[140:143]
	v_mfma_f32_16x16x32_bf16 v[140:143], v[40:43], v[164:167], v[144:147]
	v_mfma_f32_16x16x32_bf16 v[144:147], v[40:43], v[168:171], v[148:151]
	v_mfma_f32_16x16x32_bf16 v[60:63], v[40:43], v[172:175], v[60:63]
	v_mfma_f32_16x16x32_bf16 v[148:151], v[36:39], v[76:79], v[152:155]
	v_mfma_f32_16x16x32_bf16 v[152:155], v[36:39], v[164:167], v[156:159]
	v_mfma_f32_16x16x32_bf16 v[156:159], v[36:39], v[168:171], v[160:163]
	v_mfma_f32_16x16x32_bf16 v[56:59], v[36:39], v[172:175], v[56:59]
	v_mfma_f32_16x16x32_bf16 v[160:163], v[32:35], v[164:167], v[68:71]
	v_mfma_f32_16x16x32_bf16 v[72:75], v[32:35], v[168:171], v[72:75]
	v_mfma_f32_16x16x32_bf16 v[164:167], v[32:35], v[172:175], v[48:51]
	v_mov_b64_e32 v[168:169], v[220:221]
	v_mov_b64_e32 v[170:171], v[222:223]
	v_mov_b64_e32 v[172:173], v[224:225]
	v_mov_b64_e32 v[174:175], v[226:227]
	v_mov_b64_e32 v[176:177], v[228:229]
	v_mov_b64_e32 v[178:179], v[230:231]
	v_mov_b64_e32 v[184:185], v[232:233]
	v_mov_b64_e32 v[186:187], v[234:235]
	v_mfma_f32_16x16x32_bf16 v[64:67], v[32:35], v[76:79], v[64:67]
	s_waitcnt vmcnt(3)
	v_mfma_f32_16x16x32_bf16 v[80:83], v[24:27], v[168:171], v[80:83]
	s_waitcnt vmcnt(2)
	v_mfma_f32_16x16x32_bf16 v[76:79], v[24:27], v[172:175], v[92:95]
	s_waitcnt vmcnt(1)
	v_mfma_f32_16x16x32_bf16 v[68:71], v[24:27], v[176:179], v[130:133]
	s_waitcnt vmcnt(0)
	v_mfma_f32_16x16x32_bf16 v[24:27], v[24:27], v[184:187], v[44:47]
	v_mfma_f32_16x16x32_bf16 v[32:35], v[28:31], v[168:171], v[52:55]
	v_mfma_f32_16x16x32_bf16 v[44:47], v[20:23], v[168:171], v[148:151]
	v_mfma_f32_16x16x32_bf16 v[48:51], v[20:23], v[172:175], v[152:155]
	v_mfma_f32_16x16x32_bf16 v[52:55], v[20:23], v[176:179], v[156:159]
	v_mfma_f32_16x16x32_bf16 v[20:23], v[20:23], v[184:187], v[56:59]
	v_mfma_f32_16x16x32_bf16 v[56:59], v[16:19], v[168:171], v[64:67]
	v_mfma_f32_16x16x32_bf16 v[64:67], v[16:19], v[176:179], v[72:75]
	s_nop 2
	v_mov_b64_e32 v[72:73], v[236:237]
	v_mov_b64_e32 v[74:75], v[238:239]
	v_mov_b64_e32 v[92:93], v[240:241]
	v_mov_b64_e32 v[94:95], v[242:243]
	s_nop 0
	v_mov_b64_e32 v[84:85], v[244:245]
	v_mov_b64_e32 v[86:87], v[246:247]
	s_nop 0
	v_mov_b64_e32 v[130:131], v[248:249]
	v_mov_b64_e32 v[132:133], v[182:183]
	v_mfma_f32_16x16x32_bf16 v[36:39], v[28:31], v[172:175], v[140:143]
	v_mfma_f32_16x16x32_bf16 v[40:43], v[28:31], v[176:179], v[144:147]
	v_mfma_f32_16x16x32_bf16 v[28:31], v[28:31], v[184:187], v[60:63]
	v_mfma_f32_16x16x32_bf16 v[60:63], v[16:19], v[172:175], v[160:163]
	s_waitcnt vmcnt(3)
	v_mfma_f32_16x16x32_bf16 v[80:83], v[12:15], v[72:75], v[80:83]
	s_waitcnt vmcnt(2)
	v_mfma_f32_16x16x32_bf16 v[76:79], v[12:15], v[92:95], v[76:79]
	s_waitcnt vmcnt(1)
	v_mfma_f32_16x16x32_bf16 v[68:71], v[12:15], v[84:87], v[68:71]
	s_waitcnt vmcnt(0)
; DI f32x4 mfma16(bf16x8 a, bf16x8 b, f32x4 c) { return __builtin_amdgcn_mfma_f32_16x16x32_bf16(a, b, c, 0, 0, 0); }
; DI void mlstm_out_unit(const Params& p, unsigned char* smem, const int tid, int u) {
;     ...
; #pragma unroll
;     for (int ni = 0; ni < 4; ++ni) {
;         const float s = sci[16 * ni + (lane & 15)];
; #pragma unroll
;         for (int mi = 0; mi < 4; ++mi) { acc[mi][ni][0] *= s; acc[mi][ni][1] *= s; acc[mi][ni][2] *= s; acc[mi][ni][3] *= s; }
;     }
;     {
;         const bf16_t* vb = vT + (((size_t)bh * 128 + c) * 256 + 64 * w + ((lane & 15) >> 2) * 8 + (lane & 3)) * 64 + (lane >> 4) * 4;
; #pragma unroll
;         for (int pr = 0; pr < 2; ++pr) {
;             bf16x8 af[4];
; #pragma unroll
;             for (int mi = 0; mi < 4; ++mi) {
;                 uint2 lo = *(const uint2*)(vb + (size_t)((mi >> 1) * 32 + (mi & 1) * 4) * 64 + pr * 32);
;                 uint2 hi = *(const uint2*)(vb + (size_t)((mi >> 1) * 32 + (mi & 1) * 4) * 64 + pr * 32 + 16);
;                 af[mi] = __builtin_bit_cast(bf16x8, make_uint4(lo.x, lo.y, hi.x, hi.y));
;             }
; #pragma unroll
;             for (int ni = 0; ni < 4; ++ni) {
;                 if (ni >= 2 * pr) {
;                     bf16x8 xb = __builtin_bit_cast(bf16x8, xs[(ni * 2 + pr) * 64 + lane]);
; #pragma unroll
;                     for (int mi = 0; mi < 4; ++mi) acc[mi][ni] = mfma16(af[mi], xb, acc[mi][ni]);
;                 }
;             }
;         }
;     }
; #pragma unroll
;     for (int ni = 0; ni < 4; ++ni) {
;         const float rd = rden[16 * ni + (lane & 15)];
;         float s = 0.f;
; #pragma unroll
;         for (int mi = 0; mi < 4; ++mi) { acc[mi][ni][0] *= rd; acc[mi][ni][1] *= rd; acc[mi][ni][2] *= rd; acc[mi][ni][3] *= rd;
;             s += acc[mi][ni][0] + acc[mi][ni][1] + acc[mi][ni][2] + acc[mi][ni][3]; }
;         s += __shfl_xor(s, 16, 64); s += __shfl_xor(s, 32, 64);
;         if (lane < 16) part[w * 64 + 16 * ni + lane] = s;
	v_mfma_f32_16x16x32_bf16 v[140:143], v[12:15], v[130:133], v[24:27]
	v_mfma_f32_16x16x32_bf16 v[12:15], v[8:11], v[72:75], v[32:35]
	v_mfma_f32_16x16x32_bf16 v[32:35], v[8:11], v[92:95], v[36:39]
	v_mfma_f32_16x16x32_bf16 v[36:39], v[8:11], v[84:87], v[40:43]
	v_mfma_f32_16x16x32_bf16 v[40:43], v[8:11], v[130:133], v[28:31]
	s_nop 2
	ds_read2_b32 v[28:29], v123 offset0:128 offset1:144
	v_mfma_f32_16x16x32_bf16 v[16:19], v[16:19], v[184:187], v[164:167]
	s_waitcnt lgkmcnt(0)
	v_mov_b32_e32 v30, v29
	v_mfma_f32_16x16x32_bf16 v[8:11], v[4:7], v[72:75], v[44:47]
	v_mul_f32_e64 v14, v14, v28
	v_mul_f32_e64 v15, v15, v28
	v_pk_mul_f32 v[12:13], v[12:13], v[28:29] op_sel_hi:[1,0]
	v_mfma_f32_16x16x32_bf16 v[44:47], v[4:7], v[92:95], v[48:51]
	v_mfma_f32_16x16x32_bf16 v[144:147], v[4:7], v[130:133], v[20:23]
	s_nop 2
	v_mul_f32_e64 v10, v10, v28
	v_mul_f32_e64 v11, v11, v28
	v_pk_mul_f32 v[8:9], v[8:9], v[28:29] op_sel_hi:[1,0]
	v_mfma_f32_16x16x32_bf16 v[20:23], v[0:3], v[92:95], v[60:63]
	v_mfma_f32_16x16x32_bf16 v[48:51], v[4:7], v[84:87], v[52:55]
	v_mul_f32_e64 v6, v34, v30
	v_mul_f32_e64 v7, v35, v30
	v_pk_mul_f32 v[4:5], v[32:33], v[30:31] op_sel_hi:[1,0]
	s_nop 3
	v_pk_mul_f32 v[22:23], v[22:23], v[30:31] op_sel_hi:[1,0]
	v_mfma_f32_16x16x32_bf16 v[24:27], v[0:3], v[72:75], v[56:59]
	v_mul_f32_e64 v20, v20, v30
	v_mul_f32_e64 v21, v21, v30
	v_mfma_f32_16x16x32_bf16 v[52:55], v[0:3], v[84:87], v[64:67]
	v_mfma_f32_16x16x32_bf16 v[72:75], v[0:3], v[130:133], v[16:19]
	v_mul_f32_e64 v2, v78, v30
	v_mul_f32_e64 v3, v79, v30
	v_pk_mul_f32 v[0:1], v[76:77], v[30:31] op_sel_hi:[1,0]
	s_nop 0
	v_pk_mul_f32 v[26:27], v[26:27], v[28:29] op_sel_hi:[1,0]
	v_pk_mul_f32 v[18:19], v[46:47], v[30:31] op_sel_hi:[1,0]
	v_pk_mul_f32 v[16:17], v[44:45], v[30:31] op_sel_hi:[1,0]
	ds_read2_b32 v[30:31], v123 offset0:160 offset1:176
	v_pk_mul_f32 v[24:25], v[24:25], v[28:29] op_sel_hi:[1,0]
	s_waitcnt lgkmcnt(0)
	v_pk_mul_f32 v[34:35], v[70:71], v[30:31] op_sel_hi:[1,0]
	v_pk_mul_f32 v[32:33], v[68:69], v[30:31] op_sel_hi:[1,0]
	v_pk_mul_f32 v[38:39], v[38:39], v[30:31] op_sel_hi:[1,0]
	v_pk_mul_f32 v[36:37], v[36:37], v[30:31] op_sel_hi:[1,0]
	v_pk_mul_f32 v[50:51], v[50:51], v[30:31] op_sel_hi:[1,0]
	v_pk_mul_f32 v[48:49], v[48:49], v[30:31] op_sel_hi:[1,0]
	v_pk_mul_f32 v[54:55], v[54:55], v[30:31] op_sel_hi:[1,0]
	v_pk_mul_f32 v[52:53], v[52:53], v[30:31] op_sel_hi:[1,0]
	v_mov_b32_e32 v30, v31
	v_pk_mul_f32 v[58:59], v[142:143], v[30:31] op_sel_hi:[1,0]
	v_pk_mul_f32 v[56:57], v[140:141], v[30:31] op_sel_hi:[1,0]
	v_pk_mul_f32 v[62:63], v[42:43], v[30:31] op_sel_hi:[1,0]
	v_pk_mul_f32 v[60:61], v[40:41], v[30:31] op_sel_hi:[1,0]
	v_pk_mul_f32 v[66:67], v[146:147], v[30:31] op_sel_hi:[1,0]
	v_pk_mul_f32 v[64:65], v[144:145], v[30:31] op_sel_hi:[1,0]
	v_pk_mul_f32 v[70:71], v[74:75], v[30:31] op_sel_hi:[1,0]
	v_pk_mul_f32 v[68:69], v[72:73], v[30:31] op_sel_hi:[1,0]
	v_lshlrev_b64 v[30:31], 7, v[128:129]
	v_lshl_add_u64 v[88:89], v[124:125], 0, v[30:31]
	v_add_co_u32_e32 v130, vcc, s3, v88
	global_load_dwordx2 v[72:73], v[88:89], off
	global_load_dwordx2 v[74:75], v[88:89], off offset:32
	global_load_dwordx2 v[76:77], v[88:89], off offset:512
	global_load_dwordx2 v[78:79], v[88:89], off offset:544
	v_addc_co_u32_e32 v131, vcc, 0, v89, vcc
	global_load_dwordx2 v[84:85], v[130:131], off
	global_load_dwordx2 v[86:87], v[130:131], off offset:32
	global_load_dwordx2 v[92:93], v[130:131], off offset:512
	global_load_dwordx2 v[94:95], v[130:131], off offset:544
	v_pk_mul_f32 v[30:31], v[82:83], v[28:29] op_sel_hi:[1,0]
	v_pk_mul_f32 v[28:29], v[80:81], v[28:29] op_sel_hi:[1,0]
	ds_read_b128 v[80:83], v119 offset:4096
	s_waitcnt vmcnt(4) lgkmcnt(0)
	v_mfma_f32_16x16x32_bf16 v[40:43], v[76:79], v[80:83], v[12:15]
	v_mfma_f32_16x16x32_bf16 v[44:47], v[72:75], v[80:83], v[28:31]
	s_waitcnt vmcnt(2)
	v_mfma_f32_16x16x32_bf16 v[28:31], v[84:87], v[80:83], v[8:11]
	s_waitcnt vmcnt(0)
	v_mfma_f32_16x16x32_bf16 v[24:27], v[92:95], v[80:83], v[24:27]
	ds_read_b128 v[80:83], v119 offset:6144
	s_waitcnt lgkmcnt(0)
	v_mfma_f32_16x16x32_bf16 v[8:11], v[76:79], v[80:83], v[4:7]
	v_mfma_f32_16x16x32_bf16 v[4:7], v[84:87], v[80:83], v[16:19]
	s_nop 2
	ds_read_b128 v[16:19], v119 offset:8192
	v_mfma_f32_16x16x32_bf16 v[12:15], v[72:75], v[80:83], v[0:3]
	v_mfma_f32_16x16x32_bf16 v[0:3], v[92:95], v[80:83], v[20:23]
	s_waitcnt lgkmcnt(0)
	v_mfma_f32_16x16x32_bf16 v[20:23], v[72:75], v[16:19], v[32:35]
	v_mfma_f32_16x16x32_bf16 v[32:35], v[76:79], v[16:19], v[36:39]
	v_mfma_f32_16x16x32_bf16 v[36:39], v[84:87], v[16:19], v[48:51]
	s_nop 2
	ds_read_b128 v[48:51], v119 offset:10240
	v_mfma_f32_16x16x32_bf16 v[16:19], v[92:95], v[16:19], v[52:55]
	s_waitcnt lgkmcnt(0)
	v_mfma_f32_16x16x32_bf16 v[64:67], v[84:87], v[48:51], v[64:67]
	v_mfma_f32_16x16x32_bf16 v[68:71], v[92:95], v[48:51], v[68:71]
	global_load_dwordx2 v[80:81], v[88:89], off offset:64
	global_load_dwordx2 v[82:83], v[88:89], off offset:96
	global_load_dwordx2 v[84:85], v[88:89], off offset:576
	global_load_dwordx2 v[86:87], v[88:89], off offset:608
	global_load_dwordx2 v[92:93], v[130:131], off offset:64
	global_load_dwordx2 v[94:95], v[130:131], off offset:96
	global_load_dwordx2 v[128:129], v[130:131], off offset:576
	s_nop 0
	global_load_dwordx2 v[130:131], v[130:131], off offset:608
	v_mfma_f32_16x16x32_bf16 v[72:75], v[72:75], v[48:51], v[56:59]
	v_mfma_f32_16x16x32_bf16 v[76:79], v[76:79], v[48:51], v[60:63]
	ds_read_b128 v[48:51], v119 offset:9216
	s_waitcnt vmcnt(6) lgkmcnt(0)
	v_mfma_f32_16x16x32_bf16 v[60:63], v[80:83], v[48:51], v[20:23]
	s_waitcnt vmcnt(4)
	v_mfma_f32_16x16x32_bf16 v[56:59], v[84:87], v[48:51], v[32:35]
	s_waitcnt vmcnt(2)
	v_mfma_f32_16x16x32_bf16 v[52:55], v[92:95], v[48:51], v[36:39]
	s_waitcnt vmcnt(0)
	v_mfma_f32_16x16x32_bf16 v[48:51], v[128:131], v[48:51], v[16:19]
	s_nop 2
	ds_read_b128 v[16:19], v134 offset:4096
	s_waitcnt lgkmcnt(0)
	v_mfma_f32_16x16x32_bf16 v[36:39], v[80:83], v[16:19], v[72:75]
	s_nop 2
	ds_read_b32 v72, v123 offset:1280
	v_mfma_f32_16x16x32_bf16 v[32:35], v[84:87], v[16:19], v[76:79]
	v_mfma_f32_16x16x32_bf16 v[20:23], v[92:95], v[16:19], v[64:67]
	v_mfma_f32_16x16x32_bf16 v[16:19], v[128:131], v[16:19], v[68:71]
	s_waitcnt lgkmcnt(0)
	s_nop 1
	v_mul_f32_e32 v70, v45, v72
	v_fma_f32 v45, v44, v72, v70
	v_mul_f32_e32 v71, v41, v72
	v_fmac_f32_e32 v45, v46, v72
	v_fma_f32 v41, v40, v72, v71
	v_mul_f32_e32 v69, v29, v72
	v_fmac_f32_e32 v45, v47, v72
	v_fmac_f32_e32 v41, v42, v72
	v_fma_f32 v29, v28, v72, v69
	v_mul_f32_e32 v68, v25, v72
	v_add_f32_e32 v45, 0, v45
	v_fmac_f32_e32 v41, v43, v72
	v_fmac_f32_e32 v29, v30, v72
	v_fma_f32 v25, v24, v72, v68
	v_add_f32_e32 v41, v41, v45
	v_fmac_f32_e32 v29, v31, v72
	v_fmac_f32_e32 v25, v26, v72
	v_add_f32_e32 v29, v29, v41
	v_fmac_f32_e32 v25, v27, v72
	v_add_f32_e32 v25, v25, v29
	ds_bpermute_b32 v29, v90, v25
	s_waitcnt lgkmcnt(0)
	v_add_f32_e32 v25, v25, v29
	ds_bpermute_b32 v29, v91, v25
	s_and_saveexec_b64 s[86:87], s[12:13]
	s_cbranch_execz .LBB0_765
; DI void mlstm_out_unit(const Params& p, unsigned char* smem, const int tid, int u) {
;     ...
;         s += __shfl_xor(s, 16, 64); s += __shfl_xor(s, 32, 64);
;         if (lane < 16) part[w * 64 + 16 * ni + lane] = s;
	s_waitcnt lgkmcnt(0)
	v_add_f32_e32 v25, v25, v29
	ds_write_b32 v135, v25 offset:1536

; __global__ void __launch_bounds__(512, 2) fwd_megakernel(Params p) {
	.amdhsa_kernel _Z14fwd_megakernel6Params
		.amdhsa_group_segment_fixed_size 16
		.amdhsa_private_segment_fixed_size 0
		.amdhsa_kernarg_size 512
		.amdhsa_user_sgpr_count 2
		.amdhsa_user_sgpr_dispatch_ptr 0
		.amdhsa_user_sgpr_queue_ptr 0
		.amdhsa_user_sgpr_kernarg_segment_ptr 1
		.amdhsa_user_sgpr_dispatch_id 0
		.amdhsa_user_sgpr_kernarg_preload_length 0
		.amdhsa_user_sgpr_kernarg_preload_offset 0
		.amdhsa_user_sgpr_private_segment_size 0
		.amdhsa_uses_dynamic_stack 0
		.amdhsa_enable_private_segment 0
		.amdhsa_system_sgpr_workgroup_id_x 1
		.amdhsa_system_sgpr_workgroup_id_y 0
		.amdhsa_system_sgpr_workgroup_id_z 0
		.amdhsa_system_sgpr_workgroup_info 0
		.amdhsa_system_vgpr_workitem_id 2
		.amdhsa_next_free_vgpr 256
		.amdhsa_next_free_sgpr 102
		.amdhsa_accum_offset 256
		.amdhsa_reserve_vcc 1
		.amdhsa_float_round_mode_32 0
		.amdhsa_float_round_mode_16_64 0
		.amdhsa_float_denorm_mode_32 3
		.amdhsa_float_denorm_mode_16_64 3
		.amdhsa_dx10_clamp 1
		.amdhsa_ieee_mode 1
		.amdhsa_fp16_overflow 0
		.amdhsa_tg_split 0
		.amdhsa_exception_fp_ieee_invalid_op 0
		.amdhsa_exception_fp_denorm_src 0
		.amdhsa_exception_fp_ieee_div_zero 0
		.amdhsa_exception_fp_ieee_overflow 0
		.amdhsa_exception_fp_ieee_underflow 0
		.amdhsa_exception_fp_ieee_inexact 0
		.amdhsa_exception_int_div_zero 0
	.end_amdhsa_kernel

; __global__ void __launch_bounds__(512, 2) fwd_megakernel(Params p) {
amdhsa.kernels:
  - .agpr_count:     0
    .args:
      - .offset:         0
        .size:           256
        .value_kind:     by_value
      - .offset:         256
        .size:           4
        .value_kind:     hidden_block_count_x
      - .offset:         260
        .size:           4
        .value_kind:     hidden_block_count_y
      - .offset:         264
        .size:           4
        .value_kind:     hidden_block_count_z
      - .offset:         268
        .size:           2
        .value_kind:     hidden_group_size_x
      - .offset:         270
        .size:           2
        .value_kind:     hidden_group_size_y
      - .offset:         272
        .size:           2
        .value_kind:     hidden_group_size_z
      - .offset:         274
        .size:           2
        .value_kind:     hidden_remainder_x
      - .offset:         276
        .size:           2
        .value_kind:     hidden_remainder_y
      - .offset:         278
        .size:           2
        .value_kind:     hidden_remainder_z
      - .offset:         296
        .size:           8
        .value_kind:     hidden_global_offset_x
      - .offset:         304
        .size:           8
        .value_kind:     hidden_global_offset_y
      - .offset:         312
        .size:           8
        .value_kind:     hidden_global_offset_z
      - .offset:         320
        .size:           2
        .value_kind:     hidden_grid_dims
      - .offset:         344
        .size:           8
        .value_kind:     hidden_multigrid_sync_arg
      - .offset:         376
        .size:           4
        .value_kind:     hidden_dynamic_lds_size
    .group_segment_fixed_size: 16
    .kernarg_segment_align: 8
    .kernarg_segment_size: 512
    .language:       OpenCL C
    .language_version:
      - 2
      - 0
    .max_flat_workgroup_size: 512
    .name:           _Z14fwd_megakernel6Params
    .private_segment_fixed_size: 0
    .sgpr_count:     108
    .sgpr_spill_count: 70
    .symbol:         _Z14fwd_megakernel6Params.kd
    .uniform_work_group_size: 1
    .uses_dynamic_stack: false
    .vgpr_count:     256
    .vgpr_spill_count: 0
    .wavefront_size: 64
